# POST epilogue arithmetic on packed f32 ops (two adjacent channels per instruction)
# baseline (speedup 1.0000x reference)
; __device__ __forceinline__ float bf2f(u16 h) { return __uint_as_float(((unsigned)h) << 16); }
; template <int EPI> ...
;     ...
;       const int hh = nt * 2 + wn;
;       const u16* P = (const u16*)(p.ws + O_P);
;       u16* Y = (u16*)(p.ws + O_Y);
;       const float* bs = (const float*)(p.ws + O_BS);
;       const int ch0 = hh * 64 + (lane & 31), ch1 = ch0 + 32;
;       const float gg0 = p.in[20][ch0], gg1 = p.in[20][ch1];
;       const float gb0 = p.in[21][ch0], gb1 = p.in[21][ch1];
;       const float mu0 = p.in[11][1536 + ch0], mu1 = p.in[11][1536 + ch1];
; #pragma unroll 16
;       for (int i = 0; i < 16; i++) {
;         const int rl = rbase + (i & 3) + 8 * (i >> 2);
;         const int row = m0 + rl;
;         float o0 = bf2f(Y[(size_t)row * 1024 + 256 + ch0]);
;         float o1 = bf2f(Y[(size_t)row * 1024 + 256 + ch1]);
;         float mean = hsum32(o0 + o1) * (1.0f / 64.0f);
;         float d0 = o0 - mean, d1 = o1 - mean;
;         float var = hsum32(d0 * d0 + d1 * d1) * (1.0f / 64.0f);
;         float rstd = rsqrtf(var + 64e-5f);
.Lgc_epi_post:
	s_lshl_b32 s11, s6, 8
	s_lshl_b32 s12, s4, 6
	s_add_u32 s11, s11, s12
	v_add_u32_e32 v234, s11, v248
	s_lshl_b32 s11, s7, 7
	v_lshl_add_u32 v235, v249, 3, s11
	v_lshlrev_b32_e32 v245, 2, v235
	v_lshlrev_b32_e32 v237, 11, v234
	v_lshl_add_u32 v237, v235, 1, v237
	v_add_u32_e32 v237, 0x200, v237
	v_mul_u32_u24_e32 v239, 0x1600, v234
	v_lshl_add_u32 v239, v235, 1, v239
	v_add_u32_e32 v239, 0x7108f00, v239
	v_mul_u32_u24_e32 v241, 0xc0, v234
	s_lshl_b32 s11, s7, 5
	s_add_u32 s11, s11, 0x47c8108
	v_add_u32_e32 v241, s11, v241
	s_cmp_ge_u32 s6, 64
	s_cbranch_scc1 .Lpo_sample
	global_load_dwordx4 v[130:133], v245, s[2:3] offset:0
	global_load_dwordx4 v[134:137], v245, s[2:3] offset:16
	global_load_dwordx4 v[138:141], v245, s[2:3] offset:128
	global_load_dwordx4 v[142:145], v245, s[2:3] offset:144
	global_load_dwordx4 v[146:149], v245, s[16:17] offset:0
	global_load_dwordx4 v[150:153], v245, s[16:17] offset:16
	global_load_dwordx4 v[154:157], v245, s[16:17] offset:128
	global_load_dwordx4 v[158:161], v245, s[16:17] offset:144
	global_load_dwordx4 v[162:165], v245, s[0:1] offset:0
	global_load_dwordx4 v[166:169], v245, s[0:1] offset:16
	global_load_dwordx4 v[170:173], v245, s[0:1] offset:128
	global_load_dwordx4 v[174:177], v245, s[0:1] offset:144
	v_add_u32_e32 v246, 0x0, v237
	v_add_u32_e32 v247, 0x0, v239
	v_subrev_u32_e32 v230, 0x1600, v247
	global_load_dwordx4 v[178:181], v246, s[22:23] offset:0
	global_load_dwordx4 v[182:185], v246, s[22:23] offset:64
	global_load_dwordx4 v[186:189], v247, s[96:97] offset:0
	global_load_dwordx4 v[190:193], v247, s[96:97] offset:64
	global_load_dwordx4 v[194:197], v230, s[96:97] offset:0
	global_load_dwordx4 v[198:201], v230, s[96:97] offset:64
	v_add_u32_e32 v246, 0x0, v241
	s_nop 0
	global_load_dword v240, v246, s[96:97] offset:0
	v_add_u32_e32 v246, 0x8000, v237
	v_add_u32_e32 v247, 0x16000, v239
	v_subrev_u32_e32 v230, 0x1600, v247
	global_load_dwordx4 v[202:205], v246, s[22:23] offset:0
	global_load_dwordx4 v[206:209], v246, s[22:23] offset:64
	global_load_dwordx4 v[210:213], v247, s[96:97] offset:0
	global_load_dwordx4 v[214:217], v247, s[96:97] offset:64
	global_load_dwordx4 v[218:221], v230, s[96:97] offset:0
	global_load_dwordx4 v[222:225], v230, s[96:97] offset:64
	v_add_u32_e32 v246, 0xc00, v241
	s_nop 0
	global_load_dword v244, v246, s[96:97] offset:0
	s_waitcnt vmcnt(14)
	s_waitcnt vmcnt(7)
	s_and_b32 s18, s6, 7
	s_or_b32 s18, s18, s4
	s_cmp_lg_u32 s18, 0
	s_cbranch_scc1 .Lpo_nostart_p0
	v_cmp_eq_u32_e32 vcc, 0, v248
	s_nop 1
	v_cndmask_b32_e64 v194, v194, 0, vcc
	v_cndmask_b32_e64 v195, v195, 0, vcc
	v_cndmask_b32_e64 v196, v196, 0, vcc
	v_cndmask_b32_e64 v197, v197, 0, vcc
	v_cndmask_b32_e64 v198, v198, 0, vcc
	v_cndmask_b32_e64 v199, v199, 0, vcc
	v_cndmask_b32_e64 v200, v200, 0, vcc
	v_cndmask_b32_e64 v201, v201, 0, vcc
.Lpo_nostart_p0:
	v_lshlrev_b32_e32 v232, 16, v178
	v_and_b32_e32 v233, 0xffff0000, v178
	v_lshlrev_b32_e32 v230, 16, v179
	v_and_b32_e32 v231, 0xffff0000, v179
	v_pk_add_f32 v[232:233], v[232:233], v[230:231]
	v_lshlrev_b32_e32 v230, 16, v180
	v_and_b32_e32 v231, 0xffff0000, v180
	v_pk_add_f32 v[232:233], v[232:233], v[230:231]
	v_lshlrev_b32_e32 v230, 16, v181
	v_and_b32_e32 v231, 0xffff0000, v181
	v_pk_add_f32 v[232:233], v[232:233], v[230:231]
	v_lshlrev_b32_e32 v230, 16, v182
	v_and_b32_e32 v231, 0xffff0000, v182
	v_pk_add_f32 v[232:233], v[232:233], v[230:231]
	v_lshlrev_b32_e32 v230, 16, v183
	v_and_b32_e32 v231, 0xffff0000, v183
	v_pk_add_f32 v[232:233], v[232:233], v[230:231]
	v_lshlrev_b32_e32 v230, 16, v184
	v_and_b32_e32 v231, 0xffff0000, v184
	v_pk_add_f32 v[232:233], v[232:233], v[230:231]
	v_lshlrev_b32_e32 v230, 16, v185
	v_and_b32_e32 v231, 0xffff0000, v185
	v_pk_add_f32 v[232:233], v[232:233], v[230:231]
	v_add_f32_e32 v232, v232, v233
	v_mov_b32_e32 v230, v232
	s_nop 1
	v_permlane16_swap_b32_e32 v230, v232
	v_add_f32_e32 v232, v232, v230
	v_mov_b32_e32 v230, v232
	s_nop 1
	v_permlane32_swap_b32_e32 v230, v232
	v_add_f32_e32 v232, v232, v230
	v_mul_f32_e32 v236, 0x3c800000, v232
	v_lshlrev_b32_e32 v230, 16, v178
	v_and_b32_e32 v231, 0xffff0000, v178
	v_pk_add_f32 v[230:231], v[230:231], v[236:237] op_sel_hi:[1,0] neg_lo:[0,1] neg_hi:[0,1]
	v_pk_mul_f32 v[232:233], v[230:231], v[230:231]
	v_lshlrev_b32_e32 v230, 16, v179
	v_and_b32_e32 v231, 0xffff0000, v179
	v_pk_add_f32 v[230:231], v[230:231], v[236:237] op_sel_hi:[1,0] neg_lo:[0,1] neg_hi:[0,1]
	v_pk_fma_f32 v[232:233], v[230:231], v[230:231], v[232:233]
	v_lshlrev_b32_e32 v230, 16, v180
	v_and_b32_e32 v231, 0xffff0000, v180
	v_pk_add_f32 v[230:231], v[230:231], v[236:237] op_sel_hi:[1,0] neg_lo:[0,1] neg_hi:[0,1]
	v_pk_fma_f32 v[232:233], v[230:231], v[230:231], v[232:233]
	v_lshlrev_b32_e32 v230, 16, v181
	v_and_b32_e32 v231, 0xffff0000, v181
	v_pk_add_f32 v[230:231], v[230:231], v[236:237] op_sel_hi:[1,0] neg_lo:[0,1] neg_hi:[0,1]
	v_pk_fma_f32 v[232:233], v[230:231], v[230:231], v[232:233]
	v_lshlrev_b32_e32 v230, 16, v182
	v_and_b32_e32 v231, 0xffff0000, v182
	v_pk_add_f32 v[230:231], v[230:231], v[236:237] op_sel_hi:[1,0] neg_lo:[0,1] neg_hi:[0,1]
	v_pk_fma_f32 v[232:233], v[230:231], v[230:231], v[232:233]
	v_lshlrev_b32_e32 v230, 16, v183
	v_and_b32_e32 v231, 0xffff0000, v183
	v_pk_add_f32 v[230:231], v[230:231], v[236:237] op_sel_hi:[1,0] neg_lo:[0,1] neg_hi:[0,1]
	v_pk_fma_f32 v[232:233], v[230:231], v[230:231], v[232:233]
	v_lshlrev_b32_e32 v230, 16, v184
	v_and_b32_e32 v231, 0xffff0000, v184
	v_pk_add_f32 v[230:231], v[230:231], v[236:237] op_sel_hi:[1,0] neg_lo:[0,1] neg_hi:[0,1]
	v_pk_fma_f32 v[232:233], v[230:231], v[230:231], v[232:233]
	v_lshlrev_b32_e32 v230, 16, v185
; __device__ __forceinline__ float bf2f(u16 h) { return __uint_as_float(((unsigned)h) << 16); }
; template <int EPI> ...
;     ...
;         float d0 = o0 - mean, d1 = o1 - mean;
;         float var = hsum32(d0 * d0 + d1 * d1) * (1.0f / 64.0f);
;         float rstd = rsqrtf(var + 64e-5f);
;         float pv0 = bf2f(P[(size_t)row * 2816 + 256 + 1536 + ch0]);
;         float pv1 = bf2f(P[(size_t)row * 2816 + 256 + 1536 + ch1]);
;         float pp0 = prevP(p, P, row, 1536 + ch0), pp1 = prevP(p, P, row, 1536 + ch1);
;         float vv0 = pv0 + (pp0 - pv0) * mu0, vv1 = pv1 + (pp1 - pv1) * mu1;
;         float b = bs[((size_t)row * 12 + hh) * 4 + 2];
;         float y0 = (d0 * rstd * gg0 + gb0 + b * vv0) * acc0[i];
;         float y1 = (d1 * rstd * gg1 + gb1 + b * vv1) * acc1[i];
;         Y[(size_t)row * 1024 + 256 + ch0] = f2bf(y0);
;         Y[(size_t)row * 1024 + 256 + ch1] = f2bf(y1);
;       }
	v_and_b32_e32 v231, 0xffff0000, v185
	v_pk_add_f32 v[230:231], v[230:231], v[236:237] op_sel_hi:[1,0] neg_lo:[0,1] neg_hi:[0,1]
	v_pk_fma_f32 v[232:233], v[230:231], v[230:231], v[232:233]
	v_add_f32_e32 v232, v232, v233
	v_mov_b32_e32 v230, v232
	s_nop 1
	v_permlane16_swap_b32_e32 v230, v232
	v_add_f32_e32 v232, v232, v230
	v_mov_b32_e32 v230, v232
	s_nop 1
	v_permlane32_swap_b32_e32 v230, v232
	v_add_f32_e32 v232, v232, v230
	v_mov_b32_e32 v230, 0x3a27c5ac
	v_fmamk_f32 v232, v232, 0x3c800000, v230
	v_rsq_f32_e32 v238, v232
	v_add_u32_e32 v243, 0x0, v237
	v_lshlrev_b32_e32 v230, 16, v178
	v_and_b32_e32 v231, 0xffff0000, v178
	v_lshlrev_b32_e32 v232, 16, v186
	v_and_b32_e32 v233, 0xffff0000, v186
	v_lshlrev_b32_e32 v234, 16, v194
	v_and_b32_e32 v235, 0xffff0000, v194
	v_pk_add_f32 v[230:231], v[230:231], v[236:237] op_sel_hi:[1,0] neg_lo:[0,1] neg_hi:[0,1]
	v_pk_add_f32 v[234:235], v[234:235], v[232:233] neg_lo:[0,1] neg_hi:[0,1]
	v_pk_mul_f32 v[230:231], v[230:231], v[238:239] op_sel_hi:[1,0]
	v_pk_fma_f32 v[232:233], v[162:163], v[234:235], v[232:233]
	v_pk_fma_f32 v[230:231], v[130:131], v[230:231], v[146:147]
	v_pk_fma_f32 v[230:231], v[240:241], v[232:233], v[230:231] op_sel_hi:[0,1,1]
	v_pk_mul_f32 v[0:1], v[0:1], v[230:231]
	v_lshlrev_b32_e32 v230, 16, v179
	v_and_b32_e32 v231, 0xffff0000, v179
	v_lshlrev_b32_e32 v232, 16, v187
	v_and_b32_e32 v233, 0xffff0000, v187
	v_lshlrev_b32_e32 v234, 16, v195
	v_and_b32_e32 v235, 0xffff0000, v195
	v_pk_add_f32 v[230:231], v[230:231], v[236:237] op_sel_hi:[1,0] neg_lo:[0,1] neg_hi:[0,1]
	v_pk_add_f32 v[234:235], v[234:235], v[232:233] neg_lo:[0,1] neg_hi:[0,1]
	v_pk_mul_f32 v[230:231], v[230:231], v[238:239] op_sel_hi:[1,0]
	v_pk_fma_f32 v[232:233], v[164:165], v[234:235], v[232:233]
	v_pk_fma_f32 v[230:231], v[132:133], v[230:231], v[148:149]
	v_pk_fma_f32 v[230:231], v[240:241], v[232:233], v[230:231] op_sel_hi:[0,1,1]
	v_pk_mul_f32 v[2:3], v[2:3], v[230:231]
	v_lshlrev_b32_e32 v230, 16, v180
	v_and_b32_e32 v231, 0xffff0000, v180
	v_lshlrev_b32_e32 v232, 16, v188
	v_and_b32_e32 v233, 0xffff0000, v188
	v_lshlrev_b32_e32 v234, 16, v196
	v_and_b32_e32 v235, 0xffff0000, v196
	v_pk_add_f32 v[230:231], v[230:231], v[236:237] op_sel_hi:[1,0] neg_lo:[0,1] neg_hi:[0,1]
	v_pk_add_f32 v[234:235], v[234:235], v[232:233] neg_lo:[0,1] neg_hi:[0,1]
	v_pk_mul_f32 v[230:231], v[230:231], v[238:239] op_sel_hi:[1,0]
	v_pk_fma_f32 v[232:233], v[166:167], v[234:235], v[232:233]
	v_pk_fma_f32 v[230:231], v[134:135], v[230:231], v[150:151]
	v_pk_fma_f32 v[230:231], v[240:241], v[232:233], v[230:231] op_sel_hi:[0,1,1]
	v_pk_mul_f32 v[4:5], v[4:5], v[230:231]
	v_lshlrev_b32_e32 v230, 16, v181
	v_and_b32_e32 v231, 0xffff0000, v181
	v_lshlrev_b32_e32 v232, 16, v189
	v_and_b32_e32 v233, 0xffff0000, v189
	v_lshlrev_b32_e32 v234, 16, v197
	v_and_b32_e32 v235, 0xffff0000, v197
	v_pk_add_f32 v[230:231], v[230:231], v[236:237] op_sel_hi:[1,0] neg_lo:[0,1] neg_hi:[0,1]
	v_pk_add_f32 v[234:235], v[234:235], v[232:233] neg_lo:[0,1] neg_hi:[0,1]
	v_pk_mul_f32 v[230:231], v[230:231], v[238:239] op_sel_hi:[1,0]
	v_pk_fma_f32 v[232:233], v[168:169], v[234:235], v[232:233]
	v_pk_fma_f32 v[230:231], v[136:137], v[230:231], v[152:153]
	v_pk_fma_f32 v[230:231], v[240:241], v[232:233], v[230:231] op_sel_hi:[0,1,1]
	v_pk_mul_f32 v[6:7], v[6:7], v[230:231]
	v_cvt_pk_bf16_f32 v0, v0, v1
	v_cvt_pk_bf16_f32 v1, v2, v3
	v_cvt_pk_bf16_f32 v2, v4, v5
	v_cvt_pk_bf16_f32 v3, v6, v7
	global_store_dwordx4 v243, v[0:3], s[22:23] offset:0
	v_lshlrev_b32_e32 v230, 16, v182
	v_and_b32_e32 v231, 0xffff0000, v182
	v_lshlrev_b32_e32 v232, 16, v190
	v_and_b32_e32 v233, 0xffff0000, v190
	v_lshlrev_b32_e32 v234, 16, v198
	v_and_b32_e32 v235, 0xffff0000, v198
	v_pk_add_f32 v[230:231], v[230:231], v[236:237] op_sel_hi:[1,0] neg_lo:[0,1] neg_hi:[0,1]
	v_pk_add_f32 v[234:235], v[234:235], v[232:233] neg_lo:[0,1] neg_hi:[0,1]
	v_pk_mul_f32 v[230:231], v[230:231], v[238:239] op_sel_hi:[1,0]
	v_pk_fma_f32 v[232:233], v[170:171], v[234:235], v[232:233]
	v_pk_fma_f32 v[230:231], v[138:139], v[230:231], v[154:155]
	v_pk_fma_f32 v[230:231], v[240:241], v[232:233], v[230:231] op_sel_hi:[0,1,1]
	v_pk_mul_f32 v[8:9], v[8:9], v[230:231]
	v_lshlrev_b32_e32 v230, 16, v183
	v_and_b32_e32 v231, 0xffff0000, v183
	v_lshlrev_b32_e32 v232, 16, v191
	v_and_b32_e32 v233, 0xffff0000, v191
	v_lshlrev_b32_e32 v234, 16, v199
	v_and_b32_e32 v235, 0xffff0000, v199
	v_pk_add_f32 v[230:231], v[230:231], v[236:237] op_sel_hi:[1,0] neg_lo:[0,1] neg_hi:[0,1]
	v_pk_add_f32 v[234:235], v[234:235], v[232:233] neg_lo:[0,1] neg_hi:[0,1]
	v_pk_mul_f32 v[230:231], v[230:231], v[238:239] op_sel_hi:[1,0]
	v_pk_fma_f32 v[232:233], v[172:173], v[234:235], v[232:233]
	v_pk_fma_f32 v[230:231], v[140:141], v[230:231], v[156:157]
	v_pk_fma_f32 v[230:231], v[240:241], v[232:233], v[230:231] op_sel_hi:[0,1,1]
	v_pk_mul_f32 v[10:11], v[10:11], v[230:231]
	v_lshlrev_b32_e32 v230, 16, v184
	v_and_b32_e32 v231, 0xffff0000, v184
	v_lshlrev_b32_e32 v232, 16, v192
	v_and_b32_e32 v233, 0xffff0000, v192
	v_lshlrev_b32_e32 v234, 16, v200
	v_and_b32_e32 v235, 0xffff0000, v200
	v_pk_add_f32 v[230:231], v[230:231], v[236:237] op_sel_hi:[1,0] neg_lo:[0,1] neg_hi:[0,1]
	v_pk_add_f32 v[234:235], v[234:235], v[232:233] neg_lo:[0,1] neg_hi:[0,1]
	v_pk_mul_f32 v[230:231], v[230:231], v[238:239] op_sel_hi:[1,0]
	v_pk_fma_f32 v[232:233], v[174:175], v[234:235], v[232:233]
	v_pk_fma_f32 v[230:231], v[142:143], v[230:231], v[158:159]
	v_pk_fma_f32 v[230:231], v[240:241], v[232:233], v[230:231] op_sel_hi:[0,1,1]
	v_pk_mul_f32 v[12:13], v[12:13], v[230:231]
	v_lshlrev_b32_e32 v230, 16, v185
	v_and_b32_e32 v231, 0xffff0000, v185
	v_lshlrev_b32_e32 v232, 16, v193
	v_and_b32_e32 v233, 0xffff0000, v193
	v_lshlrev_b32_e32 v234, 16, v201
	v_and_b32_e32 v235, 0xffff0000, v201
	v_pk_add_f32 v[230:231], v[230:231], v[236:237] op_sel_hi:[1,0] neg_lo:[0,1] neg_hi:[0,1]
	v_pk_add_f32 v[234:235], v[234:235], v[232:233] neg_lo:[0,1] neg_hi:[0,1]
	v_pk_mul_f32 v[230:231], v[230:231], v[238:239] op_sel_hi:[1,0]
	v_pk_fma_f32 v[232:233], v[176:177], v[234:235], v[232:233]
	v_pk_fma_f32 v[230:231], v[144:145], v[230:231], v[160:161]
	v_pk_fma_f32 v[230:231], v[240:241], v[232:233], v[230:231] op_sel_hi:[0,1,1]
	v_pk_mul_f32 v[14:15], v[14:15], v[230:231]
	v_cvt_pk_bf16_f32 v8, v8, v9
	v_cvt_pk_bf16_f32 v9, v10, v11
	v_cvt_pk_bf16_f32 v10, v12, v13
	v_cvt_pk_bf16_f32 v11, v14, v15
	global_store_dwordx4 v243, v[8:11], s[22:23] offset:64
	v_add_u32_e32 v246, 0x10000, v237
	v_add_u32_e32 v247, 0x2c000, v239
	v_subrev_u32_e32 v230, 0x1600, v247
	global_load_dwordx4 v[178:181], v246, s[22:23] offset:0
	global_load_dwordx4 v[182:185], v246, s[22:23] offset:64
	global_load_dwordx4 v[186:189], v247, s[96:97] offset:0
	global_load_dwordx4 v[190:193], v247, s[96:97] offset:64
	global_load_dwordx4 v[194:197], v230, s[96:97] offset:0
	global_load_dwordx4 v[198:201], v230, s[96:97] offset:64
	v_add_u32_e32 v246, 0x1800, v241
	s_nop 0
	global_load_dword v240, v246, s[96:97] offset:0
	s_waitcnt vmcnt(9)
; __device__ __forceinline__ float bf2f(u16 h) { return __uint_as_float(((unsigned)h) << 16); }
; template <int EPI> ...
;     ...
;         float o0 = bf2f(Y[(size_t)row * 1024 + 256 + ch0]);
;         float o1 = bf2f(Y[(size_t)row * 1024 + 256 + ch1]);
;         float mean = hsum32(o0 + o1) * (1.0f / 64.0f);
;         float d0 = o0 - mean, d1 = o1 - mean;
;         float var = hsum32(d0 * d0 + d1 * d1) * (1.0f / 64.0f);
;         float rstd = rsqrtf(var + 64e-5f);
;         float pv0 = bf2f(P[(size_t)row * 2816 + 256 + 1536 + ch0]);
;         float pv1 = bf2f(P[(size_t)row * 2816 + 256 + 1536 + ch1]);
;         float pp0 = prevP(p, P, row, 1536 + ch0), pp1 = prevP(p, P, row, 1536 + ch1);
;         float vv0 = pv0 + (pp0 - pv0) * mu0, vv1 = pv1 + (pp1 - pv1) * mu1;
;         float b = bs[((size_t)row * 12 + hh) * 4 + 2];
;         float y0 = (d0 * rstd * gg0 + gb0 + b * vv0) * acc0[i];
;         float y1 = (d1 * rstd * gg1 + gb1 + b * vv1) * acc1[i];
;         Y[(size_t)row * 1024 + 256 + ch0] = f2bf(y0);
	v_lshlrev_b32_e32 v232, 16, v202
	v_and_b32_e32 v233, 0xffff0000, v202
	v_lshlrev_b32_e32 v230, 16, v203
	v_and_b32_e32 v231, 0xffff0000, v203
	v_pk_add_f32 v[232:233], v[232:233], v[230:231]
	v_lshlrev_b32_e32 v230, 16, v204
	v_and_b32_e32 v231, 0xffff0000, v204
	v_pk_add_f32 v[232:233], v[232:233], v[230:231]
	v_lshlrev_b32_e32 v230, 16, v205
	v_and_b32_e32 v231, 0xffff0000, v205
	v_pk_add_f32 v[232:233], v[232:233], v[230:231]
	v_lshlrev_b32_e32 v230, 16, v206
	v_and_b32_e32 v231, 0xffff0000, v206
	v_pk_add_f32 v[232:233], v[232:233], v[230:231]
	v_lshlrev_b32_e32 v230, 16, v207
	v_and_b32_e32 v231, 0xffff0000, v207
	v_pk_add_f32 v[232:233], v[232:233], v[230:231]
	v_lshlrev_b32_e32 v230, 16, v208
	v_and_b32_e32 v231, 0xffff0000, v208
	v_pk_add_f32 v[232:233], v[232:233], v[230:231]
	v_lshlrev_b32_e32 v230, 16, v209
	v_and_b32_e32 v231, 0xffff0000, v209
	v_pk_add_f32 v[232:233], v[232:233], v[230:231]
	v_add_f32_e32 v232, v232, v233
	v_mov_b32_e32 v230, v232
	s_nop 1
	v_permlane16_swap_b32_e32 v230, v232
	v_add_f32_e32 v232, v232, v230
	v_mov_b32_e32 v230, v232
	s_nop 1
	v_permlane32_swap_b32_e32 v230, v232
	v_add_f32_e32 v232, v232, v230
	v_mul_f32_e32 v236, 0x3c800000, v232
	v_lshlrev_b32_e32 v230, 16, v202
	v_and_b32_e32 v231, 0xffff0000, v202
	v_pk_add_f32 v[230:231], v[230:231], v[236:237] op_sel_hi:[1,0] neg_lo:[0,1] neg_hi:[0,1]
	v_pk_mul_f32 v[232:233], v[230:231], v[230:231]
	v_lshlrev_b32_e32 v230, 16, v203
	v_and_b32_e32 v231, 0xffff0000, v203
	v_pk_add_f32 v[230:231], v[230:231], v[236:237] op_sel_hi:[1,0] neg_lo:[0,1] neg_hi:[0,1]
	v_pk_fma_f32 v[232:233], v[230:231], v[230:231], v[232:233]
	v_lshlrev_b32_e32 v230, 16, v204
	v_and_b32_e32 v231, 0xffff0000, v204
	v_pk_add_f32 v[230:231], v[230:231], v[236:237] op_sel_hi:[1,0] neg_lo:[0,1] neg_hi:[0,1]
	v_pk_fma_f32 v[232:233], v[230:231], v[230:231], v[232:233]
	v_lshlrev_b32_e32 v230, 16, v205
	v_and_b32_e32 v231, 0xffff0000, v205
	v_pk_add_f32 v[230:231], v[230:231], v[236:237] op_sel_hi:[1,0] neg_lo:[0,1] neg_hi:[0,1]
	v_pk_fma_f32 v[232:233], v[230:231], v[230:231], v[232:233]
	v_lshlrev_b32_e32 v230, 16, v206
	v_and_b32_e32 v231, 0xffff0000, v206
	v_pk_add_f32 v[230:231], v[230:231], v[236:237] op_sel_hi:[1,0] neg_lo:[0,1] neg_hi:[0,1]
	v_pk_fma_f32 v[232:233], v[230:231], v[230:231], v[232:233]
	v_lshlrev_b32_e32 v230, 16, v207
	v_and_b32_e32 v231, 0xffff0000, v207
	v_pk_add_f32 v[230:231], v[230:231], v[236:237] op_sel_hi:[1,0] neg_lo:[0,1] neg_hi:[0,1]
	v_pk_fma_f32 v[232:233], v[230:231], v[230:231], v[232:233]
	v_lshlrev_b32_e32 v230, 16, v208
	v_and_b32_e32 v231, 0xffff0000, v208
	v_pk_add_f32 v[230:231], v[230:231], v[236:237] op_sel_hi:[1,0] neg_lo:[0,1] neg_hi:[0,1]
	v_pk_fma_f32 v[232:233], v[230:231], v[230:231], v[232:233]
	v_lshlrev_b32_e32 v230, 16, v209
	v_and_b32_e32 v231, 0xffff0000, v209
	v_pk_add_f32 v[230:231], v[230:231], v[236:237] op_sel_hi:[1,0] neg_lo:[0,1] neg_hi:[0,1]
	v_pk_fma_f32 v[232:233], v[230:231], v[230:231], v[232:233]
	v_add_f32_e32 v232, v232, v233
	v_mov_b32_e32 v230, v232
	s_nop 1
	v_permlane16_swap_b32_e32 v230, v232
	v_add_f32_e32 v232, v232, v230
	v_mov_b32_e32 v230, v232
	s_nop 1
	v_permlane32_swap_b32_e32 v230, v232
	v_add_f32_e32 v232, v232, v230
	v_mov_b32_e32 v230, 0x3a27c5ac
	v_fmamk_f32 v232, v232, 0x3c800000, v230
	v_rsq_f32_e32 v238, v232
	v_add_u32_e32 v243, 0x8000, v237
	v_lshlrev_b32_e32 v230, 16, v202
	v_and_b32_e32 v231, 0xffff0000, v202
	v_lshlrev_b32_e32 v232, 16, v210
	v_and_b32_e32 v233, 0xffff0000, v210
	v_lshlrev_b32_e32 v234, 16, v218
	v_and_b32_e32 v235, 0xffff0000, v218
	v_pk_add_f32 v[230:231], v[230:231], v[236:237] op_sel_hi:[1,0] neg_lo:[0,1] neg_hi:[0,1]
	v_pk_add_f32 v[234:235], v[234:235], v[232:233] neg_lo:[0,1] neg_hi:[0,1]
	v_pk_mul_f32 v[230:231], v[230:231], v[238:239] op_sel_hi:[1,0]
	v_pk_fma_f32 v[232:233], v[162:163], v[234:235], v[232:233]
	v_pk_fma_f32 v[230:231], v[130:131], v[230:231], v[146:147]
	v_pk_fma_f32 v[230:231], v[244:245], v[232:233], v[230:231] op_sel_hi:[0,1,1]
	v_pk_mul_f32 v[32:33], v[32:33], v[230:231]
	v_lshlrev_b32_e32 v230, 16, v203
	v_and_b32_e32 v231, 0xffff0000, v203
	v_lshlrev_b32_e32 v232, 16, v211
	v_and_b32_e32 v233, 0xffff0000, v211
	v_lshlrev_b32_e32 v234, 16, v219
	v_and_b32_e32 v235, 0xffff0000, v219
	v_pk_add_f32 v[230:231], v[230:231], v[236:237] op_sel_hi:[1,0] neg_lo:[0,1] neg_hi:[0,1]
	v_pk_add_f32 v[234:235], v[234:235], v[232:233] neg_lo:[0,1] neg_hi:[0,1]
	v_pk_mul_f32 v[230:231], v[230:231], v[238:239] op_sel_hi:[1,0]
	v_pk_fma_f32 v[232:233], v[164:165], v[234:235], v[232:233]
	v_pk_fma_f32 v[230:231], v[132:133], v[230:231], v[148:149]
	v_pk_fma_f32 v[230:231], v[244:245], v[232:233], v[230:231] op_sel_hi:[0,1,1]
	v_pk_mul_f32 v[34:35], v[34:35], v[230:231]
	v_lshlrev_b32_e32 v230, 16, v204
	v_and_b32_e32 v231, 0xffff0000, v204
	v_lshlrev_b32_e32 v232, 16, v212
	v_and_b32_e32 v233, 0xffff0000, v212
	v_lshlrev_b32_e32 v234, 16, v220
	v_and_b32_e32 v235, 0xffff0000, v220
	v_pk_add_f32 v[230:231], v[230:231], v[236:237] op_sel_hi:[1,0] neg_lo:[0,1] neg_hi:[0,1]
	v_pk_add_f32 v[234:235], v[234:235], v[232:233] neg_lo:[0,1] neg_hi:[0,1]
	v_pk_mul_f32 v[230:231], v[230:231], v[238:239] op_sel_hi:[1,0]
	v_pk_fma_f32 v[232:233], v[166:167], v[234:235], v[232:233]
	v_pk_fma_f32 v[230:231], v[134:135], v[230:231], v[150:151]
	v_pk_fma_f32 v[230:231], v[244:245], v[232:233], v[230:231] op_sel_hi:[0,1,1]
	v_pk_mul_f32 v[36:37], v[36:37], v[230:231]
	v_lshlrev_b32_e32 v230, 16, v205
	v_and_b32_e32 v231, 0xffff0000, v205
	v_lshlrev_b32_e32 v232, 16, v213
	v_and_b32_e32 v233, 0xffff0000, v213
	v_lshlrev_b32_e32 v234, 16, v221
	v_and_b32_e32 v235, 0xffff0000, v221
; __device__ __forceinline__ float bf2f(u16 h) { return __uint_as_float(((unsigned)h) << 16); }
; template <int EPI> ...
;     ...
;         float o0 = bf2f(Y[(size_t)row * 1024 + 256 + ch0]);
;         float o1 = bf2f(Y[(size_t)row * 1024 + 256 + ch1]);
;         float mean = hsum32(o0 + o1) * (1.0f / 64.0f);
;         float d0 = o0 - mean, d1 = o1 - mean;
;         float var = hsum32(d0 * d0 + d1 * d1) * (1.0f / 64.0f);
;         float rstd = rsqrtf(var + 64e-5f);
;         float pv0 = bf2f(P[(size_t)row * 2816 + 256 + 1536 + ch0]);
;         float pv1 = bf2f(P[(size_t)row * 2816 + 256 + 1536 + ch1]);
;         float pp0 = prevP(p, P, row, 1536 + ch0), pp1 = prevP(p, P, row, 1536 + ch1);
;         float vv0 = pv0 + (pp0 - pv0) * mu0, vv1 = pv1 + (pp1 - pv1) * mu1;
;         float b = bs[((size_t)row * 12 + hh) * 4 + 2];
;         float y0 = (d0 * rstd * gg0 + gb0 + b * vv0) * acc0[i];
;         float y1 = (d1 * rstd * gg1 + gb1 + b * vv1) * acc1[i];
;         Y[(size_t)row * 1024 + 256 + ch0] = f2bf(y0);
;         Y[(size_t)row * 1024 + 256 + ch1] = f2bf(y1);
;       }
	v_pk_add_f32 v[230:231], v[230:231], v[236:237] op_sel_hi:[1,0] neg_lo:[0,1] neg_hi:[0,1]
	v_pk_add_f32 v[234:235], v[234:235], v[232:233] neg_lo:[0,1] neg_hi:[0,1]
	v_pk_mul_f32 v[230:231], v[230:231], v[238:239] op_sel_hi:[1,0]
	v_pk_fma_f32 v[232:233], v[168:169], v[234:235], v[232:233]
	v_pk_fma_f32 v[230:231], v[136:137], v[230:231], v[152:153]
	v_pk_fma_f32 v[230:231], v[244:245], v[232:233], v[230:231] op_sel_hi:[0,1,1]
	v_pk_mul_f32 v[38:39], v[38:39], v[230:231]
	v_cvt_pk_bf16_f32 v32, v32, v33
	v_cvt_pk_bf16_f32 v33, v34, v35
	v_cvt_pk_bf16_f32 v34, v36, v37
	v_cvt_pk_bf16_f32 v35, v38, v39
	global_store_dwordx4 v243, v[32:35], s[22:23] offset:0
	v_lshlrev_b32_e32 v230, 16, v206
	v_and_b32_e32 v231, 0xffff0000, v206
	v_lshlrev_b32_e32 v232, 16, v214
	v_and_b32_e32 v233, 0xffff0000, v214
	v_lshlrev_b32_e32 v234, 16, v222
	v_and_b32_e32 v235, 0xffff0000, v222
	v_pk_add_f32 v[230:231], v[230:231], v[236:237] op_sel_hi:[1,0] neg_lo:[0,1] neg_hi:[0,1]
	v_pk_add_f32 v[234:235], v[234:235], v[232:233] neg_lo:[0,1] neg_hi:[0,1]
	v_pk_mul_f32 v[230:231], v[230:231], v[238:239] op_sel_hi:[1,0]
	v_pk_fma_f32 v[232:233], v[170:171], v[234:235], v[232:233]
	v_pk_fma_f32 v[230:231], v[138:139], v[230:231], v[154:155]
	v_pk_fma_f32 v[230:231], v[244:245], v[232:233], v[230:231] op_sel_hi:[0,1,1]
	v_pk_mul_f32 v[40:41], v[40:41], v[230:231]
	v_lshlrev_b32_e32 v230, 16, v207
	v_and_b32_e32 v231, 0xffff0000, v207
	v_lshlrev_b32_e32 v232, 16, v215
	v_and_b32_e32 v233, 0xffff0000, v215
	v_lshlrev_b32_e32 v234, 16, v223
	v_and_b32_e32 v235, 0xffff0000, v223
	v_pk_add_f32 v[230:231], v[230:231], v[236:237] op_sel_hi:[1,0] neg_lo:[0,1] neg_hi:[0,1]
	v_pk_add_f32 v[234:235], v[234:235], v[232:233] neg_lo:[0,1] neg_hi:[0,1]
	v_pk_mul_f32 v[230:231], v[230:231], v[238:239] op_sel_hi:[1,0]
	v_pk_fma_f32 v[232:233], v[172:173], v[234:235], v[232:233]
	v_pk_fma_f32 v[230:231], v[140:141], v[230:231], v[156:157]
	v_pk_fma_f32 v[230:231], v[244:245], v[232:233], v[230:231] op_sel_hi:[0,1,1]
	v_pk_mul_f32 v[42:43], v[42:43], v[230:231]
	v_lshlrev_b32_e32 v230, 16, v208
	v_and_b32_e32 v231, 0xffff0000, v208
	v_lshlrev_b32_e32 v232, 16, v216
	v_and_b32_e32 v233, 0xffff0000, v216
	v_lshlrev_b32_e32 v234, 16, v224
	v_and_b32_e32 v235, 0xffff0000, v224
	v_pk_add_f32 v[230:231], v[230:231], v[236:237] op_sel_hi:[1,0] neg_lo:[0,1] neg_hi:[0,1]
	v_pk_add_f32 v[234:235], v[234:235], v[232:233] neg_lo:[0,1] neg_hi:[0,1]
	v_pk_mul_f32 v[230:231], v[230:231], v[238:239] op_sel_hi:[1,0]
	v_pk_fma_f32 v[232:233], v[174:175], v[234:235], v[232:233]
	v_pk_fma_f32 v[230:231], v[142:143], v[230:231], v[158:159]
	v_pk_fma_f32 v[230:231], v[244:245], v[232:233], v[230:231] op_sel_hi:[0,1,1]
	v_pk_mul_f32 v[44:45], v[44:45], v[230:231]
	v_lshlrev_b32_e32 v230, 16, v209
	v_and_b32_e32 v231, 0xffff0000, v209
	v_lshlrev_b32_e32 v232, 16, v217
	v_and_b32_e32 v233, 0xffff0000, v217
	v_lshlrev_b32_e32 v234, 16, v225
	v_and_b32_e32 v235, 0xffff0000, v225
	v_pk_add_f32 v[230:231], v[230:231], v[236:237] op_sel_hi:[1,0] neg_lo:[0,1] neg_hi:[0,1]
	v_pk_add_f32 v[234:235], v[234:235], v[232:233] neg_lo:[0,1] neg_hi:[0,1]
	v_pk_mul_f32 v[230:231], v[230:231], v[238:239] op_sel_hi:[1,0]
	v_pk_fma_f32 v[232:233], v[176:177], v[234:235], v[232:233]
	v_pk_fma_f32 v[230:231], v[144:145], v[230:231], v[160:161]
	v_pk_fma_f32 v[230:231], v[244:245], v[232:233], v[230:231] op_sel_hi:[0,1,1]
	v_pk_mul_f32 v[46:47], v[46:47], v[230:231]
	v_cvt_pk_bf16_f32 v40, v40, v41
	v_cvt_pk_bf16_f32 v41, v42, v43
	v_cvt_pk_bf16_f32 v42, v44, v45
	v_cvt_pk_bf16_f32 v43, v46, v47
	global_store_dwordx4 v243, v[40:43], s[22:23] offset:64
	v_add_u32_e32 v246, 0x18000, v237
	v_add_u32_e32 v247, 0x42000, v239
	v_subrev_u32_e32 v230, 0x1600, v247
	global_load_dwordx4 v[202:205], v246, s[22:23] offset:0
	global_load_dwordx4 v[206:209], v246, s[22:23] offset:64
	global_load_dwordx4 v[210:213], v247, s[96:97] offset:0
	global_load_dwordx4 v[214:217], v247, s[96:97] offset:64
	global_load_dwordx4 v[218:221], v230, s[96:97] offset:0
	global_load_dwordx4 v[222:225], v230, s[96:97] offset:64
	v_add_u32_e32 v246, 0x2400, v241
	s_nop 0
	global_load_dword v244, v246, s[96:97] offset:0
	s_waitcnt vmcnt(9)
	v_lshlrev_b32_e32 v232, 16, v178
	v_and_b32_e32 v233, 0xffff0000, v178
	v_lshlrev_b32_e32 v230, 16, v179
	v_and_b32_e32 v231, 0xffff0000, v179
	v_pk_add_f32 v[232:233], v[232:233], v[230:231]
	v_lshlrev_b32_e32 v230, 16, v180
	v_and_b32_e32 v231, 0xffff0000, v180
	v_pk_add_f32 v[232:233], v[232:233], v[230:231]
	v_lshlrev_b32_e32 v230, 16, v181
	v_and_b32_e32 v231, 0xffff0000, v181
	v_pk_add_f32 v[232:233], v[232:233], v[230:231]
	v_lshlrev_b32_e32 v230, 16, v182
	v_and_b32_e32 v231, 0xffff0000, v182
	v_pk_add_f32 v[232:233], v[232:233], v[230:231]
	v_lshlrev_b32_e32 v230, 16, v183
	v_and_b32_e32 v231, 0xffff0000, v183
	v_pk_add_f32 v[232:233], v[232:233], v[230:231]
	v_lshlrev_b32_e32 v230, 16, v184
	v_and_b32_e32 v231, 0xffff0000, v184
	v_pk_add_f32 v[232:233], v[232:233], v[230:231]
	v_lshlrev_b32_e32 v230, 16, v185
	v_and_b32_e32 v231, 0xffff0000, v185
	v_pk_add_f32 v[232:233], v[232:233], v[230:231]
	v_add_f32_e32 v232, v232, v233
	v_mov_b32_e32 v230, v232
	s_nop 1
	v_permlane16_swap_b32_e32 v230, v232
	v_add_f32_e32 v232, v232, v230
	v_mov_b32_e32 v230, v232
	s_nop 1
	v_permlane32_swap_b32_e32 v230, v232
	v_add_f32_e32 v232, v232, v230
	v_mul_f32_e32 v236, 0x3c800000, v232
	v_lshlrev_b32_e32 v230, 16, v178
	v_and_b32_e32 v231, 0xffff0000, v178
	v_pk_add_f32 v[230:231], v[230:231], v[236:237] op_sel_hi:[1,0] neg_lo:[0,1] neg_hi:[0,1]
	v_pk_mul_f32 v[232:233], v[230:231], v[230:231]
	v_lshlrev_b32_e32 v230, 16, v179
; __device__ __forceinline__ float bf2f(u16 h) { return __uint_as_float(((unsigned)h) << 16); }
; template <int EPI> ...
;     ...
;         float d0 = o0 - mean, d1 = o1 - mean;
;         float var = hsum32(d0 * d0 + d1 * d1) * (1.0f / 64.0f);
;         float rstd = rsqrtf(var + 64e-5f);
;         float pv0 = bf2f(P[(size_t)row * 2816 + 256 + 1536 + ch0]);
;         float pv1 = bf2f(P[(size_t)row * 2816 + 256 + 1536 + ch1]);
;         float pp0 = prevP(p, P, row, 1536 + ch0), pp1 = prevP(p, P, row, 1536 + ch1);
;         float vv0 = pv0 + (pp0 - pv0) * mu0, vv1 = pv1 + (pp1 - pv1) * mu1;
;         float b = bs[((size_t)row * 12 + hh) * 4 + 2];
;         float y0 = (d0 * rstd * gg0 + gb0 + b * vv0) * acc0[i];
;         float y1 = (d1 * rstd * gg1 + gb1 + b * vv1) * acc1[i];
;         Y[(size_t)row * 1024 + 256 + ch0] = f2bf(y0);
;         Y[(size_t)row * 1024 + 256 + ch1] = f2bf(y1);
;       }
	v_and_b32_e32 v231, 0xffff0000, v179
	v_pk_add_f32 v[230:231], v[230:231], v[236:237] op_sel_hi:[1,0] neg_lo:[0,1] neg_hi:[0,1]
	v_pk_fma_f32 v[232:233], v[230:231], v[230:231], v[232:233]
	v_lshlrev_b32_e32 v230, 16, v180
	v_and_b32_e32 v231, 0xffff0000, v180
	v_pk_add_f32 v[230:231], v[230:231], v[236:237] op_sel_hi:[1,0] neg_lo:[0,1] neg_hi:[0,1]
	v_pk_fma_f32 v[232:233], v[230:231], v[230:231], v[232:233]
	v_lshlrev_b32_e32 v230, 16, v181
	v_and_b32_e32 v231, 0xffff0000, v181
	v_pk_add_f32 v[230:231], v[230:231], v[236:237] op_sel_hi:[1,0] neg_lo:[0,1] neg_hi:[0,1]
	v_pk_fma_f32 v[232:233], v[230:231], v[230:231], v[232:233]
	v_lshlrev_b32_e32 v230, 16, v182
	v_and_b32_e32 v231, 0xffff0000, v182
	v_pk_add_f32 v[230:231], v[230:231], v[236:237] op_sel_hi:[1,0] neg_lo:[0,1] neg_hi:[0,1]
	v_pk_fma_f32 v[232:233], v[230:231], v[230:231], v[232:233]
	v_lshlrev_b32_e32 v230, 16, v183
	v_and_b32_e32 v231, 0xffff0000, v183
	v_pk_add_f32 v[230:231], v[230:231], v[236:237] op_sel_hi:[1,0] neg_lo:[0,1] neg_hi:[0,1]
	v_pk_fma_f32 v[232:233], v[230:231], v[230:231], v[232:233]
	v_lshlrev_b32_e32 v230, 16, v184
	v_and_b32_e32 v231, 0xffff0000, v184
	v_pk_add_f32 v[230:231], v[230:231], v[236:237] op_sel_hi:[1,0] neg_lo:[0,1] neg_hi:[0,1]
	v_pk_fma_f32 v[232:233], v[230:231], v[230:231], v[232:233]
	v_lshlrev_b32_e32 v230, 16, v185
	v_and_b32_e32 v231, 0xffff0000, v185
	v_pk_add_f32 v[230:231], v[230:231], v[236:237] op_sel_hi:[1,0] neg_lo:[0,1] neg_hi:[0,1]
	v_pk_fma_f32 v[232:233], v[230:231], v[230:231], v[232:233]
	v_add_f32_e32 v232, v232, v233
	v_mov_b32_e32 v230, v232
	s_nop 1
	v_permlane16_swap_b32_e32 v230, v232
	v_add_f32_e32 v232, v232, v230
	v_mov_b32_e32 v230, v232
	s_nop 1
	v_permlane32_swap_b32_e32 v230, v232
	v_add_f32_e32 v232, v232, v230
	v_mov_b32_e32 v230, 0x3a27c5ac
	v_fmamk_f32 v232, v232, 0x3c800000, v230
	v_rsq_f32_e32 v238, v232
	v_add_u32_e32 v243, 0x10000, v237
	v_lshlrev_b32_e32 v230, 16, v178
	v_and_b32_e32 v231, 0xffff0000, v178
	v_lshlrev_b32_e32 v232, 16, v186
	v_and_b32_e32 v233, 0xffff0000, v186
	v_lshlrev_b32_e32 v234, 16, v194
	v_and_b32_e32 v235, 0xffff0000, v194
	v_pk_add_f32 v[230:231], v[230:231], v[236:237] op_sel_hi:[1,0] neg_lo:[0,1] neg_hi:[0,1]
	v_pk_add_f32 v[234:235], v[234:235], v[232:233] neg_lo:[0,1] neg_hi:[0,1]
	v_pk_mul_f32 v[230:231], v[230:231], v[238:239] op_sel_hi:[1,0]
	v_pk_fma_f32 v[232:233], v[162:163], v[234:235], v[232:233]
	v_pk_fma_f32 v[230:231], v[130:131], v[230:231], v[146:147]
	v_pk_fma_f32 v[230:231], v[240:241], v[232:233], v[230:231] op_sel_hi:[0,1,1]
	v_pk_mul_f32 v[64:65], v[64:65], v[230:231]
	v_lshlrev_b32_e32 v230, 16, v179
	v_and_b32_e32 v231, 0xffff0000, v179
	v_lshlrev_b32_e32 v232, 16, v187
	v_and_b32_e32 v233, 0xffff0000, v187
	v_lshlrev_b32_e32 v234, 16, v195
	v_and_b32_e32 v235, 0xffff0000, v195
	v_pk_add_f32 v[230:231], v[230:231], v[236:237] op_sel_hi:[1,0] neg_lo:[0,1] neg_hi:[0,1]
	v_pk_add_f32 v[234:235], v[234:235], v[232:233] neg_lo:[0,1] neg_hi:[0,1]
	v_pk_mul_f32 v[230:231], v[230:231], v[238:239] op_sel_hi:[1,0]
	v_pk_fma_f32 v[232:233], v[164:165], v[234:235], v[232:233]
	v_pk_fma_f32 v[230:231], v[132:133], v[230:231], v[148:149]
	v_pk_fma_f32 v[230:231], v[240:241], v[232:233], v[230:231] op_sel_hi:[0,1,1]
	v_pk_mul_f32 v[66:67], v[66:67], v[230:231]
	v_lshlrev_b32_e32 v230, 16, v180
	v_and_b32_e32 v231, 0xffff0000, v180
	v_lshlrev_b32_e32 v232, 16, v188
	v_and_b32_e32 v233, 0xffff0000, v188
	v_lshlrev_b32_e32 v234, 16, v196
	v_and_b32_e32 v235, 0xffff0000, v196
	v_pk_add_f32 v[230:231], v[230:231], v[236:237] op_sel_hi:[1,0] neg_lo:[0,1] neg_hi:[0,1]
	v_pk_add_f32 v[234:235], v[234:235], v[232:233] neg_lo:[0,1] neg_hi:[0,1]
	v_pk_mul_f32 v[230:231], v[230:231], v[238:239] op_sel_hi:[1,0]
	v_pk_fma_f32 v[232:233], v[166:167], v[234:235], v[232:233]
	v_pk_fma_f32 v[230:231], v[134:135], v[230:231], v[150:151]
	v_pk_fma_f32 v[230:231], v[240:241], v[232:233], v[230:231] op_sel_hi:[0,1,1]
	v_pk_mul_f32 v[68:69], v[68:69], v[230:231]
	v_lshlrev_b32_e32 v230, 16, v181
	v_and_b32_e32 v231, 0xffff0000, v181
	v_lshlrev_b32_e32 v232, 16, v189
	v_and_b32_e32 v233, 0xffff0000, v189
	v_lshlrev_b32_e32 v234, 16, v197
	v_and_b32_e32 v235, 0xffff0000, v197
	v_pk_add_f32 v[230:231], v[230:231], v[236:237] op_sel_hi:[1,0] neg_lo:[0,1] neg_hi:[0,1]
	v_pk_add_f32 v[234:235], v[234:235], v[232:233] neg_lo:[0,1] neg_hi:[0,1]
	v_pk_mul_f32 v[230:231], v[230:231], v[238:239] op_sel_hi:[1,0]
	v_pk_fma_f32 v[232:233], v[168:169], v[234:235], v[232:233]
	v_pk_fma_f32 v[230:231], v[136:137], v[230:231], v[152:153]
	v_pk_fma_f32 v[230:231], v[240:241], v[232:233], v[230:231] op_sel_hi:[0,1,1]
	v_pk_mul_f32 v[70:71], v[70:71], v[230:231]
	v_cvt_pk_bf16_f32 v64, v64, v65
	v_cvt_pk_bf16_f32 v65, v66, v67
	v_cvt_pk_bf16_f32 v66, v68, v69
	v_cvt_pk_bf16_f32 v67, v70, v71
	global_store_dwordx4 v243, v[64:67], s[22:23] offset:0
	v_lshlrev_b32_e32 v230, 16, v182
	v_and_b32_e32 v231, 0xffff0000, v182
	v_lshlrev_b32_e32 v232, 16, v190
	v_and_b32_e32 v233, 0xffff0000, v190
	v_lshlrev_b32_e32 v234, 16, v198
	v_and_b32_e32 v235, 0xffff0000, v198
	v_pk_add_f32 v[230:231], v[230:231], v[236:237] op_sel_hi:[1,0] neg_lo:[0,1] neg_hi:[0,1]
	v_pk_add_f32 v[234:235], v[234:235], v[232:233] neg_lo:[0,1] neg_hi:[0,1]
	v_pk_mul_f32 v[230:231], v[230:231], v[238:239] op_sel_hi:[1,0]
	v_pk_fma_f32 v[232:233], v[170:171], v[234:235], v[232:233]
	v_pk_fma_f32 v[230:231], v[138:139], v[230:231], v[154:155]
	v_pk_fma_f32 v[230:231], v[240:241], v[232:233], v[230:231] op_sel_hi:[0,1,1]
	v_pk_mul_f32 v[72:73], v[72:73], v[230:231]
	v_lshlrev_b32_e32 v230, 16, v183
	v_and_b32_e32 v231, 0xffff0000, v183
; __device__ __forceinline__ float bf2f(u16 h) { return __uint_as_float(((unsigned)h) << 16); }
; template <int EPI> ...
;     ...
;         float o0 = bf2f(Y[(size_t)row * 1024 + 256 + ch0]);
;         float o1 = bf2f(Y[(size_t)row * 1024 + 256 + ch1]);
;         float mean = hsum32(o0 + o1) * (1.0f / 64.0f);
;         float d0 = o0 - mean, d1 = o1 - mean;
;         float var = hsum32(d0 * d0 + d1 * d1) * (1.0f / 64.0f);
;         float rstd = rsqrtf(var + 64e-5f);
;         float pv0 = bf2f(P[(size_t)row * 2816 + 256 + 1536 + ch0]);
;         float pv1 = bf2f(P[(size_t)row * 2816 + 256 + 1536 + ch1]);
;         float pp0 = prevP(p, P, row, 1536 + ch0), pp1 = prevP(p, P, row, 1536 + ch1);
;         float vv0 = pv0 + (pp0 - pv0) * mu0, vv1 = pv1 + (pp1 - pv1) * mu1;
;         float b = bs[((size_t)row * 12 + hh) * 4 + 2];
;         float y0 = (d0 * rstd * gg0 + gb0 + b * vv0) * acc0[i];
;         float y1 = (d1 * rstd * gg1 + gb1 + b * vv1) * acc1[i];
;         Y[(size_t)row * 1024 + 256 + ch0] = f2bf(y0);
;         Y[(size_t)row * 1024 + 256 + ch1] = f2bf(y1);
	v_lshlrev_b32_e32 v232, 16, v191
	v_and_b32_e32 v233, 0xffff0000, v191
	v_lshlrev_b32_e32 v234, 16, v199
	v_and_b32_e32 v235, 0xffff0000, v199
	v_pk_add_f32 v[230:231], v[230:231], v[236:237] op_sel_hi:[1,0] neg_lo:[0,1] neg_hi:[0,1]
	v_pk_add_f32 v[234:235], v[234:235], v[232:233] neg_lo:[0,1] neg_hi:[0,1]
	v_pk_mul_f32 v[230:231], v[230:231], v[238:239] op_sel_hi:[1,0]
	v_pk_fma_f32 v[232:233], v[172:173], v[234:235], v[232:233]
	v_pk_fma_f32 v[230:231], v[140:141], v[230:231], v[156:157]
	v_pk_fma_f32 v[230:231], v[240:241], v[232:233], v[230:231] op_sel_hi:[0,1,1]
	v_pk_mul_f32 v[74:75], v[74:75], v[230:231]
	v_lshlrev_b32_e32 v230, 16, v184
	v_and_b32_e32 v231, 0xffff0000, v184
	v_lshlrev_b32_e32 v232, 16, v192
	v_and_b32_e32 v233, 0xffff0000, v192
	v_lshlrev_b32_e32 v234, 16, v200
	v_and_b32_e32 v235, 0xffff0000, v200
	v_pk_add_f32 v[230:231], v[230:231], v[236:237] op_sel_hi:[1,0] neg_lo:[0,1] neg_hi:[0,1]
	v_pk_add_f32 v[234:235], v[234:235], v[232:233] neg_lo:[0,1] neg_hi:[0,1]
	v_pk_mul_f32 v[230:231], v[230:231], v[238:239] op_sel_hi:[1,0]
	v_pk_fma_f32 v[232:233], v[174:175], v[234:235], v[232:233]
	v_pk_fma_f32 v[230:231], v[142:143], v[230:231], v[158:159]
	v_pk_fma_f32 v[230:231], v[240:241], v[232:233], v[230:231] op_sel_hi:[0,1,1]
	v_pk_mul_f32 v[76:77], v[76:77], v[230:231]
	v_lshlrev_b32_e32 v230, 16, v185
	v_and_b32_e32 v231, 0xffff0000, v185
	v_lshlrev_b32_e32 v232, 16, v193
	v_and_b32_e32 v233, 0xffff0000, v193
	v_lshlrev_b32_e32 v234, 16, v201
	v_and_b32_e32 v235, 0xffff0000, v201
	v_pk_add_f32 v[230:231], v[230:231], v[236:237] op_sel_hi:[1,0] neg_lo:[0,1] neg_hi:[0,1]
	v_pk_add_f32 v[234:235], v[234:235], v[232:233] neg_lo:[0,1] neg_hi:[0,1]
	v_pk_mul_f32 v[230:231], v[230:231], v[238:239] op_sel_hi:[1,0]
	v_pk_fma_f32 v[232:233], v[176:177], v[234:235], v[232:233]
	v_pk_fma_f32 v[230:231], v[144:145], v[230:231], v[160:161]
	v_pk_fma_f32 v[230:231], v[240:241], v[232:233], v[230:231] op_sel_hi:[0,1,1]
	v_pk_mul_f32 v[78:79], v[78:79], v[230:231]
	v_cvt_pk_bf16_f32 v72, v72, v73
	v_cvt_pk_bf16_f32 v73, v74, v75
	v_cvt_pk_bf16_f32 v74, v76, v77
	v_cvt_pk_bf16_f32 v75, v78, v79
	global_store_dwordx4 v243, v[72:75], s[22:23] offset:64
	v_add_u32_e32 v246, 0x0, v237
	v_add_u32_e32 v247, 0x0, v239
	v_subrev_u32_e32 v230, 0x1600, v247
	global_load_dwordx4 v[178:181], v246, s[22:23] offset:128
	global_load_dwordx4 v[182:185], v246, s[22:23] offset:192
	global_load_dwordx4 v[186:189], v247, s[96:97] offset:128
	global_load_dwordx4 v[190:193], v247, s[96:97] offset:192
	global_load_dwordx4 v[194:197], v230, s[96:97] offset:128
	global_load_dwordx4 v[198:201], v230, s[96:97] offset:192
	v_add_u32_e32 v246, 0x0, v241
	s_nop 0
	global_load_dword v240, v246, s[96:97] offset:16
	s_waitcnt vmcnt(9)
	v_lshlrev_b32_e32 v232, 16, v202
	v_and_b32_e32 v233, 0xffff0000, v202
	v_lshlrev_b32_e32 v230, 16, v203
	v_and_b32_e32 v231, 0xffff0000, v203
	v_pk_add_f32 v[232:233], v[232:233], v[230:231]
	v_lshlrev_b32_e32 v230, 16, v204
	v_and_b32_e32 v231, 0xffff0000, v204
	v_pk_add_f32 v[232:233], v[232:233], v[230:231]
	v_lshlrev_b32_e32 v230, 16, v205
	v_and_b32_e32 v231, 0xffff0000, v205
	v_pk_add_f32 v[232:233], v[232:233], v[230:231]
	v_lshlrev_b32_e32 v230, 16, v206
	v_and_b32_e32 v231, 0xffff0000, v206
	v_pk_add_f32 v[232:233], v[232:233], v[230:231]
	v_lshlrev_b32_e32 v230, 16, v207
	v_and_b32_e32 v231, 0xffff0000, v207
	v_pk_add_f32 v[232:233], v[232:233], v[230:231]
	v_lshlrev_b32_e32 v230, 16, v208
	v_and_b32_e32 v231, 0xffff0000, v208
	v_pk_add_f32 v[232:233], v[232:233], v[230:231]
	v_lshlrev_b32_e32 v230, 16, v209
	v_and_b32_e32 v231, 0xffff0000, v209
	v_pk_add_f32 v[232:233], v[232:233], v[230:231]
	v_add_f32_e32 v232, v232, v233
	v_mov_b32_e32 v230, v232
	s_nop 1
	v_permlane16_swap_b32_e32 v230, v232
	v_add_f32_e32 v232, v232, v230
	v_mov_b32_e32 v230, v232
	s_nop 1
	v_permlane32_swap_b32_e32 v230, v232
	v_add_f32_e32 v232, v232, v230
	v_mul_f32_e32 v236, 0x3c800000, v232
	v_lshlrev_b32_e32 v230, 16, v202
	v_and_b32_e32 v231, 0xffff0000, v202
	v_pk_add_f32 v[230:231], v[230:231], v[236:237] op_sel_hi:[1,0] neg_lo:[0,1] neg_hi:[0,1]
	v_pk_mul_f32 v[232:233], v[230:231], v[230:231]
	v_lshlrev_b32_e32 v230, 16, v203
	v_and_b32_e32 v231, 0xffff0000, v203
	v_pk_add_f32 v[230:231], v[230:231], v[236:237] op_sel_hi:[1,0] neg_lo:[0,1] neg_hi:[0,1]
	v_pk_fma_f32 v[232:233], v[230:231], v[230:231], v[232:233]
	v_lshlrev_b32_e32 v230, 16, v204
	v_and_b32_e32 v231, 0xffff0000, v204
	v_pk_add_f32 v[230:231], v[230:231], v[236:237] op_sel_hi:[1,0] neg_lo:[0,1] neg_hi:[0,1]
	v_pk_fma_f32 v[232:233], v[230:231], v[230:231], v[232:233]
	v_lshlrev_b32_e32 v230, 16, v205
	v_and_b32_e32 v231, 0xffff0000, v205
	v_pk_add_f32 v[230:231], v[230:231], v[236:237] op_sel_hi:[1,0] neg_lo:[0,1] neg_hi:[0,1]
	v_pk_fma_f32 v[232:233], v[230:231], v[230:231], v[232:233]
	v_lshlrev_b32_e32 v230, 16, v206
	v_and_b32_e32 v231, 0xffff0000, v206
	v_pk_add_f32 v[230:231], v[230:231], v[236:237] op_sel_hi:[1,0] neg_lo:[0,1] neg_hi:[0,1]
	v_pk_fma_f32 v[232:233], v[230:231], v[230:231], v[232:233]
	v_lshlrev_b32_e32 v230, 16, v207
	v_and_b32_e32 v231, 0xffff0000, v207
	v_pk_add_f32 v[230:231], v[230:231], v[236:237] op_sel_hi:[1,0] neg_lo:[0,1] neg_hi:[0,1]
	v_pk_fma_f32 v[232:233], v[230:231], v[230:231], v[232:233]
	v_lshlrev_b32_e32 v230, 16, v208
	v_and_b32_e32 v231, 0xffff0000, v208
	v_pk_add_f32 v[230:231], v[230:231], v[236:237] op_sel_hi:[1,0] neg_lo:[0,1] neg_hi:[0,1]
	v_pk_fma_f32 v[232:233], v[230:231], v[230:231], v[232:233]
	v_lshlrev_b32_e32 v230, 16, v209
	v_and_b32_e32 v231, 0xffff0000, v209
	v_pk_add_f32 v[230:231], v[230:231], v[236:237] op_sel_hi:[1,0] neg_lo:[0,1] neg_hi:[0,1]
; __device__ __forceinline__ float bf2f(u16 h) { return __uint_as_float(((unsigned)h) << 16); }
; template <int EPI> ...
;     ...
;         float mean = hsum32(o0 + o1) * (1.0f / 64.0f);
;         float d0 = o0 - mean, d1 = o1 - mean;
;         float var = hsum32(d0 * d0 + d1 * d1) * (1.0f / 64.0f);
;         float rstd = rsqrtf(var + 64e-5f);
;         float pv0 = bf2f(P[(size_t)row * 2816 + 256 + 1536 + ch0]);
;         float pv1 = bf2f(P[(size_t)row * 2816 + 256 + 1536 + ch1]);
;         float pp0 = prevP(p, P, row, 1536 + ch0), pp1 = prevP(p, P, row, 1536 + ch1);
;         float vv0 = pv0 + (pp0 - pv0) * mu0, vv1 = pv1 + (pp1 - pv1) * mu1;
;         float b = bs[((size_t)row * 12 + hh) * 4 + 2];
;         float y0 = (d0 * rstd * gg0 + gb0 + b * vv0) * acc0[i];
;         float y1 = (d1 * rstd * gg1 + gb1 + b * vv1) * acc1[i];
;         Y[(size_t)row * 1024 + 256 + ch0] = f2bf(y0);
;         Y[(size_t)row * 1024 + 256 + ch1] = f2bf(y1);
	v_pk_fma_f32 v[232:233], v[230:231], v[230:231], v[232:233]
	v_add_f32_e32 v232, v232, v233
	v_mov_b32_e32 v230, v232
	s_nop 1
	v_permlane16_swap_b32_e32 v230, v232
	v_add_f32_e32 v232, v232, v230
	v_mov_b32_e32 v230, v232
	s_nop 1
	v_permlane32_swap_b32_e32 v230, v232
	v_add_f32_e32 v232, v232, v230
	v_mov_b32_e32 v230, 0x3a27c5ac
	v_fmamk_f32 v232, v232, 0x3c800000, v230
	v_rsq_f32_e32 v238, v232
	v_add_u32_e32 v243, 0x18000, v237
	v_lshlrev_b32_e32 v230, 16, v202
	v_and_b32_e32 v231, 0xffff0000, v202
	v_lshlrev_b32_e32 v232, 16, v210
	v_and_b32_e32 v233, 0xffff0000, v210
	v_lshlrev_b32_e32 v234, 16, v218
	v_and_b32_e32 v235, 0xffff0000, v218
	v_pk_add_f32 v[230:231], v[230:231], v[236:237] op_sel_hi:[1,0] neg_lo:[0,1] neg_hi:[0,1]
	v_pk_add_f32 v[234:235], v[234:235], v[232:233] neg_lo:[0,1] neg_hi:[0,1]
	v_pk_mul_f32 v[230:231], v[230:231], v[238:239] op_sel_hi:[1,0]
	v_pk_fma_f32 v[232:233], v[162:163], v[234:235], v[232:233]
	v_pk_fma_f32 v[230:231], v[130:131], v[230:231], v[146:147]
	v_pk_fma_f32 v[230:231], v[244:245], v[232:233], v[230:231] op_sel_hi:[0,1,1]
	v_pk_mul_f32 v[96:97], v[96:97], v[230:231]
	v_lshlrev_b32_e32 v230, 16, v203
	v_and_b32_e32 v231, 0xffff0000, v203
	v_lshlrev_b32_e32 v232, 16, v211
	v_and_b32_e32 v233, 0xffff0000, v211
	v_lshlrev_b32_e32 v234, 16, v219
	v_and_b32_e32 v235, 0xffff0000, v219
	v_pk_add_f32 v[230:231], v[230:231], v[236:237] op_sel_hi:[1,0] neg_lo:[0,1] neg_hi:[0,1]
	v_pk_add_f32 v[234:235], v[234:235], v[232:233] neg_lo:[0,1] neg_hi:[0,1]
	v_pk_mul_f32 v[230:231], v[230:231], v[238:239] op_sel_hi:[1,0]
	v_pk_fma_f32 v[232:233], v[164:165], v[234:235], v[232:233]
	v_pk_fma_f32 v[230:231], v[132:133], v[230:231], v[148:149]
	v_pk_fma_f32 v[230:231], v[244:245], v[232:233], v[230:231] op_sel_hi:[0,1,1]
	v_pk_mul_f32 v[98:99], v[98:99], v[230:231]
	v_lshlrev_b32_e32 v230, 16, v204
	v_and_b32_e32 v231, 0xffff0000, v204
	v_lshlrev_b32_e32 v232, 16, v212
	v_and_b32_e32 v233, 0xffff0000, v212
	v_lshlrev_b32_e32 v234, 16, v220
	v_and_b32_e32 v235, 0xffff0000, v220
	v_pk_add_f32 v[230:231], v[230:231], v[236:237] op_sel_hi:[1,0] neg_lo:[0,1] neg_hi:[0,1]
	v_pk_add_f32 v[234:235], v[234:235], v[232:233] neg_lo:[0,1] neg_hi:[0,1]
	v_pk_mul_f32 v[230:231], v[230:231], v[238:239] op_sel_hi:[1,0]
	v_pk_fma_f32 v[232:233], v[166:167], v[234:235], v[232:233]
	v_pk_fma_f32 v[230:231], v[134:135], v[230:231], v[150:151]
	v_pk_fma_f32 v[230:231], v[244:245], v[232:233], v[230:231] op_sel_hi:[0,1,1]
	v_pk_mul_f32 v[100:101], v[100:101], v[230:231]
	v_lshlrev_b32_e32 v230, 16, v205
	v_and_b32_e32 v231, 0xffff0000, v205
	v_lshlrev_b32_e32 v232, 16, v213
	v_and_b32_e32 v233, 0xffff0000, v213
	v_lshlrev_b32_e32 v234, 16, v221
	v_and_b32_e32 v235, 0xffff0000, v221
	v_pk_add_f32 v[230:231], v[230:231], v[236:237] op_sel_hi:[1,0] neg_lo:[0,1] neg_hi:[0,1]
	v_pk_add_f32 v[234:235], v[234:235], v[232:233] neg_lo:[0,1] neg_hi:[0,1]
	v_pk_mul_f32 v[230:231], v[230:231], v[238:239] op_sel_hi:[1,0]
	v_pk_fma_f32 v[232:233], v[168:169], v[234:235], v[232:233]
	v_pk_fma_f32 v[230:231], v[136:137], v[230:231], v[152:153]
	v_pk_fma_f32 v[230:231], v[244:245], v[232:233], v[230:231] op_sel_hi:[0,1,1]
	v_pk_mul_f32 v[102:103], v[102:103], v[230:231]
	v_cvt_pk_bf16_f32 v96, v96, v97
	v_cvt_pk_bf16_f32 v97, v98, v99
	v_cvt_pk_bf16_f32 v98, v100, v101
	v_cvt_pk_bf16_f32 v99, v102, v103
	global_store_dwordx4 v243, v[96:99], s[22:23] offset:0
	v_lshlrev_b32_e32 v230, 16, v206
	v_and_b32_e32 v231, 0xffff0000, v206
	v_lshlrev_b32_e32 v232, 16, v214
	v_and_b32_e32 v233, 0xffff0000, v214
	v_lshlrev_b32_e32 v234, 16, v222
	v_and_b32_e32 v235, 0xffff0000, v222
	v_pk_add_f32 v[230:231], v[230:231], v[236:237] op_sel_hi:[1,0] neg_lo:[0,1] neg_hi:[0,1]
	v_pk_add_f32 v[234:235], v[234:235], v[232:233] neg_lo:[0,1] neg_hi:[0,1]
	v_pk_mul_f32 v[230:231], v[230:231], v[238:239] op_sel_hi:[1,0]
	v_pk_fma_f32 v[232:233], v[170:171], v[234:235], v[232:233]
	v_pk_fma_f32 v[230:231], v[138:139], v[230:231], v[154:155]
	v_pk_fma_f32 v[230:231], v[244:245], v[232:233], v[230:231] op_sel_hi:[0,1,1]
	v_pk_mul_f32 v[104:105], v[104:105], v[230:231]
	v_lshlrev_b32_e32 v230, 16, v207
	v_and_b32_e32 v231, 0xffff0000, v207
	v_lshlrev_b32_e32 v232, 16, v215
	v_and_b32_e32 v233, 0xffff0000, v215
	v_lshlrev_b32_e32 v234, 16, v223
	v_and_b32_e32 v235, 0xffff0000, v223
	v_pk_add_f32 v[230:231], v[230:231], v[236:237] op_sel_hi:[1,0] neg_lo:[0,1] neg_hi:[0,1]
	v_pk_add_f32 v[234:235], v[234:235], v[232:233] neg_lo:[0,1] neg_hi:[0,1]
	v_pk_mul_f32 v[230:231], v[230:231], v[238:239] op_sel_hi:[1,0]
	v_pk_fma_f32 v[232:233], v[172:173], v[234:235], v[232:233]
	v_pk_fma_f32 v[230:231], v[140:141], v[230:231], v[156:157]
	v_pk_fma_f32 v[230:231], v[244:245], v[232:233], v[230:231] op_sel_hi:[0,1,1]
	v_pk_mul_f32 v[106:107], v[106:107], v[230:231]
	v_lshlrev_b32_e32 v230, 16, v208
	v_and_b32_e32 v231, 0xffff0000, v208
	v_lshlrev_b32_e32 v232, 16, v216
	v_and_b32_e32 v233, 0xffff0000, v216
	v_lshlrev_b32_e32 v234, 16, v224
	v_and_b32_e32 v235, 0xffff0000, v224
	v_pk_add_f32 v[230:231], v[230:231], v[236:237] op_sel_hi:[1,0] neg_lo:[0,1] neg_hi:[0,1]
	v_pk_add_f32 v[234:235], v[234:235], v[232:233] neg_lo:[0,1] neg_hi:[0,1]
	v_pk_mul_f32 v[230:231], v[230:231], v[238:239] op_sel_hi:[1,0]
	v_pk_fma_f32 v[232:233], v[174:175], v[234:235], v[232:233]
	v_pk_fma_f32 v[230:231], v[142:143], v[230:231], v[158:159]
	v_pk_fma_f32 v[230:231], v[244:245], v[232:233], v[230:231] op_sel_hi:[0,1,1]
	v_pk_mul_f32 v[108:109], v[108:109], v[230:231]
	v_lshlrev_b32_e32 v230, 16, v209
	v_and_b32_e32 v231, 0xffff0000, v209
	v_lshlrev_b32_e32 v232, 16, v217
	v_and_b32_e32 v233, 0xffff0000, v217
; __device__ __forceinline__ float bf2f(u16 h) { return __uint_as_float(((unsigned)h) << 16); }
; template <int EPI> ...
;     ...
;       const float gg0 = p.in[20][ch0], gg1 = p.in[20][ch1];
;       const float gb0 = p.in[21][ch0], gb1 = p.in[21][ch1];
;       const float mu0 = p.in[11][1536 + ch0], mu1 = p.in[11][1536 + ch1];
; #pragma unroll 16
;       for (int i = 0; i < 16; i++) {
;         const int rl = rbase + (i & 3) + 8 * (i >> 2);
;         const int row = m0 + rl;
;         float o0 = bf2f(Y[(size_t)row * 1024 + 256 + ch0]);
;         float o1 = bf2f(Y[(size_t)row * 1024 + 256 + ch1]);
;         float mean = hsum32(o0 + o1) * (1.0f / 64.0f);
;         float d0 = o0 - mean, d1 = o1 - mean;
;         float var = hsum32(d0 * d0 + d1 * d1) * (1.0f / 64.0f);
;         float rstd = rsqrtf(var + 64e-5f);
;         float pv0 = bf2f(P[(size_t)row * 2816 + 256 + 1536 + ch0]);
;         float pv1 = bf2f(P[(size_t)row * 2816 + 256 + 1536 + ch1]);
;         float pp0 = prevP(p, P, row, 1536 + ch0), pp1 = prevP(p, P, row, 1536 + ch1);
;         float vv0 = pv0 + (pp0 - pv0) * mu0, vv1 = pv1 + (pp1 - pv1) * mu1;
;         float b = bs[((size_t)row * 12 + hh) * 4 + 2];
;         float y0 = (d0 * rstd * gg0 + gb0 + b * vv0) * acc0[i];
;         float y1 = (d1 * rstd * gg1 + gb1 + b * vv1) * acc1[i];
;         Y[(size_t)row * 1024 + 256 + ch0] = f2bf(y0);
;         Y[(size_t)row * 1024 + 256 + ch1] = f2bf(y1);
	v_lshlrev_b32_e32 v234, 16, v225
	v_and_b32_e32 v235, 0xffff0000, v225
	v_pk_add_f32 v[230:231], v[230:231], v[236:237] op_sel_hi:[1,0] neg_lo:[0,1] neg_hi:[0,1]
	v_pk_add_f32 v[234:235], v[234:235], v[232:233] neg_lo:[0,1] neg_hi:[0,1]
	v_pk_mul_f32 v[230:231], v[230:231], v[238:239] op_sel_hi:[1,0]
	v_pk_fma_f32 v[232:233], v[176:177], v[234:235], v[232:233]
	v_pk_fma_f32 v[230:231], v[144:145], v[230:231], v[160:161]
	v_pk_fma_f32 v[230:231], v[244:245], v[232:233], v[230:231] op_sel_hi:[0,1,1]
	v_pk_mul_f32 v[110:111], v[110:111], v[230:231]
	v_cvt_pk_bf16_f32 v104, v104, v105
	v_cvt_pk_bf16_f32 v105, v106, v107
	v_cvt_pk_bf16_f32 v106, v108, v109
	v_cvt_pk_bf16_f32 v107, v110, v111
	global_store_dwordx4 v243, v[104:107], s[22:23] offset:64
	global_load_dwordx4 v[130:133], v245, s[2:3] offset:256
	global_load_dwordx4 v[134:137], v245, s[2:3] offset:272
	global_load_dwordx4 v[138:141], v245, s[2:3] offset:384
	global_load_dwordx4 v[142:145], v245, s[2:3] offset:400
	global_load_dwordx4 v[146:149], v245, s[16:17] offset:256
	global_load_dwordx4 v[150:153], v245, s[16:17] offset:272
	global_load_dwordx4 v[154:157], v245, s[16:17] offset:384
	global_load_dwordx4 v[158:161], v245, s[16:17] offset:400
	global_load_dwordx4 v[162:165], v245, s[0:1] offset:256
	global_load_dwordx4 v[166:169], v245, s[0:1] offset:272
	global_load_dwordx4 v[170:173], v245, s[0:1] offset:384
	global_load_dwordx4 v[174:177], v245, s[0:1] offset:400
	v_add_u32_e32 v246, 0x8000, v237
	v_add_u32_e32 v247, 0x16000, v239
	v_subrev_u32_e32 v230, 0x1600, v247
	global_load_dwordx4 v[202:205], v246, s[22:23] offset:128
	global_load_dwordx4 v[206:209], v246, s[22:23] offset:192
	global_load_dwordx4 v[210:213], v247, s[96:97] offset:128
	global_load_dwordx4 v[214:217], v247, s[96:97] offset:192
	global_load_dwordx4 v[218:221], v230, s[96:97] offset:128
	global_load_dwordx4 v[222:225], v230, s[96:97] offset:192
	v_add_u32_e32 v246, 0xc00, v241
	s_nop 0
	global_load_dword v244, v246, s[96:97] offset:16
	s_waitcnt vmcnt(7)
	s_and_b32 s18, s6, 7
	s_or_b32 s18, s18, s4
	s_cmp_lg_u32 s18, 0
	s_cbranch_scc1 .Lpo_nostart_p4
	v_cmp_eq_u32_e32 vcc, 0, v248
	s_nop 1
	v_cndmask_b32_e64 v194, v194, 0, vcc
	v_cndmask_b32_e64 v195, v195, 0, vcc
	v_cndmask_b32_e64 v196, v196, 0, vcc
	v_cndmask_b32_e64 v197, v197, 0, vcc
	v_cndmask_b32_e64 v198, v198, 0, vcc
	v_cndmask_b32_e64 v199, v199, 0, vcc
	v_cndmask_b32_e64 v200, v200, 0, vcc
	v_cndmask_b32_e64 v201, v201, 0, vcc
.Lpo_nostart_p4:
	v_lshlrev_b32_e32 v232, 16, v178
	v_and_b32_e32 v233, 0xffff0000, v178
	v_lshlrev_b32_e32 v230, 16, v179
	v_and_b32_e32 v231, 0xffff0000, v179
	v_pk_add_f32 v[232:233], v[232:233], v[230:231]
	v_lshlrev_b32_e32 v230, 16, v180
	v_and_b32_e32 v231, 0xffff0000, v180
	v_pk_add_f32 v[232:233], v[232:233], v[230:231]
	v_lshlrev_b32_e32 v230, 16, v181
	v_and_b32_e32 v231, 0xffff0000, v181
	v_pk_add_f32 v[232:233], v[232:233], v[230:231]
	v_lshlrev_b32_e32 v230, 16, v182
	v_and_b32_e32 v231, 0xffff0000, v182
	v_pk_add_f32 v[232:233], v[232:233], v[230:231]
	v_lshlrev_b32_e32 v230, 16, v183
	v_and_b32_e32 v231, 0xffff0000, v183
	v_pk_add_f32 v[232:233], v[232:233], v[230:231]
	v_lshlrev_b32_e32 v230, 16, v184
	v_and_b32_e32 v231, 0xffff0000, v184
	v_pk_add_f32 v[232:233], v[232:233], v[230:231]
	v_lshlrev_b32_e32 v230, 16, v185
	v_and_b32_e32 v231, 0xffff0000, v185
	v_pk_add_f32 v[232:233], v[232:233], v[230:231]
	v_add_f32_e32 v232, v232, v233
	v_mov_b32_e32 v230, v232
	s_nop 1
	v_permlane16_swap_b32_e32 v230, v232
	v_add_f32_e32 v232, v232, v230
	v_mov_b32_e32 v230, v232
	s_nop 1
	v_permlane32_swap_b32_e32 v230, v232
	v_add_f32_e32 v232, v232, v230
	v_mul_f32_e32 v236, 0x3c800000, v232
	v_lshlrev_b32_e32 v230, 16, v178
	v_and_b32_e32 v231, 0xffff0000, v178
	v_pk_add_f32 v[230:231], v[230:231], v[236:237] op_sel_hi:[1,0] neg_lo:[0,1] neg_hi:[0,1]
	v_pk_mul_f32 v[232:233], v[230:231], v[230:231]
	v_lshlrev_b32_e32 v230, 16, v179
	v_and_b32_e32 v231, 0xffff0000, v179
	v_pk_add_f32 v[230:231], v[230:231], v[236:237] op_sel_hi:[1,0] neg_lo:[0,1] neg_hi:[0,1]
	v_pk_fma_f32 v[232:233], v[230:231], v[230:231], v[232:233]
	v_lshlrev_b32_e32 v230, 16, v180
	v_and_b32_e32 v231, 0xffff0000, v180
	v_pk_add_f32 v[230:231], v[230:231], v[236:237] op_sel_hi:[1,0] neg_lo:[0,1] neg_hi:[0,1]
	v_pk_fma_f32 v[232:233], v[230:231], v[230:231], v[232:233]
	v_lshlrev_b32_e32 v230, 16, v181
	v_and_b32_e32 v231, 0xffff0000, v181
	v_pk_add_f32 v[230:231], v[230:231], v[236:237] op_sel_hi:[1,0] neg_lo:[0,1] neg_hi:[0,1]
	v_pk_fma_f32 v[232:233], v[230:231], v[230:231], v[232:233]
	v_lshlrev_b32_e32 v230, 16, v182
	v_and_b32_e32 v231, 0xffff0000, v182
	v_pk_add_f32 v[230:231], v[230:231], v[236:237] op_sel_hi:[1,0] neg_lo:[0,1] neg_hi:[0,1]
	v_pk_fma_f32 v[232:233], v[230:231], v[230:231], v[232:233]
	v_lshlrev_b32_e32 v230, 16, v183
	v_and_b32_e32 v231, 0xffff0000, v183
	v_pk_add_f32 v[230:231], v[230:231], v[236:237] op_sel_hi:[1,0] neg_lo:[0,1] neg_hi:[0,1]
	v_pk_fma_f32 v[232:233], v[230:231], v[230:231], v[232:233]
	v_lshlrev_b32_e32 v230, 16, v184
	v_and_b32_e32 v231, 0xffff0000, v184
	v_pk_add_f32 v[230:231], v[230:231], v[236:237] op_sel_hi:[1,0] neg_lo:[0,1] neg_hi:[0,1]
	v_pk_fma_f32 v[232:233], v[230:231], v[230:231], v[232:233]
	v_lshlrev_b32_e32 v230, 16, v185
	v_and_b32_e32 v231, 0xffff0000, v185
	v_pk_add_f32 v[230:231], v[230:231], v[236:237] op_sel_hi:[1,0] neg_lo:[0,1] neg_hi:[0,1]
	v_pk_fma_f32 v[232:233], v[230:231], v[230:231], v[232:233]
	v_add_f32_e32 v232, v232, v233
	v_mov_b32_e32 v230, v232
	s_nop 1
	v_permlane16_swap_b32_e32 v230, v232
	v_add_f32_e32 v232, v232, v230
	v_mov_b32_e32 v230, v232
	s_nop 1
; __device__ __forceinline__ float bf2f(u16 h) { return __uint_as_float(((unsigned)h) << 16); }
; template <int EPI> ...
;     ...
;         float mean = hsum32(o0 + o1) * (1.0f / 64.0f);
;         float d0 = o0 - mean, d1 = o1 - mean;
;         float var = hsum32(d0 * d0 + d1 * d1) * (1.0f / 64.0f);
;         float rstd = rsqrtf(var + 64e-5f);
;         float pv0 = bf2f(P[(size_t)row * 2816 + 256 + 1536 + ch0]);
;         float pv1 = bf2f(P[(size_t)row * 2816 + 256 + 1536 + ch1]);
;         float pp0 = prevP(p, P, row, 1536 + ch0), pp1 = prevP(p, P, row, 1536 + ch1);
;         float vv0 = pv0 + (pp0 - pv0) * mu0, vv1 = pv1 + (pp1 - pv1) * mu1;
;         float b = bs[((size_t)row * 12 + hh) * 4 + 2];
;         float y0 = (d0 * rstd * gg0 + gb0 + b * vv0) * acc0[i];
;         float y1 = (d1 * rstd * gg1 + gb1 + b * vv1) * acc1[i];
;         Y[(size_t)row * 1024 + 256 + ch0] = f2bf(y0);
;         Y[(size_t)row * 1024 + 256 + ch1] = f2bf(y1);
	v_permlane32_swap_b32_e32 v230, v232
	v_add_f32_e32 v232, v232, v230
	v_mov_b32_e32 v230, 0x3a27c5ac
	v_fmamk_f32 v232, v232, 0x3c800000, v230
	v_rsq_f32_e32 v238, v232
	v_add_u32_e32 v243, 0x0, v237
	v_lshlrev_b32_e32 v230, 16, v178
	v_and_b32_e32 v231, 0xffff0000, v178
	v_lshlrev_b32_e32 v232, 16, v186
	v_and_b32_e32 v233, 0xffff0000, v186
	v_lshlrev_b32_e32 v234, 16, v194
	v_and_b32_e32 v235, 0xffff0000, v194
	v_pk_add_f32 v[230:231], v[230:231], v[236:237] op_sel_hi:[1,0] neg_lo:[0,1] neg_hi:[0,1]
	v_pk_add_f32 v[234:235], v[234:235], v[232:233] neg_lo:[0,1] neg_hi:[0,1]
	v_pk_mul_f32 v[230:231], v[230:231], v[238:239] op_sel_hi:[1,0]
	v_pk_fma_f32 v[232:233], v[162:163], v[234:235], v[232:233]
	v_pk_fma_f32 v[230:231], v[130:131], v[230:231], v[146:147]
	v_pk_fma_f32 v[230:231], v[240:241], v[232:233], v[230:231] op_sel_hi:[0,1,1]
	v_pk_mul_f32 v[16:17], v[16:17], v[230:231]
	v_lshlrev_b32_e32 v230, 16, v179
	v_and_b32_e32 v231, 0xffff0000, v179
	v_lshlrev_b32_e32 v232, 16, v187
	v_and_b32_e32 v233, 0xffff0000, v187
	v_lshlrev_b32_e32 v234, 16, v195
	v_and_b32_e32 v235, 0xffff0000, v195
	v_pk_add_f32 v[230:231], v[230:231], v[236:237] op_sel_hi:[1,0] neg_lo:[0,1] neg_hi:[0,1]
	v_pk_add_f32 v[234:235], v[234:235], v[232:233] neg_lo:[0,1] neg_hi:[0,1]
	v_pk_mul_f32 v[230:231], v[230:231], v[238:239] op_sel_hi:[1,0]
	v_pk_fma_f32 v[232:233], v[164:165], v[234:235], v[232:233]
	v_pk_fma_f32 v[230:231], v[132:133], v[230:231], v[148:149]
	v_pk_fma_f32 v[230:231], v[240:241], v[232:233], v[230:231] op_sel_hi:[0,1,1]
	v_pk_mul_f32 v[18:19], v[18:19], v[230:231]
	v_lshlrev_b32_e32 v230, 16, v180
	v_and_b32_e32 v231, 0xffff0000, v180
	v_lshlrev_b32_e32 v232, 16, v188
	v_and_b32_e32 v233, 0xffff0000, v188
	v_lshlrev_b32_e32 v234, 16, v196
	v_and_b32_e32 v235, 0xffff0000, v196
	v_pk_add_f32 v[230:231], v[230:231], v[236:237] op_sel_hi:[1,0] neg_lo:[0,1] neg_hi:[0,1]
	v_pk_add_f32 v[234:235], v[234:235], v[232:233] neg_lo:[0,1] neg_hi:[0,1]
	v_pk_mul_f32 v[230:231], v[230:231], v[238:239] op_sel_hi:[1,0]
	v_pk_fma_f32 v[232:233], v[166:167], v[234:235], v[232:233]
	v_pk_fma_f32 v[230:231], v[134:135], v[230:231], v[150:151]
	v_pk_fma_f32 v[230:231], v[240:241], v[232:233], v[230:231] op_sel_hi:[0,1,1]
	v_pk_mul_f32 v[20:21], v[20:21], v[230:231]
	v_lshlrev_b32_e32 v230, 16, v181
	v_and_b32_e32 v231, 0xffff0000, v181
	v_lshlrev_b32_e32 v232, 16, v189
	v_and_b32_e32 v233, 0xffff0000, v189
	v_lshlrev_b32_e32 v234, 16, v197
	v_and_b32_e32 v235, 0xffff0000, v197
	v_pk_add_f32 v[230:231], v[230:231], v[236:237] op_sel_hi:[1,0] neg_lo:[0,1] neg_hi:[0,1]
	v_pk_add_f32 v[234:235], v[234:235], v[232:233] neg_lo:[0,1] neg_hi:[0,1]
	v_pk_mul_f32 v[230:231], v[230:231], v[238:239] op_sel_hi:[1,0]
	v_pk_fma_f32 v[232:233], v[168:169], v[234:235], v[232:233]
	v_pk_fma_f32 v[230:231], v[136:137], v[230:231], v[152:153]
	v_pk_fma_f32 v[230:231], v[240:241], v[232:233], v[230:231] op_sel_hi:[0,1,1]
	v_pk_mul_f32 v[22:23], v[22:23], v[230:231]
	v_cvt_pk_bf16_f32 v16, v16, v17
	v_cvt_pk_bf16_f32 v17, v18, v19
	v_cvt_pk_bf16_f32 v18, v20, v21
	v_cvt_pk_bf16_f32 v19, v22, v23
	global_store_dwordx4 v243, v[16:19], s[22:23] offset:128
	v_lshlrev_b32_e32 v230, 16, v182
	v_and_b32_e32 v231, 0xffff0000, v182
	v_lshlrev_b32_e32 v232, 16, v190
	v_and_b32_e32 v233, 0xffff0000, v190
	v_lshlrev_b32_e32 v234, 16, v198
	v_and_b32_e32 v235, 0xffff0000, v198
	v_pk_add_f32 v[230:231], v[230:231], v[236:237] op_sel_hi:[1,0] neg_lo:[0,1] neg_hi:[0,1]
	v_pk_add_f32 v[234:235], v[234:235], v[232:233] neg_lo:[0,1] neg_hi:[0,1]
	v_pk_mul_f32 v[230:231], v[230:231], v[238:239] op_sel_hi:[1,0]
	v_pk_fma_f32 v[232:233], v[170:171], v[234:235], v[232:233]
	v_pk_fma_f32 v[230:231], v[138:139], v[230:231], v[154:155]
	v_pk_fma_f32 v[230:231], v[240:241], v[232:233], v[230:231] op_sel_hi:[0,1,1]
	v_pk_mul_f32 v[24:25], v[24:25], v[230:231]
	v_lshlrev_b32_e32 v230, 16, v183
	v_and_b32_e32 v231, 0xffff0000, v183
	v_lshlrev_b32_e32 v232, 16, v191
	v_and_b32_e32 v233, 0xffff0000, v191
	v_lshlrev_b32_e32 v234, 16, v199
	v_and_b32_e32 v235, 0xffff0000, v199
	v_pk_add_f32 v[230:231], v[230:231], v[236:237] op_sel_hi:[1,0] neg_lo:[0,1] neg_hi:[0,1]
	v_pk_add_f32 v[234:235], v[234:235], v[232:233] neg_lo:[0,1] neg_hi:[0,1]
	v_pk_mul_f32 v[230:231], v[230:231], v[238:239] op_sel_hi:[1,0]
	v_pk_fma_f32 v[232:233], v[172:173], v[234:235], v[232:233]
	v_pk_fma_f32 v[230:231], v[140:141], v[230:231], v[156:157]
	v_pk_fma_f32 v[230:231], v[240:241], v[232:233], v[230:231] op_sel_hi:[0,1,1]
	v_pk_mul_f32 v[26:27], v[26:27], v[230:231]
	v_lshlrev_b32_e32 v230, 16, v184
	v_and_b32_e32 v231, 0xffff0000, v184
	v_lshlrev_b32_e32 v232, 16, v192
	v_and_b32_e32 v233, 0xffff0000, v192
	v_lshlrev_b32_e32 v234, 16, v200
	v_and_b32_e32 v235, 0xffff0000, v200
	v_pk_add_f32 v[230:231], v[230:231], v[236:237] op_sel_hi:[1,0] neg_lo:[0,1] neg_hi:[0,1]
	v_pk_add_f32 v[234:235], v[234:235], v[232:233] neg_lo:[0,1] neg_hi:[0,1]
	v_pk_mul_f32 v[230:231], v[230:231], v[238:239] op_sel_hi:[1,0]
	v_pk_fma_f32 v[232:233], v[174:175], v[234:235], v[232:233]
	v_pk_fma_f32 v[230:231], v[142:143], v[230:231], v[158:159]
	v_pk_fma_f32 v[230:231], v[240:241], v[232:233], v[230:231] op_sel_hi:[0,1,1]
	v_pk_mul_f32 v[28:29], v[28:29], v[230:231]
	v_lshlrev_b32_e32 v230, 16, v185
	v_and_b32_e32 v231, 0xffff0000, v185
	v_lshlrev_b32_e32 v232, 16, v193
	v_and_b32_e32 v233, 0xffff0000, v193
	v_lshlrev_b32_e32 v234, 16, v201
	v_and_b32_e32 v235, 0xffff0000, v201
	v_pk_add_f32 v[230:231], v[230:231], v[236:237] op_sel_hi:[1,0] neg_lo:[0,1] neg_hi:[0,1]
	v_pk_add_f32 v[234:235], v[234:235], v[232:233] neg_lo:[0,1] neg_hi:[0,1]
	v_pk_mul_f32 v[230:231], v[230:231], v[238:239] op_sel_hi:[1,0]
	v_pk_fma_f32 v[232:233], v[176:177], v[234:235], v[232:233]
	v_pk_fma_f32 v[230:231], v[144:145], v[230:231], v[160:161]
	v_pk_fma_f32 v[230:231], v[240:241], v[232:233], v[230:231] op_sel_hi:[0,1,1]
	v_pk_mul_f32 v[30:31], v[30:31], v[230:231]
	v_cvt_pk_bf16_f32 v24, v24, v25
	v_cvt_pk_bf16_f32 v25, v26, v27
	v_cvt_pk_bf16_f32 v26, v28, v29
	v_cvt_pk_bf16_f32 v27, v30, v31
	global_store_dwordx4 v243, v[24:27], s[22:23] offset:192
	v_add_u32_e32 v246, 0x10000, v237
	v_add_u32_e32 v247, 0x2c000, v239
	v_subrev_u32_e32 v230, 0x1600, v247
	global_load_dwordx4 v[178:181], v246, s[22:23] offset:128
	global_load_dwordx4 v[182:185], v246, s[22:23] offset:192
	global_load_dwordx4 v[186:189], v247, s[96:97] offset:128
	global_load_dwordx4 v[190:193], v247, s[96:97] offset:192
	global_load_dwordx4 v[194:197], v230, s[96:97] offset:128
	global_load_dwordx4 v[198:201], v230, s[96:97] offset:192
	v_add_u32_e32 v246, 0x1800, v241
	s_nop 0
	global_load_dword v240, v246, s[96:97] offset:16
	s_waitcnt vmcnt(9)
; __device__ __forceinline__ float bf2f(u16 h) { return __uint_as_float(((unsigned)h) << 16); }
; template <int EPI> ...
;     ...
;         float o0 = bf2f(Y[(size_t)row * 1024 + 256 + ch0]);
;         float o1 = bf2f(Y[(size_t)row * 1024 + 256 + ch1]);
;         float mean = hsum32(o0 + o1) * (1.0f / 64.0f);
;         float d0 = o0 - mean, d1 = o1 - mean;
;         float var = hsum32(d0 * d0 + d1 * d1) * (1.0f / 64.0f);
;         float rstd = rsqrtf(var + 64e-5f);
;         float pv0 = bf2f(P[(size_t)row * 2816 + 256 + 1536 + ch0]);
;         float pv1 = bf2f(P[(size_t)row * 2816 + 256 + 1536 + ch1]);
;         float pp0 = prevP(p, P, row, 1536 + ch0), pp1 = prevP(p, P, row, 1536 + ch1);
;         float vv0 = pv0 + (pp0 - pv0) * mu0, vv1 = pv1 + (pp1 - pv1) * mu1;
;         float b = bs[((size_t)row * 12 + hh) * 4 + 2];
;         float y0 = (d0 * rstd * gg0 + gb0 + b * vv0) * acc0[i];
;         float y1 = (d1 * rstd * gg1 + gb1 + b * vv1) * acc1[i];
;         Y[(size_t)row * 1024 + 256 + ch0] = f2bf(y0);
;         Y[(size_t)row * 1024 + 256 + ch1] = f2bf(y1);
	v_lshlrev_b32_e32 v232, 16, v202
	v_and_b32_e32 v233, 0xffff0000, v202
	v_lshlrev_b32_e32 v230, 16, v203
	v_and_b32_e32 v231, 0xffff0000, v203
	v_pk_add_f32 v[232:233], v[232:233], v[230:231]
	v_lshlrev_b32_e32 v230, 16, v204
	v_and_b32_e32 v231, 0xffff0000, v204
	v_pk_add_f32 v[232:233], v[232:233], v[230:231]
	v_lshlrev_b32_e32 v230, 16, v205
	v_and_b32_e32 v231, 0xffff0000, v205
	v_pk_add_f32 v[232:233], v[232:233], v[230:231]
	v_lshlrev_b32_e32 v230, 16, v206
	v_and_b32_e32 v231, 0xffff0000, v206
	v_pk_add_f32 v[232:233], v[232:233], v[230:231]
	v_lshlrev_b32_e32 v230, 16, v207
	v_and_b32_e32 v231, 0xffff0000, v207
	v_pk_add_f32 v[232:233], v[232:233], v[230:231]
	v_lshlrev_b32_e32 v230, 16, v208
	v_and_b32_e32 v231, 0xffff0000, v208
	v_pk_add_f32 v[232:233], v[232:233], v[230:231]
	v_lshlrev_b32_e32 v230, 16, v209
	v_and_b32_e32 v231, 0xffff0000, v209
	v_pk_add_f32 v[232:233], v[232:233], v[230:231]
	v_add_f32_e32 v232, v232, v233
	v_mov_b32_e32 v230, v232
	s_nop 1
	v_permlane16_swap_b32_e32 v230, v232
	v_add_f32_e32 v232, v232, v230
	v_mov_b32_e32 v230, v232
	s_nop 1
	v_permlane32_swap_b32_e32 v230, v232
	v_add_f32_e32 v232, v232, v230
	v_mul_f32_e32 v236, 0x3c800000, v232
	v_lshlrev_b32_e32 v230, 16, v202
	v_and_b32_e32 v231, 0xffff0000, v202
	v_pk_add_f32 v[230:231], v[230:231], v[236:237] op_sel_hi:[1,0] neg_lo:[0,1] neg_hi:[0,1]
	v_pk_mul_f32 v[232:233], v[230:231], v[230:231]
	v_lshlrev_b32_e32 v230, 16, v203
	v_and_b32_e32 v231, 0xffff0000, v203
	v_pk_add_f32 v[230:231], v[230:231], v[236:237] op_sel_hi:[1,0] neg_lo:[0,1] neg_hi:[0,1]
	v_pk_fma_f32 v[232:233], v[230:231], v[230:231], v[232:233]
	v_lshlrev_b32_e32 v230, 16, v204
	v_and_b32_e32 v231, 0xffff0000, v204
	v_pk_add_f32 v[230:231], v[230:231], v[236:237] op_sel_hi:[1,0] neg_lo:[0,1] neg_hi:[0,1]
	v_pk_fma_f32 v[232:233], v[230:231], v[230:231], v[232:233]
	v_lshlrev_b32_e32 v230, 16, v205
	v_and_b32_e32 v231, 0xffff0000, v205
	v_pk_add_f32 v[230:231], v[230:231], v[236:237] op_sel_hi:[1,0] neg_lo:[0,1] neg_hi:[0,1]
	v_pk_fma_f32 v[232:233], v[230:231], v[230:231], v[232:233]
	v_lshlrev_b32_e32 v230, 16, v206
	v_and_b32_e32 v231, 0xffff0000, v206
	v_pk_add_f32 v[230:231], v[230:231], v[236:237] op_sel_hi:[1,0] neg_lo:[0,1] neg_hi:[0,1]
	v_pk_fma_f32 v[232:233], v[230:231], v[230:231], v[232:233]
	v_lshlrev_b32_e32 v230, 16, v207
	v_and_b32_e32 v231, 0xffff0000, v207
	v_pk_add_f32 v[230:231], v[230:231], v[236:237] op_sel_hi:[1,0] neg_lo:[0,1] neg_hi:[0,1]
	v_pk_fma_f32 v[232:233], v[230:231], v[230:231], v[232:233]
	v_lshlrev_b32_e32 v230, 16, v208
	v_and_b32_e32 v231, 0xffff0000, v208
	v_pk_add_f32 v[230:231], v[230:231], v[236:237] op_sel_hi:[1,0] neg_lo:[0,1] neg_hi:[0,1]
	v_pk_fma_f32 v[232:233], v[230:231], v[230:231], v[232:233]
	v_lshlrev_b32_e32 v230, 16, v209
	v_and_b32_e32 v231, 0xffff0000, v209
	v_pk_add_f32 v[230:231], v[230:231], v[236:237] op_sel_hi:[1,0] neg_lo:[0,1] neg_hi:[0,1]
	v_pk_fma_f32 v[232:233], v[230:231], v[230:231], v[232:233]
	v_add_f32_e32 v232, v232, v233
	v_mov_b32_e32 v230, v232
	s_nop 1
	v_permlane16_swap_b32_e32 v230, v232
	v_add_f32_e32 v232, v232, v230
	v_mov_b32_e32 v230, v232
	s_nop 1
	v_permlane32_swap_b32_e32 v230, v232
	v_add_f32_e32 v232, v232, v230
	v_mov_b32_e32 v230, 0x3a27c5ac
	v_fmamk_f32 v232, v232, 0x3c800000, v230
	v_rsq_f32_e32 v238, v232
	v_add_u32_e32 v243, 0x8000, v237
	v_lshlrev_b32_e32 v230, 16, v202
	v_and_b32_e32 v231, 0xffff0000, v202
	v_lshlrev_b32_e32 v232, 16, v210
	v_and_b32_e32 v233, 0xffff0000, v210
	v_lshlrev_b32_e32 v234, 16, v218
	v_and_b32_e32 v235, 0xffff0000, v218
	v_pk_add_f32 v[230:231], v[230:231], v[236:237] op_sel_hi:[1,0] neg_lo:[0,1] neg_hi:[0,1]
	v_pk_add_f32 v[234:235], v[234:235], v[232:233] neg_lo:[0,1] neg_hi:[0,1]
	v_pk_mul_f32 v[230:231], v[230:231], v[238:239] op_sel_hi:[1,0]
	v_pk_fma_f32 v[232:233], v[162:163], v[234:235], v[232:233]
	v_pk_fma_f32 v[230:231], v[130:131], v[230:231], v[146:147]
	v_pk_fma_f32 v[230:231], v[244:245], v[232:233], v[230:231] op_sel_hi:[0,1,1]
	v_pk_mul_f32 v[48:49], v[48:49], v[230:231]
	v_lshlrev_b32_e32 v230, 16, v203
	v_and_b32_e32 v231, 0xffff0000, v203
	v_lshlrev_b32_e32 v232, 16, v211
	v_and_b32_e32 v233, 0xffff0000, v211
	v_lshlrev_b32_e32 v234, 16, v219
	v_and_b32_e32 v235, 0xffff0000, v219
	v_pk_add_f32 v[230:231], v[230:231], v[236:237] op_sel_hi:[1,0] neg_lo:[0,1] neg_hi:[0,1]
	v_pk_add_f32 v[234:235], v[234:235], v[232:233] neg_lo:[0,1] neg_hi:[0,1]
	v_pk_mul_f32 v[230:231], v[230:231], v[238:239] op_sel_hi:[1,0]
	v_pk_fma_f32 v[232:233], v[164:165], v[234:235], v[232:233]
	v_pk_fma_f32 v[230:231], v[132:133], v[230:231], v[148:149]
	v_pk_fma_f32 v[230:231], v[244:245], v[232:233], v[230:231] op_sel_hi:[0,1,1]
	v_pk_mul_f32 v[50:51], v[50:51], v[230:231]
	v_lshlrev_b32_e32 v230, 16, v204
	v_and_b32_e32 v231, 0xffff0000, v204
	v_lshlrev_b32_e32 v232, 16, v212
	v_and_b32_e32 v233, 0xffff0000, v212
	v_lshlrev_b32_e32 v234, 16, v220
	v_and_b32_e32 v235, 0xffff0000, v220
	v_pk_add_f32 v[230:231], v[230:231], v[236:237] op_sel_hi:[1,0] neg_lo:[0,1] neg_hi:[0,1]
	v_pk_add_f32 v[234:235], v[234:235], v[232:233] neg_lo:[0,1] neg_hi:[0,1]
	v_pk_mul_f32 v[230:231], v[230:231], v[238:239] op_sel_hi:[1,0]
	v_pk_fma_f32 v[232:233], v[166:167], v[234:235], v[232:233]
	v_pk_fma_f32 v[230:231], v[134:135], v[230:231], v[150:151]
	v_pk_fma_f32 v[230:231], v[244:245], v[232:233], v[230:231] op_sel_hi:[0,1,1]
	v_pk_mul_f32 v[52:53], v[52:53], v[230:231]
	v_lshlrev_b32_e32 v230, 16, v205
	v_and_b32_e32 v231, 0xffff0000, v205
	v_lshlrev_b32_e32 v232, 16, v213
	v_and_b32_e32 v233, 0xffff0000, v213
	v_lshlrev_b32_e32 v234, 16, v221
	v_and_b32_e32 v235, 0xffff0000, v221
; __device__ __forceinline__ float bf2f(u16 h) { return __uint_as_float(((unsigned)h) << 16); }
; template <int EPI> ...
;     ...
;         float o0 = bf2f(Y[(size_t)row * 1024 + 256 + ch0]);
;         float o1 = bf2f(Y[(size_t)row * 1024 + 256 + ch1]);
;         float mean = hsum32(o0 + o1) * (1.0f / 64.0f);
;         float d0 = o0 - mean, d1 = o1 - mean;
;         float var = hsum32(d0 * d0 + d1 * d1) * (1.0f / 64.0f);
;         float rstd = rsqrtf(var + 64e-5f);
;         float pv0 = bf2f(P[(size_t)row * 2816 + 256 + 1536 + ch0]);
;         float pv1 = bf2f(P[(size_t)row * 2816 + 256 + 1536 + ch1]);
;         float pp0 = prevP(p, P, row, 1536 + ch0), pp1 = prevP(p, P, row, 1536 + ch1);
;         float vv0 = pv0 + (pp0 - pv0) * mu0, vv1 = pv1 + (pp1 - pv1) * mu1;
;         float b = bs[((size_t)row * 12 + hh) * 4 + 2];
;         float y0 = (d0 * rstd * gg0 + gb0 + b * vv0) * acc0[i];
;         float y1 = (d1 * rstd * gg1 + gb1 + b * vv1) * acc1[i];
;         Y[(size_t)row * 1024 + 256 + ch0] = f2bf(y0);
;         Y[(size_t)row * 1024 + 256 + ch1] = f2bf(y1);
	v_pk_add_f32 v[230:231], v[230:231], v[236:237] op_sel_hi:[1,0] neg_lo:[0,1] neg_hi:[0,1]
	v_pk_add_f32 v[234:235], v[234:235], v[232:233] neg_lo:[0,1] neg_hi:[0,1]
	v_pk_mul_f32 v[230:231], v[230:231], v[238:239] op_sel_hi:[1,0]
	v_pk_fma_f32 v[232:233], v[168:169], v[234:235], v[232:233]
	v_pk_fma_f32 v[230:231], v[136:137], v[230:231], v[152:153]
	v_pk_fma_f32 v[230:231], v[244:245], v[232:233], v[230:231] op_sel_hi:[0,1,1]
	v_pk_mul_f32 v[54:55], v[54:55], v[230:231]
	v_cvt_pk_bf16_f32 v48, v48, v49
	v_cvt_pk_bf16_f32 v49, v50, v51
	v_cvt_pk_bf16_f32 v50, v52, v53
	v_cvt_pk_bf16_f32 v51, v54, v55
	global_store_dwordx4 v243, v[48:51], s[22:23] offset:128
	v_lshlrev_b32_e32 v230, 16, v206
	v_and_b32_e32 v231, 0xffff0000, v206
	v_lshlrev_b32_e32 v232, 16, v214
	v_and_b32_e32 v233, 0xffff0000, v214
	v_lshlrev_b32_e32 v234, 16, v222
	v_and_b32_e32 v235, 0xffff0000, v222
	v_pk_add_f32 v[230:231], v[230:231], v[236:237] op_sel_hi:[1,0] neg_lo:[0,1] neg_hi:[0,1]
	v_pk_add_f32 v[234:235], v[234:235], v[232:233] neg_lo:[0,1] neg_hi:[0,1]
	v_pk_mul_f32 v[230:231], v[230:231], v[238:239] op_sel_hi:[1,0]
	v_pk_fma_f32 v[232:233], v[170:171], v[234:235], v[232:233]
	v_pk_fma_f32 v[230:231], v[138:139], v[230:231], v[154:155]
	v_pk_fma_f32 v[230:231], v[244:245], v[232:233], v[230:231] op_sel_hi:[0,1,1]
	v_pk_mul_f32 v[56:57], v[56:57], v[230:231]
	v_lshlrev_b32_e32 v230, 16, v207
	v_and_b32_e32 v231, 0xffff0000, v207
	v_lshlrev_b32_e32 v232, 16, v215
	v_and_b32_e32 v233, 0xffff0000, v215
	v_lshlrev_b32_e32 v234, 16, v223
	v_and_b32_e32 v235, 0xffff0000, v223
	v_pk_add_f32 v[230:231], v[230:231], v[236:237] op_sel_hi:[1,0] neg_lo:[0,1] neg_hi:[0,1]
	v_pk_add_f32 v[234:235], v[234:235], v[232:233] neg_lo:[0,1] neg_hi:[0,1]
	v_pk_mul_f32 v[230:231], v[230:231], v[238:239] op_sel_hi:[1,0]
	v_pk_fma_f32 v[232:233], v[172:173], v[234:235], v[232:233]
	v_pk_fma_f32 v[230:231], v[140:141], v[230:231], v[156:157]
	v_pk_fma_f32 v[230:231], v[244:245], v[232:233], v[230:231] op_sel_hi:[0,1,1]
	v_pk_mul_f32 v[58:59], v[58:59], v[230:231]
	v_lshlrev_b32_e32 v230, 16, v208
	v_and_b32_e32 v231, 0xffff0000, v208
	v_lshlrev_b32_e32 v232, 16, v216
	v_and_b32_e32 v233, 0xffff0000, v216
	v_lshlrev_b32_e32 v234, 16, v224
	v_and_b32_e32 v235, 0xffff0000, v224
	v_pk_add_f32 v[230:231], v[230:231], v[236:237] op_sel_hi:[1,0] neg_lo:[0,1] neg_hi:[0,1]
	v_pk_add_f32 v[234:235], v[234:235], v[232:233] neg_lo:[0,1] neg_hi:[0,1]
	v_pk_mul_f32 v[230:231], v[230:231], v[238:239] op_sel_hi:[1,0]
	v_pk_fma_f32 v[232:233], v[174:175], v[234:235], v[232:233]
	v_pk_fma_f32 v[230:231], v[142:143], v[230:231], v[158:159]
	v_pk_fma_f32 v[230:231], v[244:245], v[232:233], v[230:231] op_sel_hi:[0,1,1]
	v_pk_mul_f32 v[60:61], v[60:61], v[230:231]
	v_lshlrev_b32_e32 v230, 16, v209
	v_and_b32_e32 v231, 0xffff0000, v209
	v_lshlrev_b32_e32 v232, 16, v217
	v_and_b32_e32 v233, 0xffff0000, v217
	v_lshlrev_b32_e32 v234, 16, v225
	v_and_b32_e32 v235, 0xffff0000, v225
	v_pk_add_f32 v[230:231], v[230:231], v[236:237] op_sel_hi:[1,0] neg_lo:[0,1] neg_hi:[0,1]
	v_pk_add_f32 v[234:235], v[234:235], v[232:233] neg_lo:[0,1] neg_hi:[0,1]
	v_pk_mul_f32 v[230:231], v[230:231], v[238:239] op_sel_hi:[1,0]
	v_pk_fma_f32 v[232:233], v[176:177], v[234:235], v[232:233]
	v_pk_fma_f32 v[230:231], v[144:145], v[230:231], v[160:161]
	v_pk_fma_f32 v[230:231], v[244:245], v[232:233], v[230:231] op_sel_hi:[0,1,1]
	v_pk_mul_f32 v[62:63], v[62:63], v[230:231]
	v_cvt_pk_bf16_f32 v56, v56, v57
	v_cvt_pk_bf16_f32 v57, v58, v59
	v_cvt_pk_bf16_f32 v58, v60, v61
	v_cvt_pk_bf16_f32 v59, v62, v63
	global_store_dwordx4 v243, v[56:59], s[22:23] offset:192
	v_add_u32_e32 v246, 0x18000, v237
	v_add_u32_e32 v247, 0x42000, v239
	v_subrev_u32_e32 v230, 0x1600, v247
	global_load_dwordx4 v[202:205], v246, s[22:23] offset:128
	global_load_dwordx4 v[206:209], v246, s[22:23] offset:192
	global_load_dwordx4 v[210:213], v247, s[96:97] offset:128
	global_load_dwordx4 v[214:217], v247, s[96:97] offset:192
	global_load_dwordx4 v[218:221], v230, s[96:97] offset:128
	global_load_dwordx4 v[222:225], v230, s[96:97] offset:192
	v_add_u32_e32 v246, 0x2400, v241
	s_nop 0
	global_load_dword v244, v246, s[96:97] offset:16
	s_waitcnt vmcnt(9)
	v_lshlrev_b32_e32 v232, 16, v178
	v_and_b32_e32 v233, 0xffff0000, v178
	v_lshlrev_b32_e32 v230, 16, v179
	v_and_b32_e32 v231, 0xffff0000, v179
	v_pk_add_f32 v[232:233], v[232:233], v[230:231]
	v_lshlrev_b32_e32 v230, 16, v180
	v_and_b32_e32 v231, 0xffff0000, v180
	v_pk_add_f32 v[232:233], v[232:233], v[230:231]
	v_lshlrev_b32_e32 v230, 16, v181
	v_and_b32_e32 v231, 0xffff0000, v181
	v_pk_add_f32 v[232:233], v[232:233], v[230:231]
	v_lshlrev_b32_e32 v230, 16, v182
	v_and_b32_e32 v231, 0xffff0000, v182
	v_pk_add_f32 v[232:233], v[232:233], v[230:231]
	v_lshlrev_b32_e32 v230, 16, v183
	v_and_b32_e32 v231, 0xffff0000, v183
	v_pk_add_f32 v[232:233], v[232:233], v[230:231]
	v_lshlrev_b32_e32 v230, 16, v184
	v_and_b32_e32 v231, 0xffff0000, v184
	v_pk_add_f32 v[232:233], v[232:233], v[230:231]
	v_lshlrev_b32_e32 v230, 16, v185
	v_and_b32_e32 v231, 0xffff0000, v185
	v_pk_add_f32 v[232:233], v[232:233], v[230:231]
	v_add_f32_e32 v232, v232, v233
	v_mov_b32_e32 v230, v232
	s_nop 1
	v_permlane16_swap_b32_e32 v230, v232
	v_add_f32_e32 v232, v232, v230
	v_mov_b32_e32 v230, v232
	s_nop 1
	v_permlane32_swap_b32_e32 v230, v232
	v_add_f32_e32 v232, v232, v230
	v_mul_f32_e32 v236, 0x3c800000, v232
	v_lshlrev_b32_e32 v230, 16, v178
	v_and_b32_e32 v231, 0xffff0000, v178
	v_pk_add_f32 v[230:231], v[230:231], v[236:237] op_sel_hi:[1,0] neg_lo:[0,1] neg_hi:[0,1]
	v_pk_mul_f32 v[232:233], v[230:231], v[230:231]
	v_lshlrev_b32_e32 v230, 16, v179
; __device__ __forceinline__ float bf2f(u16 h) { return __uint_as_float(((unsigned)h) << 16); }
; template <int EPI> ...
;     ...
;         float mean = hsum32(o0 + o1) * (1.0f / 64.0f);
;         float d0 = o0 - mean, d1 = o1 - mean;
;         float var = hsum32(d0 * d0 + d1 * d1) * (1.0f / 64.0f);
;         float rstd = rsqrtf(var + 64e-5f);
;         float pv0 = bf2f(P[(size_t)row * 2816 + 256 + 1536 + ch0]);
;         float pv1 = bf2f(P[(size_t)row * 2816 + 256 + 1536 + ch1]);
;         float pp0 = prevP(p, P, row, 1536 + ch0), pp1 = prevP(p, P, row, 1536 + ch1);
;         float vv0 = pv0 + (pp0 - pv0) * mu0, vv1 = pv1 + (pp1 - pv1) * mu1;
;         float b = bs[((size_t)row * 12 + hh) * 4 + 2];
;         float y0 = (d0 * rstd * gg0 + gb0 + b * vv0) * acc0[i];
;         float y1 = (d1 * rstd * gg1 + gb1 + b * vv1) * acc1[i];
;         Y[(size_t)row * 1024 + 256 + ch0] = f2bf(y0);
;         Y[(size_t)row * 1024 + 256 + ch1] = f2bf(y1);
	v_and_b32_e32 v231, 0xffff0000, v179
	v_pk_add_f32 v[230:231], v[230:231], v[236:237] op_sel_hi:[1,0] neg_lo:[0,1] neg_hi:[0,1]
	v_pk_fma_f32 v[232:233], v[230:231], v[230:231], v[232:233]
	v_lshlrev_b32_e32 v230, 16, v180
	v_and_b32_e32 v231, 0xffff0000, v180
	v_pk_add_f32 v[230:231], v[230:231], v[236:237] op_sel_hi:[1,0] neg_lo:[0,1] neg_hi:[0,1]
	v_pk_fma_f32 v[232:233], v[230:231], v[230:231], v[232:233]
	v_lshlrev_b32_e32 v230, 16, v181
	v_and_b32_e32 v231, 0xffff0000, v181
	v_pk_add_f32 v[230:231], v[230:231], v[236:237] op_sel_hi:[1,0] neg_lo:[0,1] neg_hi:[0,1]
	v_pk_fma_f32 v[232:233], v[230:231], v[230:231], v[232:233]
	v_lshlrev_b32_e32 v230, 16, v182
	v_and_b32_e32 v231, 0xffff0000, v182
	v_pk_add_f32 v[230:231], v[230:231], v[236:237] op_sel_hi:[1,0] neg_lo:[0,1] neg_hi:[0,1]
	v_pk_fma_f32 v[232:233], v[230:231], v[230:231], v[232:233]
	v_lshlrev_b32_e32 v230, 16, v183
	v_and_b32_e32 v231, 0xffff0000, v183
	v_pk_add_f32 v[230:231], v[230:231], v[236:237] op_sel_hi:[1,0] neg_lo:[0,1] neg_hi:[0,1]
	v_pk_fma_f32 v[232:233], v[230:231], v[230:231], v[232:233]
	v_lshlrev_b32_e32 v230, 16, v184
	v_and_b32_e32 v231, 0xffff0000, v184
	v_pk_add_f32 v[230:231], v[230:231], v[236:237] op_sel_hi:[1,0] neg_lo:[0,1] neg_hi:[0,1]
	v_pk_fma_f32 v[232:233], v[230:231], v[230:231], v[232:233]
	v_lshlrev_b32_e32 v230, 16, v185
	v_and_b32_e32 v231, 0xffff0000, v185
	v_pk_add_f32 v[230:231], v[230:231], v[236:237] op_sel_hi:[1,0] neg_lo:[0,1] neg_hi:[0,1]
	v_pk_fma_f32 v[232:233], v[230:231], v[230:231], v[232:233]
	v_add_f32_e32 v232, v232, v233
	v_mov_b32_e32 v230, v232
	s_nop 1
	v_permlane16_swap_b32_e32 v230, v232
	v_add_f32_e32 v232, v232, v230
	v_mov_b32_e32 v230, v232
	s_nop 1
	v_permlane32_swap_b32_e32 v230, v232
	v_add_f32_e32 v232, v232, v230
	v_mov_b32_e32 v230, 0x3a27c5ac
	v_fmamk_f32 v232, v232, 0x3c800000, v230
	v_rsq_f32_e32 v238, v232
	v_add_u32_e32 v243, 0x10000, v237
	v_lshlrev_b32_e32 v230, 16, v178
	v_and_b32_e32 v231, 0xffff0000, v178
	v_lshlrev_b32_e32 v232, 16, v186
	v_and_b32_e32 v233, 0xffff0000, v186
	v_lshlrev_b32_e32 v234, 16, v194
	v_and_b32_e32 v235, 0xffff0000, v194
	v_pk_add_f32 v[230:231], v[230:231], v[236:237] op_sel_hi:[1,0] neg_lo:[0,1] neg_hi:[0,1]
	v_pk_add_f32 v[234:235], v[234:235], v[232:233] neg_lo:[0,1] neg_hi:[0,1]
	v_pk_mul_f32 v[230:231], v[230:231], v[238:239] op_sel_hi:[1,0]
	v_pk_fma_f32 v[232:233], v[162:163], v[234:235], v[232:233]
	v_pk_fma_f32 v[230:231], v[130:131], v[230:231], v[146:147]
	v_pk_fma_f32 v[230:231], v[240:241], v[232:233], v[230:231] op_sel_hi:[0,1,1]
	v_pk_mul_f32 v[80:81], v[80:81], v[230:231]
	v_lshlrev_b32_e32 v230, 16, v179
	v_and_b32_e32 v231, 0xffff0000, v179
	v_lshlrev_b32_e32 v232, 16, v187
	v_and_b32_e32 v233, 0xffff0000, v187
	v_lshlrev_b32_e32 v234, 16, v195
	v_and_b32_e32 v235, 0xffff0000, v195
	v_pk_add_f32 v[230:231], v[230:231], v[236:237] op_sel_hi:[1,0] neg_lo:[0,1] neg_hi:[0,1]
	v_pk_add_f32 v[234:235], v[234:235], v[232:233] neg_lo:[0,1] neg_hi:[0,1]
	v_pk_mul_f32 v[230:231], v[230:231], v[238:239] op_sel_hi:[1,0]
	v_pk_fma_f32 v[232:233], v[164:165], v[234:235], v[232:233]
	v_pk_fma_f32 v[230:231], v[132:133], v[230:231], v[148:149]
	v_pk_fma_f32 v[230:231], v[240:241], v[232:233], v[230:231] op_sel_hi:[0,1,1]
	v_pk_mul_f32 v[82:83], v[82:83], v[230:231]
	v_lshlrev_b32_e32 v230, 16, v180
	v_and_b32_e32 v231, 0xffff0000, v180
	v_lshlrev_b32_e32 v232, 16, v188
	v_and_b32_e32 v233, 0xffff0000, v188
	v_lshlrev_b32_e32 v234, 16, v196
	v_and_b32_e32 v235, 0xffff0000, v196
	v_pk_add_f32 v[230:231], v[230:231], v[236:237] op_sel_hi:[1,0] neg_lo:[0,1] neg_hi:[0,1]
	v_pk_add_f32 v[234:235], v[234:235], v[232:233] neg_lo:[0,1] neg_hi:[0,1]
	v_pk_mul_f32 v[230:231], v[230:231], v[238:239] op_sel_hi:[1,0]
	v_pk_fma_f32 v[232:233], v[166:167], v[234:235], v[232:233]
	v_pk_fma_f32 v[230:231], v[134:135], v[230:231], v[150:151]
	v_pk_fma_f32 v[230:231], v[240:241], v[232:233], v[230:231] op_sel_hi:[0,1,1]
	v_pk_mul_f32 v[84:85], v[84:85], v[230:231]
	v_lshlrev_b32_e32 v230, 16, v181
	v_and_b32_e32 v231, 0xffff0000, v181
	v_lshlrev_b32_e32 v232, 16, v189
	v_and_b32_e32 v233, 0xffff0000, v189
	v_lshlrev_b32_e32 v234, 16, v197
	v_and_b32_e32 v235, 0xffff0000, v197
	v_pk_add_f32 v[230:231], v[230:231], v[236:237] op_sel_hi:[1,0] neg_lo:[0,1] neg_hi:[0,1]
	v_pk_add_f32 v[234:235], v[234:235], v[232:233] neg_lo:[0,1] neg_hi:[0,1]
	v_pk_mul_f32 v[230:231], v[230:231], v[238:239] op_sel_hi:[1,0]
	v_pk_fma_f32 v[232:233], v[168:169], v[234:235], v[232:233]
	v_pk_fma_f32 v[230:231], v[136:137], v[230:231], v[152:153]
	v_pk_fma_f32 v[230:231], v[240:241], v[232:233], v[230:231] op_sel_hi:[0,1,1]
	v_pk_mul_f32 v[86:87], v[86:87], v[230:231]
	v_cvt_pk_bf16_f32 v80, v80, v81
	v_cvt_pk_bf16_f32 v81, v82, v83
	v_cvt_pk_bf16_f32 v82, v84, v85
	v_cvt_pk_bf16_f32 v83, v86, v87
	global_store_dwordx4 v243, v[80:83], s[22:23] offset:128
	v_lshlrev_b32_e32 v230, 16, v182
	v_and_b32_e32 v231, 0xffff0000, v182
	v_lshlrev_b32_e32 v232, 16, v190
	v_and_b32_e32 v233, 0xffff0000, v190
	v_lshlrev_b32_e32 v234, 16, v198
	v_and_b32_e32 v235, 0xffff0000, v198
	v_pk_add_f32 v[230:231], v[230:231], v[236:237] op_sel_hi:[1,0] neg_lo:[0,1] neg_hi:[0,1]
	v_pk_add_f32 v[234:235], v[234:235], v[232:233] neg_lo:[0,1] neg_hi:[0,1]
	v_pk_mul_f32 v[230:231], v[230:231], v[238:239] op_sel_hi:[1,0]
	v_pk_fma_f32 v[232:233], v[170:171], v[234:235], v[232:233]
	v_pk_fma_f32 v[230:231], v[138:139], v[230:231], v[154:155]
	v_pk_fma_f32 v[230:231], v[240:241], v[232:233], v[230:231] op_sel_hi:[0,1,1]
	v_pk_mul_f32 v[88:89], v[88:89], v[230:231]
	v_lshlrev_b32_e32 v230, 16, v183
	v_and_b32_e32 v231, 0xffff0000, v183
; __device__ __forceinline__ float bf2f(u16 h) { return __uint_as_float(((unsigned)h) << 16); }
; template <int EPI> ...
;     ...
;         float mean = hsum32(o0 + o1) * (1.0f / 64.0f);
;         float d0 = o0 - mean, d1 = o1 - mean;
;         float var = hsum32(d0 * d0 + d1 * d1) * (1.0f / 64.0f);
;         float rstd = rsqrtf(var + 64e-5f);
;         float pv0 = bf2f(P[(size_t)row * 2816 + 256 + 1536 + ch0]);
;         float pv1 = bf2f(P[(size_t)row * 2816 + 256 + 1536 + ch1]);
;         float pp0 = prevP(p, P, row, 1536 + ch0), pp1 = prevP(p, P, row, 1536 + ch1);
;         float vv0 = pv0 + (pp0 - pv0) * mu0, vv1 = pv1 + (pp1 - pv1) * mu1;
;         float b = bs[((size_t)row * 12 + hh) * 4 + 2];
;         float y0 = (d0 * rstd * gg0 + gb0 + b * vv0) * acc0[i];
;         float y1 = (d1 * rstd * gg1 + gb1 + b * vv1) * acc1[i];
;         Y[(size_t)row * 1024 + 256 + ch0] = f2bf(y0);
;         Y[(size_t)row * 1024 + 256 + ch1] = f2bf(y1);
	v_lshlrev_b32_e32 v232, 16, v191
	v_and_b32_e32 v233, 0xffff0000, v191
	v_lshlrev_b32_e32 v234, 16, v199
	v_and_b32_e32 v235, 0xffff0000, v199
	v_pk_add_f32 v[230:231], v[230:231], v[236:237] op_sel_hi:[1,0] neg_lo:[0,1] neg_hi:[0,1]
	v_pk_add_f32 v[234:235], v[234:235], v[232:233] neg_lo:[0,1] neg_hi:[0,1]
	v_pk_mul_f32 v[230:231], v[230:231], v[238:239] op_sel_hi:[1,0]
	v_pk_fma_f32 v[232:233], v[172:173], v[234:235], v[232:233]
	v_pk_fma_f32 v[230:231], v[140:141], v[230:231], v[156:157]
	v_pk_fma_f32 v[230:231], v[240:241], v[232:233], v[230:231] op_sel_hi:[0,1,1]
	v_pk_mul_f32 v[90:91], v[90:91], v[230:231]
	v_lshlrev_b32_e32 v230, 16, v184
	v_and_b32_e32 v231, 0xffff0000, v184
	v_lshlrev_b32_e32 v232, 16, v192
	v_and_b32_e32 v233, 0xffff0000, v192
	v_lshlrev_b32_e32 v234, 16, v200
	v_and_b32_e32 v235, 0xffff0000, v200
	v_pk_add_f32 v[230:231], v[230:231], v[236:237] op_sel_hi:[1,0] neg_lo:[0,1] neg_hi:[0,1]
	v_pk_add_f32 v[234:235], v[234:235], v[232:233] neg_lo:[0,1] neg_hi:[0,1]
	v_pk_mul_f32 v[230:231], v[230:231], v[238:239] op_sel_hi:[1,0]
	v_pk_fma_f32 v[232:233], v[174:175], v[234:235], v[232:233]
	v_pk_fma_f32 v[230:231], v[142:143], v[230:231], v[158:159]
	v_pk_fma_f32 v[230:231], v[240:241], v[232:233], v[230:231] op_sel_hi:[0,1,1]
	v_pk_mul_f32 v[92:93], v[92:93], v[230:231]
	v_lshlrev_b32_e32 v230, 16, v185
	v_and_b32_e32 v231, 0xffff0000, v185
	v_lshlrev_b32_e32 v232, 16, v193
	v_and_b32_e32 v233, 0xffff0000, v193
	v_lshlrev_b32_e32 v234, 16, v201
	v_and_b32_e32 v235, 0xffff0000, v201
	v_pk_add_f32 v[230:231], v[230:231], v[236:237] op_sel_hi:[1,0] neg_lo:[0,1] neg_hi:[0,1]
	v_pk_add_f32 v[234:235], v[234:235], v[232:233] neg_lo:[0,1] neg_hi:[0,1]
	v_pk_mul_f32 v[230:231], v[230:231], v[238:239] op_sel_hi:[1,0]
	v_pk_fma_f32 v[232:233], v[176:177], v[234:235], v[232:233]
	v_pk_fma_f32 v[230:231], v[144:145], v[230:231], v[160:161]
	v_pk_fma_f32 v[230:231], v[240:241], v[232:233], v[230:231] op_sel_hi:[0,1,1]
	v_pk_mul_f32 v[94:95], v[94:95], v[230:231]
	v_cvt_pk_bf16_f32 v88, v88, v89
	v_cvt_pk_bf16_f32 v89, v90, v91
	v_cvt_pk_bf16_f32 v90, v92, v93
	v_cvt_pk_bf16_f32 v91, v94, v95
	global_store_dwordx4 v243, v[88:91], s[22:23] offset:192
	s_waitcnt vmcnt(2)
	v_lshlrev_b32_e32 v232, 16, v202
	v_and_b32_e32 v233, 0xffff0000, v202
	v_lshlrev_b32_e32 v230, 16, v203
	v_and_b32_e32 v231, 0xffff0000, v203
	v_pk_add_f32 v[232:233], v[232:233], v[230:231]
	v_lshlrev_b32_e32 v230, 16, v204
	v_and_b32_e32 v231, 0xffff0000, v204
	v_pk_add_f32 v[232:233], v[232:233], v[230:231]
	v_lshlrev_b32_e32 v230, 16, v205
	v_and_b32_e32 v231, 0xffff0000, v205
	v_pk_add_f32 v[232:233], v[232:233], v[230:231]
	v_lshlrev_b32_e32 v230, 16, v206
	v_and_b32_e32 v231, 0xffff0000, v206
	v_pk_add_f32 v[232:233], v[232:233], v[230:231]
	v_lshlrev_b32_e32 v230, 16, v207
	v_and_b32_e32 v231, 0xffff0000, v207
	v_pk_add_f32 v[232:233], v[232:233], v[230:231]
	v_lshlrev_b32_e32 v230, 16, v208
	v_and_b32_e32 v231, 0xffff0000, v208
	v_pk_add_f32 v[232:233], v[232:233], v[230:231]
	v_lshlrev_b32_e32 v230, 16, v209
	v_and_b32_e32 v231, 0xffff0000, v209
	v_pk_add_f32 v[232:233], v[232:233], v[230:231]
	v_add_f32_e32 v232, v232, v233
	v_mov_b32_e32 v230, v232
	s_nop 1
	v_permlane16_swap_b32_e32 v230, v232
	v_add_f32_e32 v232, v232, v230
	v_mov_b32_e32 v230, v232
	s_nop 1
	v_permlane32_swap_b32_e32 v230, v232
	v_add_f32_e32 v232, v232, v230
	v_mul_f32_e32 v236, 0x3c800000, v232
	v_lshlrev_b32_e32 v230, 16, v202
	v_and_b32_e32 v231, 0xffff0000, v202
	v_pk_add_f32 v[230:231], v[230:231], v[236:237] op_sel_hi:[1,0] neg_lo:[0,1] neg_hi:[0,1]
	v_pk_mul_f32 v[232:233], v[230:231], v[230:231]
	v_lshlrev_b32_e32 v230, 16, v203
	v_and_b32_e32 v231, 0xffff0000, v203
	v_pk_add_f32 v[230:231], v[230:231], v[236:237] op_sel_hi:[1,0] neg_lo:[0,1] neg_hi:[0,1]
	v_pk_fma_f32 v[232:233], v[230:231], v[230:231], v[232:233]
	v_lshlrev_b32_e32 v230, 16, v204
	v_and_b32_e32 v231, 0xffff0000, v204
	v_pk_add_f32 v[230:231], v[230:231], v[236:237] op_sel_hi:[1,0] neg_lo:[0,1] neg_hi:[0,1]
	v_pk_fma_f32 v[232:233], v[230:231], v[230:231], v[232:233]
	v_lshlrev_b32_e32 v230, 16, v205
	v_and_b32_e32 v231, 0xffff0000, v205
	v_pk_add_f32 v[230:231], v[230:231], v[236:237] op_sel_hi:[1,0] neg_lo:[0,1] neg_hi:[0,1]
	v_pk_fma_f32 v[232:233], v[230:231], v[230:231], v[232:233]
	v_lshlrev_b32_e32 v230, 16, v206
	v_and_b32_e32 v231, 0xffff0000, v206
	v_pk_add_f32 v[230:231], v[230:231], v[236:237] op_sel_hi:[1,0] neg_lo:[0,1] neg_hi:[0,1]
	v_pk_fma_f32 v[232:233], v[230:231], v[230:231], v[232:233]
	v_lshlrev_b32_e32 v230, 16, v207
	v_and_b32_e32 v231, 0xffff0000, v207
	v_pk_add_f32 v[230:231], v[230:231], v[236:237] op_sel_hi:[1,0] neg_lo:[0,1] neg_hi:[0,1]
	v_pk_fma_f32 v[232:233], v[230:231], v[230:231], v[232:233]
	v_lshlrev_b32_e32 v230, 16, v208
	v_and_b32_e32 v231, 0xffff0000, v208
	v_pk_add_f32 v[230:231], v[230:231], v[236:237] op_sel_hi:[1,0] neg_lo:[0,1] neg_hi:[0,1]
	v_pk_fma_f32 v[232:233], v[230:231], v[230:231], v[232:233]
	v_lshlrev_b32_e32 v230, 16, v209
	v_and_b32_e32 v231, 0xffff0000, v209
	v_pk_add_f32 v[230:231], v[230:231], v[236:237] op_sel_hi:[1,0] neg_lo:[0,1] neg_hi:[0,1]
	v_pk_fma_f32 v[232:233], v[230:231], v[230:231], v[232:233]
	v_add_f32_e32 v232, v232, v233
	v_mov_b32_e32 v230, v232
	s_nop 1
	v_permlane16_swap_b32_e32 v230, v232
	v_add_f32_e32 v232, v232, v230
	v_mov_b32_e32 v230, v232
	s_nop 1
	v_permlane32_swap_b32_e32 v230, v232
	v_add_f32_e32 v232, v232, v230
	v_mov_b32_e32 v230, 0x3a27c5ac
	v_fmamk_f32 v232, v232, 0x3c800000, v230
	v_rsq_f32_e32 v238, v232
	v_add_u32_e32 v243, 0x18000, v237
	v_lshlrev_b32_e32 v230, 16, v202
	v_and_b32_e32 v231, 0xffff0000, v202
; template <int EPI> ...
;     ...
;         float pp0 = prevP(p, P, row, 1536 + ch0), pp1 = prevP(p, P, row, 1536 + ch1);
;         float vv0 = pv0 + (pp0 - pv0) * mu0, vv1 = pv1 + (pp1 - pv1) * mu1;
;         float b = bs[((size_t)row * 12 + hh) * 4 + 2];
;         float y0 = (d0 * rstd * gg0 + gb0 + b * vv0) * acc0[i];
;         float y1 = (d1 * rstd * gg1 + gb1 + b * vv1) * acc1[i];
;         Y[(size_t)row * 1024 + 256 + ch0] = f2bf(y0);
;         Y[(size_t)row * 1024 + 256 + ch1] = f2bf(y1);
	v_lshlrev_b32_e32 v232, 16, v210
	v_and_b32_e32 v233, 0xffff0000, v210
	v_lshlrev_b32_e32 v234, 16, v218
	v_and_b32_e32 v235, 0xffff0000, v218
	v_pk_add_f32 v[230:231], v[230:231], v[236:237] op_sel_hi:[1,0] neg_lo:[0,1] neg_hi:[0,1]
	v_pk_add_f32 v[234:235], v[234:235], v[232:233] neg_lo:[0,1] neg_hi:[0,1]
	v_pk_mul_f32 v[230:231], v[230:231], v[238:239] op_sel_hi:[1,0]
	v_pk_fma_f32 v[232:233], v[162:163], v[234:235], v[232:233]
	v_pk_fma_f32 v[230:231], v[130:131], v[230:231], v[146:147]
	v_pk_fma_f32 v[230:231], v[244:245], v[232:233], v[230:231] op_sel_hi:[0,1,1]
	v_pk_mul_f32 v[112:113], v[112:113], v[230:231]
	v_lshlrev_b32_e32 v230, 16, v203
	v_and_b32_e32 v231, 0xffff0000, v203
	v_lshlrev_b32_e32 v232, 16, v211
	v_and_b32_e32 v233, 0xffff0000, v211
	v_lshlrev_b32_e32 v234, 16, v219
	v_and_b32_e32 v235, 0xffff0000, v219
	v_pk_add_f32 v[230:231], v[230:231], v[236:237] op_sel_hi:[1,0] neg_lo:[0,1] neg_hi:[0,1]
	v_pk_add_f32 v[234:235], v[234:235], v[232:233] neg_lo:[0,1] neg_hi:[0,1]
	v_pk_mul_f32 v[230:231], v[230:231], v[238:239] op_sel_hi:[1,0]
	v_pk_fma_f32 v[232:233], v[164:165], v[234:235], v[232:233]
	v_pk_fma_f32 v[230:231], v[132:133], v[230:231], v[148:149]
	v_pk_fma_f32 v[230:231], v[244:245], v[232:233], v[230:231] op_sel_hi:[0,1,1]
	v_pk_mul_f32 v[114:115], v[114:115], v[230:231]
	v_lshlrev_b32_e32 v230, 16, v204
	v_and_b32_e32 v231, 0xffff0000, v204
	v_lshlrev_b32_e32 v232, 16, v212
	v_and_b32_e32 v233, 0xffff0000, v212
	v_lshlrev_b32_e32 v234, 16, v220
	v_and_b32_e32 v235, 0xffff0000, v220
	v_pk_add_f32 v[230:231], v[230:231], v[236:237] op_sel_hi:[1,0] neg_lo:[0,1] neg_hi:[0,1]
	v_pk_add_f32 v[234:235], v[234:235], v[232:233] neg_lo:[0,1] neg_hi:[0,1]
	v_pk_mul_f32 v[230:231], v[230:231], v[238:239] op_sel_hi:[1,0]
	v_pk_fma_f32 v[232:233], v[166:167], v[234:235], v[232:233]
	v_pk_fma_f32 v[230:231], v[134:135], v[230:231], v[150:151]
	v_pk_fma_f32 v[230:231], v[244:245], v[232:233], v[230:231] op_sel_hi:[0,1,1]
	v_pk_mul_f32 v[116:117], v[116:117], v[230:231]
	v_lshlrev_b32_e32 v230, 16, v205
	v_and_b32_e32 v231, 0xffff0000, v205
	v_lshlrev_b32_e32 v232, 16, v213
	v_and_b32_e32 v233, 0xffff0000, v213
	v_lshlrev_b32_e32 v234, 16, v221
	v_and_b32_e32 v235, 0xffff0000, v221
	v_pk_add_f32 v[230:231], v[230:231], v[236:237] op_sel_hi:[1,0] neg_lo:[0,1] neg_hi:[0,1]
	v_pk_add_f32 v[234:235], v[234:235], v[232:233] neg_lo:[0,1] neg_hi:[0,1]
	v_pk_mul_f32 v[230:231], v[230:231], v[238:239] op_sel_hi:[1,0]
	v_pk_fma_f32 v[232:233], v[168:169], v[234:235], v[232:233]
	v_pk_fma_f32 v[230:231], v[136:137], v[230:231], v[152:153]
	v_pk_fma_f32 v[230:231], v[244:245], v[232:233], v[230:231] op_sel_hi:[0,1,1]
	v_pk_mul_f32 v[118:119], v[118:119], v[230:231]
	v_cvt_pk_bf16_f32 v112, v112, v113
	v_cvt_pk_bf16_f32 v113, v114, v115
	v_cvt_pk_bf16_f32 v114, v116, v117
	v_cvt_pk_bf16_f32 v115, v118, v119
	global_store_dwordx4 v243, v[112:115], s[22:23] offset:128
	v_lshlrev_b32_e32 v230, 16, v206
	v_and_b32_e32 v231, 0xffff0000, v206
	v_lshlrev_b32_e32 v232, 16, v214
	v_and_b32_e32 v233, 0xffff0000, v214
	v_lshlrev_b32_e32 v234, 16, v222
	v_and_b32_e32 v235, 0xffff0000, v222
	v_pk_add_f32 v[230:231], v[230:231], v[236:237] op_sel_hi:[1,0] neg_lo:[0,1] neg_hi:[0,1]
	v_pk_add_f32 v[234:235], v[234:235], v[232:233] neg_lo:[0,1] neg_hi:[0,1]
	v_pk_mul_f32 v[230:231], v[230:231], v[238:239] op_sel_hi:[1,0]
	v_pk_fma_f32 v[232:233], v[170:171], v[234:235], v[232:233]
	v_pk_fma_f32 v[230:231], v[138:139], v[230:231], v[154:155]
	v_pk_fma_f32 v[230:231], v[244:245], v[232:233], v[230:231] op_sel_hi:[0,1,1]
	v_pk_mul_f32 v[120:121], v[120:121], v[230:231]
	v_lshlrev_b32_e32 v230, 16, v207
	v_and_b32_e32 v231, 0xffff0000, v207
	v_lshlrev_b32_e32 v232, 16, v215
	v_and_b32_e32 v233, 0xffff0000, v215
	v_lshlrev_b32_e32 v234, 16, v223
	v_and_b32_e32 v235, 0xffff0000, v223
	v_pk_add_f32 v[230:231], v[230:231], v[236:237] op_sel_hi:[1,0] neg_lo:[0,1] neg_hi:[0,1]
	v_pk_add_f32 v[234:235], v[234:235], v[232:233] neg_lo:[0,1] neg_hi:[0,1]
	v_pk_mul_f32 v[230:231], v[230:231], v[238:239] op_sel_hi:[1,0]
	v_pk_fma_f32 v[232:233], v[172:173], v[234:235], v[232:233]
	v_pk_fma_f32 v[230:231], v[140:141], v[230:231], v[156:157]
	v_pk_fma_f32 v[230:231], v[244:245], v[232:233], v[230:231] op_sel_hi:[0,1,1]
	v_pk_mul_f32 v[122:123], v[122:123], v[230:231]
	v_lshlrev_b32_e32 v230, 16, v208
	v_and_b32_e32 v231, 0xffff0000, v208
	v_lshlrev_b32_e32 v232, 16, v216
	v_and_b32_e32 v233, 0xffff0000, v216
	v_lshlrev_b32_e32 v234, 16, v224
	v_and_b32_e32 v235, 0xffff0000, v224
	v_pk_add_f32 v[230:231], v[230:231], v[236:237] op_sel_hi:[1,0] neg_lo:[0,1] neg_hi:[0,1]
	v_pk_add_f32 v[234:235], v[234:235], v[232:233] neg_lo:[0,1] neg_hi:[0,1]
	v_pk_mul_f32 v[230:231], v[230:231], v[238:239] op_sel_hi:[1,0]
	v_pk_fma_f32 v[232:233], v[174:175], v[234:235], v[232:233]
	v_pk_fma_f32 v[230:231], v[142:143], v[230:231], v[158:159]
	v_pk_fma_f32 v[230:231], v[244:245], v[232:233], v[230:231] op_sel_hi:[0,1,1]
	v_pk_mul_f32 v[124:125], v[124:125], v[230:231]
	v_lshlrev_b32_e32 v230, 16, v209
	v_and_b32_e32 v231, 0xffff0000, v209
	v_lshlrev_b32_e32 v232, 16, v217
	v_and_b32_e32 v233, 0xffff0000, v217
	v_lshlrev_b32_e32 v234, 16, v225
	v_and_b32_e32 v235, 0xffff0000, v225
	v_pk_add_f32 v[230:231], v[230:231], v[236:237] op_sel_hi:[1,0] neg_lo:[0,1] neg_hi:[0,1]
	v_pk_add_f32 v[234:235], v[234:235], v[232:233] neg_lo:[0,1] neg_hi:[0,1]
	v_pk_mul_f32 v[230:231], v[230:231], v[238:239] op_sel_hi:[1,0]
	v_pk_fma_f32 v[232:233], v[176:177], v[234:235], v[232:233]
	v_pk_fma_f32 v[230:231], v[144:145], v[230:231], v[160:161]
	v_pk_fma_f32 v[230:231], v[244:245], v[232:233], v[230:231] op_sel_hi:[0,1,1]
	v_pk_mul_f32 v[126:127], v[126:127], v[230:231]
	v_cvt_pk_bf16_f32 v120, v120, v121
	v_cvt_pk_bf16_f32 v121, v122, v123
	v_cvt_pk_bf16_f32 v122, v124, v125
	v_cvt_pk_bf16_f32 v123, v126, v127
	global_store_dwordx4 v243, v[120:123], s[22:23] offset:192
	s_branch .Lpo_done
; __device__ __forceinline__ float bf2f(u16 h) { return __uint_as_float(((unsigned)h) << 16); }
; __device__ __forceinline__ float prevP(const Params& p, const u16* P, int row, int c) {
;   const int rp = row > 0 ? row - 1 : 0;
;   float v = bf2f(P[(size_t)rp * 2816 + 256 + c]);
;   const bool start = (row < NP) ? ((row & 2047) == 0) : (((row - NP) & 3) == 0);
;   if (start) v = (row < NP) ? 0.f : p.in[3][(size_t)((row - NP) >> 2) * 2560 + c];
;   return v;
; }
; template <int EPI> ...
;     ...
;         float o0 = bf2f(Y[(size_t)row * 1024 + 256 + ch0]);
;         float o1 = bf2f(Y[(size_t)row * 1024 + 256 + ch1]);
;         float mean = hsum32(o0 + o1) * (1.0f / 64.0f);
;         float d0 = o0 - mean, d1 = o1 - mean;
;         float var = hsum32(d0 * d0 + d1 * d1) * (1.0f / 64.0f);
;         float rstd = rsqrtf(var + 64e-5f);
;         float pv0 = bf2f(P[(size_t)row * 2816 + 256 + 1536 + ch0]);
;         float pv1 = bf2f(P[(size_t)row * 2816 + 256 + 1536 + ch1]);
;         float pp0 = prevP(p, P, row, 1536 + ch0), pp1 = prevP(p, P, row, 1536 + ch1);
;         float vv0 = pv0 + (pp0 - pv0) * mu0, vv1 = pv1 + (pp1 - pv1) * mu1;
;         float b = bs[((size_t)row * 12 + hh) * 4 + 2];
.Lpo_sample:
	s_sub_u32 s11, s6, 64
	s_lshl_b32 s11, s11, 6
	s_lshl_b32 s12, s4, 4
	s_add_u32 s11, s11, s12
	v_lshrrev_b32_e32 v243, 2, v248
	v_add_u32_e32 v243, s11, v243
	v_mul_u32_u24_e32 v243, 0x2800, v243
	v_add_u32_e32 v243, v243, v245
	v_add_u32_e32 v243, 0x1800, v243
	v_add_u32_e32 v246, 0x8000, v237
	v_add_u32_e32 v247, 0x16000, v239
	v_add_u32_e32 v230, 0xa000, v243
	global_load_dwordx4 v[218:221], v246, s[22:23] offset:0
	global_load_dwordx4 v[222:225], v247, s[96:97] offset:0
	global_load_dwordx4 v[218:221], v230, s[20:21] offset:0
	global_load_dwordx4 v[222:225], v230, s[20:21] offset:16
	global_load_dwordx4 v[218:221], v246, s[22:23] offset:64
	global_load_dwordx4 v[222:225], v247, s[96:97] offset:64
	global_load_dwordx4 v[218:221], v230, s[20:21] offset:128
	global_load_dwordx4 v[222:225], v230, s[20:21] offset:144
	v_add_u32_e32 v246, 0x10000, v237
	v_add_u32_e32 v247, 0x2c000, v239
	v_add_u32_e32 v230, 0x14000, v243
	global_load_dwordx4 v[218:221], v246, s[22:23] offset:0
	global_load_dwordx4 v[222:225], v247, s[96:97] offset:0
	global_load_dwordx4 v[218:221], v230, s[20:21] offset:0
	global_load_dwordx4 v[222:225], v230, s[20:21] offset:16
	global_load_dwordx4 v[218:221], v246, s[22:23] offset:64
	global_load_dwordx4 v[222:225], v247, s[96:97] offset:64
	global_load_dwordx4 v[218:221], v230, s[20:21] offset:128
	global_load_dwordx4 v[222:225], v230, s[20:21] offset:144
	v_add_u32_e32 v246, 0x18000, v237
	v_add_u32_e32 v247, 0x42000, v239
	v_add_u32_e32 v230, 0x1e000, v243
	global_load_dwordx4 v[218:221], v246, s[22:23] offset:0
	global_load_dwordx4 v[222:225], v247, s[96:97] offset:0
	global_load_dwordx4 v[218:221], v230, s[20:21] offset:0
	global_load_dwordx4 v[222:225], v230, s[20:21] offset:16
	global_load_dwordx4 v[218:221], v246, s[22:23] offset:64
	global_load_dwordx4 v[222:225], v247, s[96:97] offset:64
	global_load_dwordx4 v[218:221], v230, s[20:21] offset:128
	global_load_dwordx4 v[222:225], v230, s[20:21] offset:144
	v_add_u32_e32 v246, 0x0, v237
	v_add_u32_e32 v247, 0x0, v239
	v_add_u32_e32 v230, 0x0, v243
	global_load_dwordx4 v[218:221], v246, s[22:23] offset:128
	global_load_dwordx4 v[222:225], v247, s[96:97] offset:128
	global_load_dwordx4 v[218:221], v230, s[20:21] offset:256
	global_load_dwordx4 v[222:225], v230, s[20:21] offset:272
	global_load_dwordx4 v[218:221], v246, s[22:23] offset:192
	global_load_dwordx4 v[222:225], v247, s[96:97] offset:192
	global_load_dwordx4 v[218:221], v230, s[20:21] offset:384
	global_load_dwordx4 v[222:225], v230, s[20:21] offset:400
	v_add_u32_e32 v246, 0x8000, v237
	v_add_u32_e32 v247, 0x16000, v239
	v_add_u32_e32 v230, 0xa000, v243
	global_load_dwordx4 v[218:221], v246, s[22:23] offset:128
	global_load_dwordx4 v[222:225], v247, s[96:97] offset:128
	global_load_dwordx4 v[218:221], v230, s[20:21] offset:256
	global_load_dwordx4 v[222:225], v230, s[20:21] offset:272
	global_load_dwordx4 v[218:221], v246, s[22:23] offset:192
	global_load_dwordx4 v[222:225], v247, s[96:97] offset:192
	global_load_dwordx4 v[218:221], v230, s[20:21] offset:384
	global_load_dwordx4 v[222:225], v230, s[20:21] offset:400
	v_add_u32_e32 v246, 0x10000, v237
	v_add_u32_e32 v247, 0x2c000, v239
	v_add_u32_e32 v230, 0x14000, v243
	global_load_dwordx4 v[218:221], v246, s[22:23] offset:128
	global_load_dwordx4 v[222:225], v247, s[96:97] offset:128
	global_load_dwordx4 v[218:221], v230, s[20:21] offset:256
	global_load_dwordx4 v[222:225], v230, s[20:21] offset:272
	global_load_dwordx4 v[218:221], v246, s[22:23] offset:192
	global_load_dwordx4 v[222:225], v247, s[96:97] offset:192
	global_load_dwordx4 v[218:221], v230, s[20:21] offset:384
	global_load_dwordx4 v[222:225], v230, s[20:21] offset:400
	v_add_u32_e32 v246, 0x18000, v237
	v_add_u32_e32 v247, 0x42000, v239
	v_add_u32_e32 v230, 0x1e000, v243
	global_load_dwordx4 v[218:221], v246, s[22:23] offset:128
	global_load_dwordx4 v[222:225], v247, s[96:97] offset:128
	global_load_dwordx4 v[218:221], v230, s[20:21] offset:256
	global_load_dwordx4 v[222:225], v230, s[20:21] offset:272
	global_load_dwordx4 v[218:221], v246, s[22:23] offset:192
	global_load_dwordx4 v[222:225], v247, s[96:97] offset:192
	global_load_dwordx4 v[218:221], v230, s[20:21] offset:384
	global_load_dwordx4 v[222:225], v230, s[20:21] offset:400
	global_load_dwordx4 v[130:133], v245, s[2:3] offset:0
	global_load_dwordx4 v[134:137], v245, s[2:3] offset:16
	global_load_dwordx4 v[138:141], v245, s[2:3] offset:128
	global_load_dwordx4 v[142:145], v245, s[2:3] offset:144
	global_load_dwordx4 v[146:149], v245, s[16:17] offset:0
	global_load_dwordx4 v[150:153], v245, s[16:17] offset:16
	global_load_dwordx4 v[154:157], v245, s[16:17] offset:128
	global_load_dwordx4 v[158:161], v245, s[16:17] offset:144
	global_load_dwordx4 v[162:165], v245, s[0:1] offset:0
	global_load_dwordx4 v[166:169], v245, s[0:1] offset:16
	global_load_dwordx4 v[170:173], v245, s[0:1] offset:128
	global_load_dwordx4 v[174:177], v245, s[0:1] offset:144
	v_add_u32_e32 v246, 0x0, v237
	v_add_u32_e32 v247, 0x0, v239
	v_subrev_u32_e32 v230, 0x1600, v247
	global_load_dwordx4 v[178:181], v246, s[22:23] offset:0
	global_load_dwordx4 v[182:185], v246, s[22:23] offset:64
	global_load_dwordx4 v[186:189], v247, s[96:97] offset:0
	global_load_dwordx4 v[190:193], v247, s[96:97] offset:64
	global_load_dwordx4 v[194:197], v230, s[96:97] offset:0
	global_load_dwordx4 v[198:201], v230, s[96:97] offset:64
	v_add_u32_e32 v246, 0x0, v241
	s_nop 0
	global_load_dword v240, v246, s[96:97] offset:0
	v_add_u32_e32 v247, 0x0, v243
	global_load_dwordx4 v[202:205], v247, s[20:21] offset:0
	global_load_dwordx4 v[206:209], v247, s[20:21] offset:16
	global_load_dwordx4 v[210:213], v247, s[20:21] offset:128
	global_load_dwordx4 v[214:217], v247, s[20:21] offset:144
	s_waitcnt vmcnt(0)
; __device__ __forceinline__ float bf2f(u16 h) { return __uint_as_float(((unsigned)h) << 16); }
; __device__ __forceinline__ float prevP(const Params& p, const u16* P, int row, int c) {
;   const int rp = row > 0 ? row - 1 : 0;
;   float v = bf2f(P[(size_t)rp * 2816 + 256 + c]);
;   const bool start = (row < NP) ? ((row & 2047) == 0) : (((row - NP) & 3) == 0);
;   if (start) v = (row < NP) ? 0.f : p.in[3][(size_t)((row - NP) >> 2) * 2560 + c];
;   return v;
; }
; template <int EPI> ...
;     ...
;         float mean = hsum32(o0 + o1) * (1.0f / 64.0f);
;         float d0 = o0 - mean, d1 = o1 - mean;
;         float var = hsum32(d0 * d0 + d1 * d1) * (1.0f / 64.0f);
;         float rstd = rsqrtf(var + 64e-5f);
;         float pv0 = bf2f(P[(size_t)row * 2816 + 256 + 1536 + ch0]);
;         float pv1 = bf2f(P[(size_t)row * 2816 + 256 + 1536 + ch1]);
;         float pp0 = prevP(p, P, row, 1536 + ch0), pp1 = prevP(p, P, row, 1536 + ch1);
;         float vv0 = pv0 + (pp0 - pv0) * mu0, vv1 = pv1 + (pp1 - pv1) * mu1;
;         float b = bs[((size_t)row * 12 + hh) * 4 + 2];
;         float y0 = (d0 * rstd * gg0 + gb0 + b * vv0) * acc0[i];
;         float y1 = (d1 * rstd * gg1 + gb1 + b * vv1) * acc1[i];
	v_lshlrev_b32_e32 v232, 16, v178
	v_and_b32_e32 v233, 0xffff0000, v178
	v_lshlrev_b32_e32 v230, 16, v179
	v_and_b32_e32 v231, 0xffff0000, v179
	v_pk_add_f32 v[232:233], v[232:233], v[230:231]
	v_lshlrev_b32_e32 v230, 16, v180
	v_and_b32_e32 v231, 0xffff0000, v180
	v_pk_add_f32 v[232:233], v[232:233], v[230:231]
	v_lshlrev_b32_e32 v230, 16, v181
	v_and_b32_e32 v231, 0xffff0000, v181
	v_pk_add_f32 v[232:233], v[232:233], v[230:231]
	v_lshlrev_b32_e32 v230, 16, v182
	v_and_b32_e32 v231, 0xffff0000, v182
	v_pk_add_f32 v[232:233], v[232:233], v[230:231]
	v_lshlrev_b32_e32 v230, 16, v183
	v_and_b32_e32 v231, 0xffff0000, v183
	v_pk_add_f32 v[232:233], v[232:233], v[230:231]
	v_lshlrev_b32_e32 v230, 16, v184
	v_and_b32_e32 v231, 0xffff0000, v184
	v_pk_add_f32 v[232:233], v[232:233], v[230:231]
	v_lshlrev_b32_e32 v230, 16, v185
	v_and_b32_e32 v231, 0xffff0000, v185
	v_pk_add_f32 v[232:233], v[232:233], v[230:231]
	v_add_f32_e32 v232, v232, v233
	v_mov_b32_e32 v230, v232
	s_nop 1
	v_permlane16_swap_b32_e32 v230, v232
	v_add_f32_e32 v232, v232, v230
	v_mov_b32_e32 v230, v232
	s_nop 1
	v_permlane32_swap_b32_e32 v230, v232
	v_add_f32_e32 v232, v232, v230
	v_mul_f32_e32 v236, 0x3c800000, v232
	v_lshlrev_b32_e32 v230, 16, v178
	v_and_b32_e32 v231, 0xffff0000, v178
	v_pk_add_f32 v[230:231], v[230:231], v[236:237] op_sel_hi:[1,0] neg_lo:[0,1] neg_hi:[0,1]
	v_pk_mul_f32 v[232:233], v[230:231], v[230:231]
	v_lshlrev_b32_e32 v230, 16, v179
	v_and_b32_e32 v231, 0xffff0000, v179
	v_pk_add_f32 v[230:231], v[230:231], v[236:237] op_sel_hi:[1,0] neg_lo:[0,1] neg_hi:[0,1]
	v_pk_fma_f32 v[232:233], v[230:231], v[230:231], v[232:233]
	v_lshlrev_b32_e32 v230, 16, v180
	v_and_b32_e32 v231, 0xffff0000, v180
	v_pk_add_f32 v[230:231], v[230:231], v[236:237] op_sel_hi:[1,0] neg_lo:[0,1] neg_hi:[0,1]
	v_pk_fma_f32 v[232:233], v[230:231], v[230:231], v[232:233]
	v_lshlrev_b32_e32 v230, 16, v181
	v_and_b32_e32 v231, 0xffff0000, v181
	v_pk_add_f32 v[230:231], v[230:231], v[236:237] op_sel_hi:[1,0] neg_lo:[0,1] neg_hi:[0,1]
	v_pk_fma_f32 v[232:233], v[230:231], v[230:231], v[232:233]
	v_lshlrev_b32_e32 v230, 16, v182
	v_and_b32_e32 v231, 0xffff0000, v182
	v_pk_add_f32 v[230:231], v[230:231], v[236:237] op_sel_hi:[1,0] neg_lo:[0,1] neg_hi:[0,1]
	v_pk_fma_f32 v[232:233], v[230:231], v[230:231], v[232:233]
	v_lshlrev_b32_e32 v230, 16, v183
	v_and_b32_e32 v231, 0xffff0000, v183
	v_pk_add_f32 v[230:231], v[230:231], v[236:237] op_sel_hi:[1,0] neg_lo:[0,1] neg_hi:[0,1]
	v_pk_fma_f32 v[232:233], v[230:231], v[230:231], v[232:233]
	v_lshlrev_b32_e32 v230, 16, v184
	v_and_b32_e32 v231, 0xffff0000, v184
	v_pk_add_f32 v[230:231], v[230:231], v[236:237] op_sel_hi:[1,0] neg_lo:[0,1] neg_hi:[0,1]
	v_pk_fma_f32 v[232:233], v[230:231], v[230:231], v[232:233]
	v_lshlrev_b32_e32 v230, 16, v185
	v_and_b32_e32 v231, 0xffff0000, v185
	v_pk_add_f32 v[230:231], v[230:231], v[236:237] op_sel_hi:[1,0] neg_lo:[0,1] neg_hi:[0,1]
	v_pk_fma_f32 v[232:233], v[230:231], v[230:231], v[232:233]
	v_add_f32_e32 v232, v232, v233
	v_mov_b32_e32 v230, v232
	s_nop 1
	v_permlane16_swap_b32_e32 v230, v232
	v_add_f32_e32 v232, v232, v230
	v_mov_b32_e32 v230, v232
	s_nop 1
	v_permlane32_swap_b32_e32 v230, v232
	v_add_f32_e32 v232, v232, v230
	v_mov_b32_e32 v230, 0x3a27c5ac
	v_fmamk_f32 v232, v232, 0x3c800000, v230
	v_rsq_f32_e32 v238, v232
	v_and_b32_e32 v230, 3, v248
	v_cmp_eq_u32_e32 vcc, 0, v230
	s_nop 1
	v_lshlrev_b32_e32 v230, 16, v178
	v_and_b32_e32 v231, 0xffff0000, v178
	v_lshlrev_b32_e32 v232, 16, v186
	v_and_b32_e32 v233, 0xffff0000, v186
	v_lshlrev_b32_e32 v234, 16, v194
	v_and_b32_e32 v235, 0xffff0000, v194
	v_cndmask_b32_e32 v234, v234, v202, vcc
	v_cndmask_b32_e32 v235, v235, v203, vcc
	v_pk_add_f32 v[230:231], v[230:231], v[236:237] op_sel_hi:[1,0] neg_lo:[0,1] neg_hi:[0,1]
	v_pk_add_f32 v[234:235], v[234:235], v[232:233] neg_lo:[0,1] neg_hi:[0,1]
	v_pk_mul_f32 v[230:231], v[230:231], v[238:239] op_sel_hi:[1,0]
	v_pk_fma_f32 v[232:233], v[162:163], v[234:235], v[232:233]
	v_pk_fma_f32 v[230:231], v[130:131], v[230:231], v[146:147]
	v_pk_fma_f32 v[230:231], v[240:241], v[232:233], v[230:231] op_sel_hi:[0,1,1]
	v_pk_mul_f32 v[0:1], v[0:1], v[230:231]
	v_lshlrev_b32_e32 v230, 16, v179
	v_and_b32_e32 v231, 0xffff0000, v179
	v_lshlrev_b32_e32 v232, 16, v187
	v_and_b32_e32 v233, 0xffff0000, v187
	v_lshlrev_b32_e32 v234, 16, v195
	v_and_b32_e32 v235, 0xffff0000, v195
	v_cndmask_b32_e32 v234, v234, v204, vcc
	v_cndmask_b32_e32 v235, v235, v205, vcc
	v_pk_add_f32 v[230:231], v[230:231], v[236:237] op_sel_hi:[1,0] neg_lo:[0,1] neg_hi:[0,1]
	v_pk_add_f32 v[234:235], v[234:235], v[232:233] neg_lo:[0,1] neg_hi:[0,1]
	v_pk_mul_f32 v[230:231], v[230:231], v[238:239] op_sel_hi:[1,0]
	v_pk_fma_f32 v[232:233], v[164:165], v[234:235], v[232:233]
	v_pk_fma_f32 v[230:231], v[132:133], v[230:231], v[148:149]
	v_pk_fma_f32 v[230:231], v[240:241], v[232:233], v[230:231] op_sel_hi:[0,1,1]
	v_pk_mul_f32 v[2:3], v[2:3], v[230:231]
	v_lshlrev_b32_e32 v230, 16, v180
	v_and_b32_e32 v231, 0xffff0000, v180
	v_lshlrev_b32_e32 v232, 16, v188
	v_and_b32_e32 v233, 0xffff0000, v188
	v_lshlrev_b32_e32 v234, 16, v196
	v_and_b32_e32 v235, 0xffff0000, v196
	v_cndmask_b32_e32 v234, v234, v206, vcc
	v_cndmask_b32_e32 v235, v235, v207, vcc
	v_pk_add_f32 v[230:231], v[230:231], v[236:237] op_sel_hi:[1,0] neg_lo:[0,1] neg_hi:[0,1]
	v_pk_add_f32 v[234:235], v[234:235], v[232:233] neg_lo:[0,1] neg_hi:[0,1]
	v_pk_mul_f32 v[230:231], v[230:231], v[238:239] op_sel_hi:[1,0]
	v_pk_fma_f32 v[232:233], v[166:167], v[234:235], v[232:233]
	v_pk_fma_f32 v[230:231], v[134:135], v[230:231], v[150:151]
	v_pk_fma_f32 v[230:231], v[240:241], v[232:233], v[230:231] op_sel_hi:[0,1,1]
; template <int EPI> ...
;     ...
;         float pp0 = prevP(p, P, row, 1536 + ch0), pp1 = prevP(p, P, row, 1536 + ch1);
;         float vv0 = pv0 + (pp0 - pv0) * mu0, vv1 = pv1 + (pp1 - pv1) * mu1;
;         float b = bs[((size_t)row * 12 + hh) * 4 + 2];
;         float y0 = (d0 * rstd * gg0 + gb0 + b * vv0) * acc0[i];
;         float y1 = (d1 * rstd * gg1 + gb1 + b * vv1) * acc1[i];
;         Y[(size_t)row * 1024 + 256 + ch0] = f2bf(y0);
;         Y[(size_t)row * 1024 + 256 + ch1] = f2bf(y1);
	v_pk_mul_f32 v[4:5], v[4:5], v[230:231]
	v_lshlrev_b32_e32 v230, 16, v181
	v_and_b32_e32 v231, 0xffff0000, v181
	v_lshlrev_b32_e32 v232, 16, v189
	v_and_b32_e32 v233, 0xffff0000, v189
	v_lshlrev_b32_e32 v234, 16, v197
	v_and_b32_e32 v235, 0xffff0000, v197
	v_cndmask_b32_e32 v234, v234, v208, vcc
	v_cndmask_b32_e32 v235, v235, v209, vcc
	v_pk_add_f32 v[230:231], v[230:231], v[236:237] op_sel_hi:[1,0] neg_lo:[0,1] neg_hi:[0,1]
	v_pk_add_f32 v[234:235], v[234:235], v[232:233] neg_lo:[0,1] neg_hi:[0,1]
	v_pk_mul_f32 v[230:231], v[230:231], v[238:239] op_sel_hi:[1,0]
	v_pk_fma_f32 v[232:233], v[168:169], v[234:235], v[232:233]
	v_pk_fma_f32 v[230:231], v[136:137], v[230:231], v[152:153]
	v_pk_fma_f32 v[230:231], v[240:241], v[232:233], v[230:231] op_sel_hi:[0,1,1]
	v_pk_mul_f32 v[6:7], v[6:7], v[230:231]
	v_cvt_pk_bf16_f32 v0, v0, v1
	v_cvt_pk_bf16_f32 v1, v2, v3
	v_cvt_pk_bf16_f32 v2, v4, v5
	v_cvt_pk_bf16_f32 v3, v6, v7
	v_add_u32_e32 v246, 0x0, v237
	s_nop 0
	global_store_dwordx4 v246, v[0:3], s[22:23] offset:0
	v_lshlrev_b32_e32 v230, 16, v182
	v_and_b32_e32 v231, 0xffff0000, v182
	v_lshlrev_b32_e32 v232, 16, v190
	v_and_b32_e32 v233, 0xffff0000, v190
	v_lshlrev_b32_e32 v234, 16, v198
	v_and_b32_e32 v235, 0xffff0000, v198
	v_cndmask_b32_e32 v234, v234, v210, vcc
	v_cndmask_b32_e32 v235, v235, v211, vcc
	v_pk_add_f32 v[230:231], v[230:231], v[236:237] op_sel_hi:[1,0] neg_lo:[0,1] neg_hi:[0,1]
	v_pk_add_f32 v[234:235], v[234:235], v[232:233] neg_lo:[0,1] neg_hi:[0,1]
	v_pk_mul_f32 v[230:231], v[230:231], v[238:239] op_sel_hi:[1,0]
	v_pk_fma_f32 v[232:233], v[170:171], v[234:235], v[232:233]
	v_pk_fma_f32 v[230:231], v[138:139], v[230:231], v[154:155]
	v_pk_fma_f32 v[230:231], v[240:241], v[232:233], v[230:231] op_sel_hi:[0,1,1]
	v_pk_mul_f32 v[8:9], v[8:9], v[230:231]
	v_lshlrev_b32_e32 v230, 16, v183
	v_and_b32_e32 v231, 0xffff0000, v183
	v_lshlrev_b32_e32 v232, 16, v191
	v_and_b32_e32 v233, 0xffff0000, v191
	v_lshlrev_b32_e32 v234, 16, v199
	v_and_b32_e32 v235, 0xffff0000, v199
	v_cndmask_b32_e32 v234, v234, v212, vcc
	v_cndmask_b32_e32 v235, v235, v213, vcc
	v_pk_add_f32 v[230:231], v[230:231], v[236:237] op_sel_hi:[1,0] neg_lo:[0,1] neg_hi:[0,1]
	v_pk_add_f32 v[234:235], v[234:235], v[232:233] neg_lo:[0,1] neg_hi:[0,1]
	v_pk_mul_f32 v[230:231], v[230:231], v[238:239] op_sel_hi:[1,0]
	v_pk_fma_f32 v[232:233], v[172:173], v[234:235], v[232:233]
	v_pk_fma_f32 v[230:231], v[140:141], v[230:231], v[156:157]
	v_pk_fma_f32 v[230:231], v[240:241], v[232:233], v[230:231] op_sel_hi:[0,1,1]
	v_pk_mul_f32 v[10:11], v[10:11], v[230:231]
	v_lshlrev_b32_e32 v230, 16, v184
	v_and_b32_e32 v231, 0xffff0000, v184
	v_lshlrev_b32_e32 v232, 16, v192
	v_and_b32_e32 v233, 0xffff0000, v192
	v_lshlrev_b32_e32 v234, 16, v200
	v_and_b32_e32 v235, 0xffff0000, v200
	v_cndmask_b32_e32 v234, v234, v214, vcc
	v_cndmask_b32_e32 v235, v235, v215, vcc
	v_pk_add_f32 v[230:231], v[230:231], v[236:237] op_sel_hi:[1,0] neg_lo:[0,1] neg_hi:[0,1]
	v_pk_add_f32 v[234:235], v[234:235], v[232:233] neg_lo:[0,1] neg_hi:[0,1]
	v_pk_mul_f32 v[230:231], v[230:231], v[238:239] op_sel_hi:[1,0]
	v_pk_fma_f32 v[232:233], v[174:175], v[234:235], v[232:233]
	v_pk_fma_f32 v[230:231], v[142:143], v[230:231], v[158:159]
	v_pk_fma_f32 v[230:231], v[240:241], v[232:233], v[230:231] op_sel_hi:[0,1,1]
	v_pk_mul_f32 v[12:13], v[12:13], v[230:231]
	v_lshlrev_b32_e32 v230, 16, v185
	v_and_b32_e32 v231, 0xffff0000, v185
	v_lshlrev_b32_e32 v232, 16, v193
	v_and_b32_e32 v233, 0xffff0000, v193
	v_lshlrev_b32_e32 v234, 16, v201
	v_and_b32_e32 v235, 0xffff0000, v201
	v_cndmask_b32_e32 v234, v234, v216, vcc
	v_cndmask_b32_e32 v235, v235, v217, vcc
	v_pk_add_f32 v[230:231], v[230:231], v[236:237] op_sel_hi:[1,0] neg_lo:[0,1] neg_hi:[0,1]
	v_pk_add_f32 v[234:235], v[234:235], v[232:233] neg_lo:[0,1] neg_hi:[0,1]
	v_pk_mul_f32 v[230:231], v[230:231], v[238:239] op_sel_hi:[1,0]
	v_pk_fma_f32 v[232:233], v[176:177], v[234:235], v[232:233]
	v_pk_fma_f32 v[230:231], v[144:145], v[230:231], v[160:161]
	v_pk_fma_f32 v[230:231], v[240:241], v[232:233], v[230:231] op_sel_hi:[0,1,1]
	v_pk_mul_f32 v[14:15], v[14:15], v[230:231]
	v_cvt_pk_bf16_f32 v8, v8, v9
	v_cvt_pk_bf16_f32 v9, v10, v11
	v_cvt_pk_bf16_f32 v10, v12, v13
	v_cvt_pk_bf16_f32 v11, v14, v15
	v_add_u32_e32 v246, 0x0, v237
	s_nop 0
	global_store_dwordx4 v246, v[8:11], s[22:23] offset:64
	v_add_u32_e32 v246, 0x8000, v237
	v_add_u32_e32 v247, 0x16000, v239
	v_subrev_u32_e32 v230, 0x1600, v247
	global_load_dwordx4 v[178:181], v246, s[22:23] offset:0
	global_load_dwordx4 v[182:185], v246, s[22:23] offset:64
	global_load_dwordx4 v[186:189], v247, s[96:97] offset:0
	global_load_dwordx4 v[190:193], v247, s[96:97] offset:64
	global_load_dwordx4 v[194:197], v230, s[96:97] offset:0
	global_load_dwordx4 v[198:201], v230, s[96:97] offset:64
	v_add_u32_e32 v246, 0xc00, v241
	s_nop 0
	global_load_dword v240, v246, s[96:97] offset:0
	v_add_u32_e32 v247, 0xa000, v243
	global_load_dwordx4 v[202:205], v247, s[20:21] offset:0
	global_load_dwordx4 v[206:209], v247, s[20:21] offset:16
	global_load_dwordx4 v[210:213], v247, s[20:21] offset:128
	global_load_dwordx4 v[214:217], v247, s[20:21] offset:144
	s_waitcnt vmcnt(0)
; __device__ __forceinline__ float bf2f(u16 h) { return __uint_as_float(((unsigned)h) << 16); }
; template <int EPI> ...
;     ...
;         float o0 = bf2f(Y[(size_t)row * 1024 + 256 + ch0]);
;         float o1 = bf2f(Y[(size_t)row * 1024 + 256 + ch1]);
;         float mean = hsum32(o0 + o1) * (1.0f / 64.0f);
;         float d0 = o0 - mean, d1 = o1 - mean;
;         float var = hsum32(d0 * d0 + d1 * d1) * (1.0f / 64.0f);
;         float rstd = rsqrtf(var + 64e-5f);
;         float pv0 = bf2f(P[(size_t)row * 2816 + 256 + 1536 + ch0]);
;         float pv1 = bf2f(P[(size_t)row * 2816 + 256 + 1536 + ch1]);
;         float pp0 = prevP(p, P, row, 1536 + ch0), pp1 = prevP(p, P, row, 1536 + ch1);
;         float vv0 = pv0 + (pp0 - pv0) * mu0, vv1 = pv1 + (pp1 - pv1) * mu1;
;         float b = bs[((size_t)row * 12 + hh) * 4 + 2];
;         float y0 = (d0 * rstd * gg0 + gb0 + b * vv0) * acc0[i];
;         float y1 = (d1 * rstd * gg1 + gb1 + b * vv1) * acc1[i];
	v_lshlrev_b32_e32 v232, 16, v178
	v_and_b32_e32 v233, 0xffff0000, v178
	v_lshlrev_b32_e32 v230, 16, v179
	v_and_b32_e32 v231, 0xffff0000, v179
	v_pk_add_f32 v[232:233], v[232:233], v[230:231]
	v_lshlrev_b32_e32 v230, 16, v180
	v_and_b32_e32 v231, 0xffff0000, v180
	v_pk_add_f32 v[232:233], v[232:233], v[230:231]
	v_lshlrev_b32_e32 v230, 16, v181
	v_and_b32_e32 v231, 0xffff0000, v181
	v_pk_add_f32 v[232:233], v[232:233], v[230:231]
	v_lshlrev_b32_e32 v230, 16, v182
	v_and_b32_e32 v231, 0xffff0000, v182
	v_pk_add_f32 v[232:233], v[232:233], v[230:231]
	v_lshlrev_b32_e32 v230, 16, v183
	v_and_b32_e32 v231, 0xffff0000, v183
	v_pk_add_f32 v[232:233], v[232:233], v[230:231]
	v_lshlrev_b32_e32 v230, 16, v184
	v_and_b32_e32 v231, 0xffff0000, v184
	v_pk_add_f32 v[232:233], v[232:233], v[230:231]
	v_lshlrev_b32_e32 v230, 16, v185
	v_and_b32_e32 v231, 0xffff0000, v185
	v_pk_add_f32 v[232:233], v[232:233], v[230:231]
	v_add_f32_e32 v232, v232, v233
	v_mov_b32_e32 v230, v232
	s_nop 1
	v_permlane16_swap_b32_e32 v230, v232
	v_add_f32_e32 v232, v232, v230
	v_mov_b32_e32 v230, v232
	s_nop 1
	v_permlane32_swap_b32_e32 v230, v232
	v_add_f32_e32 v232, v232, v230
	v_mul_f32_e32 v236, 0x3c800000, v232
	v_lshlrev_b32_e32 v230, 16, v178
	v_and_b32_e32 v231, 0xffff0000, v178
	v_pk_add_f32 v[230:231], v[230:231], v[236:237] op_sel_hi:[1,0] neg_lo:[0,1] neg_hi:[0,1]
	v_pk_mul_f32 v[232:233], v[230:231], v[230:231]
	v_lshlrev_b32_e32 v230, 16, v179
	v_and_b32_e32 v231, 0xffff0000, v179
	v_pk_add_f32 v[230:231], v[230:231], v[236:237] op_sel_hi:[1,0] neg_lo:[0,1] neg_hi:[0,1]
	v_pk_fma_f32 v[232:233], v[230:231], v[230:231], v[232:233]
	v_lshlrev_b32_e32 v230, 16, v180
	v_and_b32_e32 v231, 0xffff0000, v180
	v_pk_add_f32 v[230:231], v[230:231], v[236:237] op_sel_hi:[1,0] neg_lo:[0,1] neg_hi:[0,1]
	v_pk_fma_f32 v[232:233], v[230:231], v[230:231], v[232:233]
	v_lshlrev_b32_e32 v230, 16, v181
	v_and_b32_e32 v231, 0xffff0000, v181
	v_pk_add_f32 v[230:231], v[230:231], v[236:237] op_sel_hi:[1,0] neg_lo:[0,1] neg_hi:[0,1]
	v_pk_fma_f32 v[232:233], v[230:231], v[230:231], v[232:233]
	v_lshlrev_b32_e32 v230, 16, v182
	v_and_b32_e32 v231, 0xffff0000, v182
	v_pk_add_f32 v[230:231], v[230:231], v[236:237] op_sel_hi:[1,0] neg_lo:[0,1] neg_hi:[0,1]
	v_pk_fma_f32 v[232:233], v[230:231], v[230:231], v[232:233]
	v_lshlrev_b32_e32 v230, 16, v183
	v_and_b32_e32 v231, 0xffff0000, v183
	v_pk_add_f32 v[230:231], v[230:231], v[236:237] op_sel_hi:[1,0] neg_lo:[0,1] neg_hi:[0,1]
	v_pk_fma_f32 v[232:233], v[230:231], v[230:231], v[232:233]
	v_lshlrev_b32_e32 v230, 16, v184
	v_and_b32_e32 v231, 0xffff0000, v184
	v_pk_add_f32 v[230:231], v[230:231], v[236:237] op_sel_hi:[1,0] neg_lo:[0,1] neg_hi:[0,1]
	v_pk_fma_f32 v[232:233], v[230:231], v[230:231], v[232:233]
	v_lshlrev_b32_e32 v230, 16, v185
	v_and_b32_e32 v231, 0xffff0000, v185
	v_pk_add_f32 v[230:231], v[230:231], v[236:237] op_sel_hi:[1,0] neg_lo:[0,1] neg_hi:[0,1]
	v_pk_fma_f32 v[232:233], v[230:231], v[230:231], v[232:233]
	v_add_f32_e32 v232, v232, v233
	v_mov_b32_e32 v230, v232
	s_nop 1
	v_permlane16_swap_b32_e32 v230, v232
	v_add_f32_e32 v232, v232, v230
	v_mov_b32_e32 v230, v232
	s_nop 1
	v_permlane32_swap_b32_e32 v230, v232
	v_add_f32_e32 v232, v232, v230
	v_mov_b32_e32 v230, 0x3a27c5ac
	v_fmamk_f32 v232, v232, 0x3c800000, v230
	v_rsq_f32_e32 v238, v232
	v_and_b32_e32 v230, 3, v248
	v_cmp_eq_u32_e32 vcc, 0, v230
	s_nop 1
	v_lshlrev_b32_e32 v230, 16, v178
	v_and_b32_e32 v231, 0xffff0000, v178
	v_lshlrev_b32_e32 v232, 16, v186
	v_and_b32_e32 v233, 0xffff0000, v186
	v_lshlrev_b32_e32 v234, 16, v194
	v_and_b32_e32 v235, 0xffff0000, v194
	v_cndmask_b32_e32 v234, v234, v202, vcc
	v_cndmask_b32_e32 v235, v235, v203, vcc
	v_pk_add_f32 v[230:231], v[230:231], v[236:237] op_sel_hi:[1,0] neg_lo:[0,1] neg_hi:[0,1]
	v_pk_add_f32 v[234:235], v[234:235], v[232:233] neg_lo:[0,1] neg_hi:[0,1]
	v_pk_mul_f32 v[230:231], v[230:231], v[238:239] op_sel_hi:[1,0]
	v_pk_fma_f32 v[232:233], v[162:163], v[234:235], v[232:233]
	v_pk_fma_f32 v[230:231], v[130:131], v[230:231], v[146:147]
	v_pk_fma_f32 v[230:231], v[240:241], v[232:233], v[230:231] op_sel_hi:[0,1,1]
	v_pk_mul_f32 v[32:33], v[32:33], v[230:231]
	v_lshlrev_b32_e32 v230, 16, v179
	v_and_b32_e32 v231, 0xffff0000, v179
	v_lshlrev_b32_e32 v232, 16, v187
	v_and_b32_e32 v233, 0xffff0000, v187
	v_lshlrev_b32_e32 v234, 16, v195
	v_and_b32_e32 v235, 0xffff0000, v195
	v_cndmask_b32_e32 v234, v234, v204, vcc
	v_cndmask_b32_e32 v235, v235, v205, vcc
	v_pk_add_f32 v[230:231], v[230:231], v[236:237] op_sel_hi:[1,0] neg_lo:[0,1] neg_hi:[0,1]
	v_pk_add_f32 v[234:235], v[234:235], v[232:233] neg_lo:[0,1] neg_hi:[0,1]
	v_pk_mul_f32 v[230:231], v[230:231], v[238:239] op_sel_hi:[1,0]
	v_pk_fma_f32 v[232:233], v[164:165], v[234:235], v[232:233]
	v_pk_fma_f32 v[230:231], v[132:133], v[230:231], v[148:149]
	v_pk_fma_f32 v[230:231], v[240:241], v[232:233], v[230:231] op_sel_hi:[0,1,1]
	v_pk_mul_f32 v[34:35], v[34:35], v[230:231]
	v_lshlrev_b32_e32 v230, 16, v180
	v_and_b32_e32 v231, 0xffff0000, v180
	v_lshlrev_b32_e32 v232, 16, v188
	v_and_b32_e32 v233, 0xffff0000, v188
	v_lshlrev_b32_e32 v234, 16, v196
	v_and_b32_e32 v235, 0xffff0000, v196
	v_cndmask_b32_e32 v234, v234, v206, vcc
	v_cndmask_b32_e32 v235, v235, v207, vcc
	v_pk_add_f32 v[230:231], v[230:231], v[236:237] op_sel_hi:[1,0] neg_lo:[0,1] neg_hi:[0,1]
	v_pk_add_f32 v[234:235], v[234:235], v[232:233] neg_lo:[0,1] neg_hi:[0,1]
	v_pk_mul_f32 v[230:231], v[230:231], v[238:239] op_sel_hi:[1,0]
	v_pk_fma_f32 v[232:233], v[166:167], v[234:235], v[232:233]
	v_pk_fma_f32 v[230:231], v[134:135], v[230:231], v[150:151]
	v_pk_fma_f32 v[230:231], v[240:241], v[232:233], v[230:231] op_sel_hi:[0,1,1]
; template <int EPI> ...
;     ...
;         float pp0 = prevP(p, P, row, 1536 + ch0), pp1 = prevP(p, P, row, 1536 + ch1);
;         float vv0 = pv0 + (pp0 - pv0) * mu0, vv1 = pv1 + (pp1 - pv1) * mu1;
;         float b = bs[((size_t)row * 12 + hh) * 4 + 2];
;         float y0 = (d0 * rstd * gg0 + gb0 + b * vv0) * acc0[i];
;         float y1 = (d1 * rstd * gg1 + gb1 + b * vv1) * acc1[i];
;         Y[(size_t)row * 1024 + 256 + ch0] = f2bf(y0);
;         Y[(size_t)row * 1024 + 256 + ch1] = f2bf(y1);
	v_pk_mul_f32 v[36:37], v[36:37], v[230:231]
	v_lshlrev_b32_e32 v230, 16, v181
	v_and_b32_e32 v231, 0xffff0000, v181
	v_lshlrev_b32_e32 v232, 16, v189
	v_and_b32_e32 v233, 0xffff0000, v189
	v_lshlrev_b32_e32 v234, 16, v197
	v_and_b32_e32 v235, 0xffff0000, v197
	v_cndmask_b32_e32 v234, v234, v208, vcc
	v_cndmask_b32_e32 v235, v235, v209, vcc
	v_pk_add_f32 v[230:231], v[230:231], v[236:237] op_sel_hi:[1,0] neg_lo:[0,1] neg_hi:[0,1]
	v_pk_add_f32 v[234:235], v[234:235], v[232:233] neg_lo:[0,1] neg_hi:[0,1]
	v_pk_mul_f32 v[230:231], v[230:231], v[238:239] op_sel_hi:[1,0]
	v_pk_fma_f32 v[232:233], v[168:169], v[234:235], v[232:233]
	v_pk_fma_f32 v[230:231], v[136:137], v[230:231], v[152:153]
	v_pk_fma_f32 v[230:231], v[240:241], v[232:233], v[230:231] op_sel_hi:[0,1,1]
	v_pk_mul_f32 v[38:39], v[38:39], v[230:231]
	v_cvt_pk_bf16_f32 v32, v32, v33
	v_cvt_pk_bf16_f32 v33, v34, v35
	v_cvt_pk_bf16_f32 v34, v36, v37
	v_cvt_pk_bf16_f32 v35, v38, v39
	v_add_u32_e32 v246, 0x8000, v237
	s_nop 0
	global_store_dwordx4 v246, v[32:35], s[22:23] offset:0
	v_lshlrev_b32_e32 v230, 16, v182
	v_and_b32_e32 v231, 0xffff0000, v182
	v_lshlrev_b32_e32 v232, 16, v190
	v_and_b32_e32 v233, 0xffff0000, v190
	v_lshlrev_b32_e32 v234, 16, v198
	v_and_b32_e32 v235, 0xffff0000, v198
	v_cndmask_b32_e32 v234, v234, v210, vcc
	v_cndmask_b32_e32 v235, v235, v211, vcc
	v_pk_add_f32 v[230:231], v[230:231], v[236:237] op_sel_hi:[1,0] neg_lo:[0,1] neg_hi:[0,1]
	v_pk_add_f32 v[234:235], v[234:235], v[232:233] neg_lo:[0,1] neg_hi:[0,1]
	v_pk_mul_f32 v[230:231], v[230:231], v[238:239] op_sel_hi:[1,0]
	v_pk_fma_f32 v[232:233], v[170:171], v[234:235], v[232:233]
	v_pk_fma_f32 v[230:231], v[138:139], v[230:231], v[154:155]
	v_pk_fma_f32 v[230:231], v[240:241], v[232:233], v[230:231] op_sel_hi:[0,1,1]
	v_pk_mul_f32 v[40:41], v[40:41], v[230:231]
	v_lshlrev_b32_e32 v230, 16, v183
	v_and_b32_e32 v231, 0xffff0000, v183
	v_lshlrev_b32_e32 v232, 16, v191
	v_and_b32_e32 v233, 0xffff0000, v191
	v_lshlrev_b32_e32 v234, 16, v199
	v_and_b32_e32 v235, 0xffff0000, v199
	v_cndmask_b32_e32 v234, v234, v212, vcc
	v_cndmask_b32_e32 v235, v235, v213, vcc
	v_pk_add_f32 v[230:231], v[230:231], v[236:237] op_sel_hi:[1,0] neg_lo:[0,1] neg_hi:[0,1]
	v_pk_add_f32 v[234:235], v[234:235], v[232:233] neg_lo:[0,1] neg_hi:[0,1]
	v_pk_mul_f32 v[230:231], v[230:231], v[238:239] op_sel_hi:[1,0]
	v_pk_fma_f32 v[232:233], v[172:173], v[234:235], v[232:233]
	v_pk_fma_f32 v[230:231], v[140:141], v[230:231], v[156:157]
	v_pk_fma_f32 v[230:231], v[240:241], v[232:233], v[230:231] op_sel_hi:[0,1,1]
	v_pk_mul_f32 v[42:43], v[42:43], v[230:231]
	v_lshlrev_b32_e32 v230, 16, v184
	v_and_b32_e32 v231, 0xffff0000, v184
	v_lshlrev_b32_e32 v232, 16, v192
	v_and_b32_e32 v233, 0xffff0000, v192
	v_lshlrev_b32_e32 v234, 16, v200
	v_and_b32_e32 v235, 0xffff0000, v200
	v_cndmask_b32_e32 v234, v234, v214, vcc
	v_cndmask_b32_e32 v235, v235, v215, vcc
	v_pk_add_f32 v[230:231], v[230:231], v[236:237] op_sel_hi:[1,0] neg_lo:[0,1] neg_hi:[0,1]
	v_pk_add_f32 v[234:235], v[234:235], v[232:233] neg_lo:[0,1] neg_hi:[0,1]
	v_pk_mul_f32 v[230:231], v[230:231], v[238:239] op_sel_hi:[1,0]
	v_pk_fma_f32 v[232:233], v[174:175], v[234:235], v[232:233]
	v_pk_fma_f32 v[230:231], v[142:143], v[230:231], v[158:159]
	v_pk_fma_f32 v[230:231], v[240:241], v[232:233], v[230:231] op_sel_hi:[0,1,1]
	v_pk_mul_f32 v[44:45], v[44:45], v[230:231]
	v_lshlrev_b32_e32 v230, 16, v185
	v_and_b32_e32 v231, 0xffff0000, v185
	v_lshlrev_b32_e32 v232, 16, v193
	v_and_b32_e32 v233, 0xffff0000, v193
	v_lshlrev_b32_e32 v234, 16, v201
	v_and_b32_e32 v235, 0xffff0000, v201
	v_cndmask_b32_e32 v234, v234, v216, vcc
	v_cndmask_b32_e32 v235, v235, v217, vcc
	v_pk_add_f32 v[230:231], v[230:231], v[236:237] op_sel_hi:[1,0] neg_lo:[0,1] neg_hi:[0,1]
	v_pk_add_f32 v[234:235], v[234:235], v[232:233] neg_lo:[0,1] neg_hi:[0,1]
	v_pk_mul_f32 v[230:231], v[230:231], v[238:239] op_sel_hi:[1,0]
	v_pk_fma_f32 v[232:233], v[176:177], v[234:235], v[232:233]
	v_pk_fma_f32 v[230:231], v[144:145], v[230:231], v[160:161]
	v_pk_fma_f32 v[230:231], v[240:241], v[232:233], v[230:231] op_sel_hi:[0,1,1]
	v_pk_mul_f32 v[46:47], v[46:47], v[230:231]
	v_cvt_pk_bf16_f32 v40, v40, v41
	v_cvt_pk_bf16_f32 v41, v42, v43
	v_cvt_pk_bf16_f32 v42, v44, v45
	v_cvt_pk_bf16_f32 v43, v46, v47
	v_add_u32_e32 v246, 0x8000, v237
	s_nop 0
	global_store_dwordx4 v246, v[40:43], s[22:23] offset:64
	v_add_u32_e32 v246, 0x10000, v237
	v_add_u32_e32 v247, 0x2c000, v239
	v_subrev_u32_e32 v230, 0x1600, v247
	global_load_dwordx4 v[178:181], v246, s[22:23] offset:0
	global_load_dwordx4 v[182:185], v246, s[22:23] offset:64
	global_load_dwordx4 v[186:189], v247, s[96:97] offset:0
	global_load_dwordx4 v[190:193], v247, s[96:97] offset:64
	global_load_dwordx4 v[194:197], v230, s[96:97] offset:0
	global_load_dwordx4 v[198:201], v230, s[96:97] offset:64
	v_add_u32_e32 v246, 0x1800, v241
	s_nop 0
	global_load_dword v240, v246, s[96:97] offset:0
	v_add_u32_e32 v247, 0x14000, v243
	global_load_dwordx4 v[202:205], v247, s[20:21] offset:0
	global_load_dwordx4 v[206:209], v247, s[20:21] offset:16
	global_load_dwordx4 v[210:213], v247, s[20:21] offset:128
	global_load_dwordx4 v[214:217], v247, s[20:21] offset:144
	s_waitcnt vmcnt(0)
; __device__ __forceinline__ float bf2f(u16 h) { return __uint_as_float(((unsigned)h) << 16); }
; template <int EPI> ...
;     ...
; #pragma unroll 16
;       for (int i = 0; i < 16; i++) {
;         const int rl = rbase + (i & 3) + 8 * (i >> 2);
;         const int row = m0 + rl;
;         float o0 = bf2f(Y[(size_t)row * 1024 + 256 + ch0]);
;         float o1 = bf2f(Y[(size_t)row * 1024 + 256 + ch1]);
;         float mean = hsum32(o0 + o1) * (1.0f / 64.0f);
;         float d0 = o0 - mean, d1 = o1 - mean;
;         float var = hsum32(d0 * d0 + d1 * d1) * (1.0f / 64.0f);
;         float rstd = rsqrtf(var + 64e-5f);
;         float pv0 = bf2f(P[(size_t)row * 2816 + 256 + 1536 + ch0]);
;         float pv1 = bf2f(P[(size_t)row * 2816 + 256 + 1536 + ch1]);
;         float pp0 = prevP(p, P, row, 1536 + ch0), pp1 = prevP(p, P, row, 1536 + ch1);
;         float vv0 = pv0 + (pp0 - pv0) * mu0, vv1 = pv1 + (pp1 - pv1) * mu1;
;         float b = bs[((size_t)row * 12 + hh) * 4 + 2];
;         float y0 = (d0 * rstd * gg0 + gb0 + b * vv0) * acc0[i];
;         float y1 = (d1 * rstd * gg1 + gb1 + b * vv1) * acc1[i];
;         Y[(size_t)row * 1024 + 256 + ch0] = f2bf(y0);
;         Y[(size_t)row * 1024 + 256 + ch1] = f2bf(y1);
;       }
	v_lshlrev_b32_e32 v232, 16, v178
	v_and_b32_e32 v233, 0xffff0000, v178
	v_lshlrev_b32_e32 v230, 16, v179
	v_and_b32_e32 v231, 0xffff0000, v179
	v_pk_add_f32 v[232:233], v[232:233], v[230:231]
	v_lshlrev_b32_e32 v230, 16, v180
	v_and_b32_e32 v231, 0xffff0000, v180
	v_pk_add_f32 v[232:233], v[232:233], v[230:231]
	v_lshlrev_b32_e32 v230, 16, v181
	v_and_b32_e32 v231, 0xffff0000, v181
	v_pk_add_f32 v[232:233], v[232:233], v[230:231]
	v_lshlrev_b32_e32 v230, 16, v182
	v_and_b32_e32 v231, 0xffff0000, v182
	v_pk_add_f32 v[232:233], v[232:233], v[230:231]
	v_lshlrev_b32_e32 v230, 16, v183
	v_and_b32_e32 v231, 0xffff0000, v183
	v_pk_add_f32 v[232:233], v[232:233], v[230:231]
	v_lshlrev_b32_e32 v230, 16, v184
	v_and_b32_e32 v231, 0xffff0000, v184
	v_pk_add_f32 v[232:233], v[232:233], v[230:231]
	v_lshlrev_b32_e32 v230, 16, v185
	v_and_b32_e32 v231, 0xffff0000, v185
	v_pk_add_f32 v[232:233], v[232:233], v[230:231]
	v_add_f32_e32 v232, v232, v233
	v_mov_b32_e32 v230, v232
	s_nop 1
	v_permlane16_swap_b32_e32 v230, v232
	v_add_f32_e32 v232, v232, v230
	v_mov_b32_e32 v230, v232
	s_nop 1
	v_permlane32_swap_b32_e32 v230, v232
	v_add_f32_e32 v232, v232, v230
	v_mul_f32_e32 v236, 0x3c800000, v232
	v_lshlrev_b32_e32 v230, 16, v178
	v_and_b32_e32 v231, 0xffff0000, v178
	v_pk_add_f32 v[230:231], v[230:231], v[236:237] op_sel_hi:[1,0] neg_lo:[0,1] neg_hi:[0,1]
	v_pk_mul_f32 v[232:233], v[230:231], v[230:231]
	v_lshlrev_b32_e32 v230, 16, v179
	v_and_b32_e32 v231, 0xffff0000, v179
	v_pk_add_f32 v[230:231], v[230:231], v[236:237] op_sel_hi:[1,0] neg_lo:[0,1] neg_hi:[0,1]
	v_pk_fma_f32 v[232:233], v[230:231], v[230:231], v[232:233]
	v_lshlrev_b32_e32 v230, 16, v180
	v_and_b32_e32 v231, 0xffff0000, v180
	v_pk_add_f32 v[230:231], v[230:231], v[236:237] op_sel_hi:[1,0] neg_lo:[0,1] neg_hi:[0,1]
	v_pk_fma_f32 v[232:233], v[230:231], v[230:231], v[232:233]
	v_lshlrev_b32_e32 v230, 16, v181
	v_and_b32_e32 v231, 0xffff0000, v181
	v_pk_add_f32 v[230:231], v[230:231], v[236:237] op_sel_hi:[1,0] neg_lo:[0,1] neg_hi:[0,1]
	v_pk_fma_f32 v[232:233], v[230:231], v[230:231], v[232:233]
	v_lshlrev_b32_e32 v230, 16, v182
	v_and_b32_e32 v231, 0xffff0000, v182
	v_pk_add_f32 v[230:231], v[230:231], v[236:237] op_sel_hi:[1,0] neg_lo:[0,1] neg_hi:[0,1]
	v_pk_fma_f32 v[232:233], v[230:231], v[230:231], v[232:233]
	v_lshlrev_b32_e32 v230, 16, v183
	v_and_b32_e32 v231, 0xffff0000, v183
	v_pk_add_f32 v[230:231], v[230:231], v[236:237] op_sel_hi:[1,0] neg_lo:[0,1] neg_hi:[0,1]
	v_pk_fma_f32 v[232:233], v[230:231], v[230:231], v[232:233]
	v_lshlrev_b32_e32 v230, 16, v184
	v_and_b32_e32 v231, 0xffff0000, v184
	v_pk_add_f32 v[230:231], v[230:231], v[236:237] op_sel_hi:[1,0] neg_lo:[0,1] neg_hi:[0,1]
	v_pk_fma_f32 v[232:233], v[230:231], v[230:231], v[232:233]
	v_lshlrev_b32_e32 v230, 16, v185
	v_and_b32_e32 v231, 0xffff0000, v185
	v_pk_add_f32 v[230:231], v[230:231], v[236:237] op_sel_hi:[1,0] neg_lo:[0,1] neg_hi:[0,1]
	v_pk_fma_f32 v[232:233], v[230:231], v[230:231], v[232:233]
	v_add_f32_e32 v232, v232, v233
	v_mov_b32_e32 v230, v232
	s_nop 1
	v_permlane16_swap_b32_e32 v230, v232
	v_add_f32_e32 v232, v232, v230
	v_mov_b32_e32 v230, v232
	s_nop 1
	v_permlane32_swap_b32_e32 v230, v232
	v_add_f32_e32 v232, v232, v230
	v_mov_b32_e32 v230, 0x3a27c5ac
	v_fmamk_f32 v232, v232, 0x3c800000, v230
	v_rsq_f32_e32 v238, v232
	v_and_b32_e32 v230, 3, v248
	v_cmp_eq_u32_e32 vcc, 0, v230
	s_nop 1
	v_lshlrev_b32_e32 v230, 16, v178
	v_and_b32_e32 v231, 0xffff0000, v178
	v_lshlrev_b32_e32 v232, 16, v186
	v_and_b32_e32 v233, 0xffff0000, v186
	v_lshlrev_b32_e32 v234, 16, v194
	v_and_b32_e32 v235, 0xffff0000, v194
	v_cndmask_b32_e32 v234, v234, v202, vcc
	v_cndmask_b32_e32 v235, v235, v203, vcc
	v_pk_add_f32 v[230:231], v[230:231], v[236:237] op_sel_hi:[1,0] neg_lo:[0,1] neg_hi:[0,1]
	v_pk_add_f32 v[234:235], v[234:235], v[232:233] neg_lo:[0,1] neg_hi:[0,1]
	v_pk_mul_f32 v[230:231], v[230:231], v[238:239] op_sel_hi:[1,0]
	v_pk_fma_f32 v[232:233], v[162:163], v[234:235], v[232:233]
	v_pk_fma_f32 v[230:231], v[130:131], v[230:231], v[146:147]
	v_pk_fma_f32 v[230:231], v[240:241], v[232:233], v[230:231] op_sel_hi:[0,1,1]
	v_pk_mul_f32 v[64:65], v[64:65], v[230:231]
	v_lshlrev_b32_e32 v230, 16, v179
	v_and_b32_e32 v231, 0xffff0000, v179
	v_lshlrev_b32_e32 v232, 16, v187
	v_and_b32_e32 v233, 0xffff0000, v187
	v_lshlrev_b32_e32 v234, 16, v195
	v_and_b32_e32 v235, 0xffff0000, v195
	v_cndmask_b32_e32 v234, v234, v204, vcc
	v_cndmask_b32_e32 v235, v235, v205, vcc
	v_pk_add_f32 v[230:231], v[230:231], v[236:237] op_sel_hi:[1,0] neg_lo:[0,1] neg_hi:[0,1]
	v_pk_add_f32 v[234:235], v[234:235], v[232:233] neg_lo:[0,1] neg_hi:[0,1]
	v_pk_mul_f32 v[230:231], v[230:231], v[238:239] op_sel_hi:[1,0]
	v_pk_fma_f32 v[232:233], v[164:165], v[234:235], v[232:233]
	v_pk_fma_f32 v[230:231], v[132:133], v[230:231], v[148:149]
	v_pk_fma_f32 v[230:231], v[240:241], v[232:233], v[230:231] op_sel_hi:[0,1,1]
	v_pk_mul_f32 v[66:67], v[66:67], v[230:231]
	v_lshlrev_b32_e32 v230, 16, v180
	v_and_b32_e32 v231, 0xffff0000, v180
	v_lshlrev_b32_e32 v232, 16, v188
	v_and_b32_e32 v233, 0xffff0000, v188
	v_lshlrev_b32_e32 v234, 16, v196
	v_and_b32_e32 v235, 0xffff0000, v196
	v_cndmask_b32_e32 v234, v234, v206, vcc
	v_cndmask_b32_e32 v235, v235, v207, vcc
	v_pk_add_f32 v[230:231], v[230:231], v[236:237] op_sel_hi:[1,0] neg_lo:[0,1] neg_hi:[0,1]
	v_pk_add_f32 v[234:235], v[234:235], v[232:233] neg_lo:[0,1] neg_hi:[0,1]
	v_pk_mul_f32 v[230:231], v[230:231], v[238:239] op_sel_hi:[1,0]
	v_pk_fma_f32 v[232:233], v[166:167], v[234:235], v[232:233]
	v_pk_fma_f32 v[230:231], v[134:135], v[230:231], v[150:151]
	v_pk_fma_f32 v[230:231], v[240:241], v[232:233], v[230:231] op_sel_hi:[0,1,1]
; __device__ __forceinline__ float bf2f(u16 h) { return __uint_as_float(((unsigned)h) << 16); }
; template <int EPI> ...
;     ...
; #pragma unroll 16
;       for (int i = 0; i < 16; i++) {
;         const int rl = rbase + (i & 3) + 8 * (i >> 2);
;         const int row = m0 + rl;
;         float o0 = bf2f(Y[(size_t)row * 1024 + 256 + ch0]);
;         float o1 = bf2f(Y[(size_t)row * 1024 + 256 + ch1]);
;         float mean = hsum32(o0 + o1) * (1.0f / 64.0f);
;         float d0 = o0 - mean, d1 = o1 - mean;
;         float var = hsum32(d0 * d0 + d1 * d1) * (1.0f / 64.0f);
;         float rstd = rsqrtf(var + 64e-5f);
;         float pv0 = bf2f(P[(size_t)row * 2816 + 256 + 1536 + ch0]);
;         float pv1 = bf2f(P[(size_t)row * 2816 + 256 + 1536 + ch1]);
;         float pp0 = prevP(p, P, row, 1536 + ch0), pp1 = prevP(p, P, row, 1536 + ch1);
;         float vv0 = pv0 + (pp0 - pv0) * mu0, vv1 = pv1 + (pp1 - pv1) * mu1;
;         float b = bs[((size_t)row * 12 + hh) * 4 + 2];
;         float y0 = (d0 * rstd * gg0 + gb0 + b * vv0) * acc0[i];
;         float y1 = (d1 * rstd * gg1 + gb1 + b * vv1) * acc1[i];
;         Y[(size_t)row * 1024 + 256 + ch0] = f2bf(y0);
;         Y[(size_t)row * 1024 + 256 + ch1] = f2bf(y1);
;       }
	v_pk_mul_f32 v[68:69], v[68:69], v[230:231]
	v_lshlrev_b32_e32 v230, 16, v181
	v_and_b32_e32 v231, 0xffff0000, v181
	v_lshlrev_b32_e32 v232, 16, v189
	v_and_b32_e32 v233, 0xffff0000, v189
	v_lshlrev_b32_e32 v234, 16, v197
	v_and_b32_e32 v235, 0xffff0000, v197
	v_cndmask_b32_e32 v234, v234, v208, vcc
	v_cndmask_b32_e32 v235, v235, v209, vcc
	v_pk_add_f32 v[230:231], v[230:231], v[236:237] op_sel_hi:[1,0] neg_lo:[0,1] neg_hi:[0,1]
	v_pk_add_f32 v[234:235], v[234:235], v[232:233] neg_lo:[0,1] neg_hi:[0,1]
	v_pk_mul_f32 v[230:231], v[230:231], v[238:239] op_sel_hi:[1,0]
	v_pk_fma_f32 v[232:233], v[168:169], v[234:235], v[232:233]
	v_pk_fma_f32 v[230:231], v[136:137], v[230:231], v[152:153]
	v_pk_fma_f32 v[230:231], v[240:241], v[232:233], v[230:231] op_sel_hi:[0,1,1]
	v_pk_mul_f32 v[70:71], v[70:71], v[230:231]
	v_cvt_pk_bf16_f32 v64, v64, v65
	v_cvt_pk_bf16_f32 v65, v66, v67
	v_cvt_pk_bf16_f32 v66, v68, v69
	v_cvt_pk_bf16_f32 v67, v70, v71
	v_add_u32_e32 v246, 0x10000, v237
	s_nop 0
	global_store_dwordx4 v246, v[64:67], s[22:23] offset:0
	v_lshlrev_b32_e32 v230, 16, v182
	v_and_b32_e32 v231, 0xffff0000, v182
	v_lshlrev_b32_e32 v232, 16, v190
	v_and_b32_e32 v233, 0xffff0000, v190
	v_lshlrev_b32_e32 v234, 16, v198
	v_and_b32_e32 v235, 0xffff0000, v198
	v_cndmask_b32_e32 v234, v234, v210, vcc
	v_cndmask_b32_e32 v235, v235, v211, vcc
	v_pk_add_f32 v[230:231], v[230:231], v[236:237] op_sel_hi:[1,0] neg_lo:[0,1] neg_hi:[0,1]
	v_pk_add_f32 v[234:235], v[234:235], v[232:233] neg_lo:[0,1] neg_hi:[0,1]
	v_pk_mul_f32 v[230:231], v[230:231], v[238:239] op_sel_hi:[1,0]
	v_pk_fma_f32 v[232:233], v[170:171], v[234:235], v[232:233]
	v_pk_fma_f32 v[230:231], v[138:139], v[230:231], v[154:155]
	v_pk_fma_f32 v[230:231], v[240:241], v[232:233], v[230:231] op_sel_hi:[0,1,1]
	v_pk_mul_f32 v[72:73], v[72:73], v[230:231]
	v_lshlrev_b32_e32 v230, 16, v183
	v_and_b32_e32 v231, 0xffff0000, v183
	v_lshlrev_b32_e32 v232, 16, v191
	v_and_b32_e32 v233, 0xffff0000, v191
	v_lshlrev_b32_e32 v234, 16, v199
	v_and_b32_e32 v235, 0xffff0000, v199
	v_cndmask_b32_e32 v234, v234, v212, vcc
	v_cndmask_b32_e32 v235, v235, v213, vcc
	v_pk_add_f32 v[230:231], v[230:231], v[236:237] op_sel_hi:[1,0] neg_lo:[0,1] neg_hi:[0,1]
	v_pk_add_f32 v[234:235], v[234:235], v[232:233] neg_lo:[0,1] neg_hi:[0,1]
	v_pk_mul_f32 v[230:231], v[230:231], v[238:239] op_sel_hi:[1,0]
	v_pk_fma_f32 v[232:233], v[172:173], v[234:235], v[232:233]
	v_pk_fma_f32 v[230:231], v[140:141], v[230:231], v[156:157]
	v_pk_fma_f32 v[230:231], v[240:241], v[232:233], v[230:231] op_sel_hi:[0,1,1]
	v_pk_mul_f32 v[74:75], v[74:75], v[230:231]
	v_lshlrev_b32_e32 v230, 16, v184
	v_and_b32_e32 v231, 0xffff0000, v184
	v_lshlrev_b32_e32 v232, 16, v192
	v_and_b32_e32 v233, 0xffff0000, v192
	v_lshlrev_b32_e32 v234, 16, v200
	v_and_b32_e32 v235, 0xffff0000, v200
	v_cndmask_b32_e32 v234, v234, v214, vcc
	v_cndmask_b32_e32 v235, v235, v215, vcc
	v_pk_add_f32 v[230:231], v[230:231], v[236:237] op_sel_hi:[1,0] neg_lo:[0,1] neg_hi:[0,1]
	v_pk_add_f32 v[234:235], v[234:235], v[232:233] neg_lo:[0,1] neg_hi:[0,1]
	v_pk_mul_f32 v[230:231], v[230:231], v[238:239] op_sel_hi:[1,0]
	v_pk_fma_f32 v[232:233], v[174:175], v[234:235], v[232:233]
	v_pk_fma_f32 v[230:231], v[142:143], v[230:231], v[158:159]
	v_pk_fma_f32 v[230:231], v[240:241], v[232:233], v[230:231] op_sel_hi:[0,1,1]
	v_pk_mul_f32 v[76:77], v[76:77], v[230:231]
	v_lshlrev_b32_e32 v230, 16, v185
	v_and_b32_e32 v231, 0xffff0000, v185
	v_lshlrev_b32_e32 v232, 16, v193
	v_and_b32_e32 v233, 0xffff0000, v193
	v_lshlrev_b32_e32 v234, 16, v201
	v_and_b32_e32 v235, 0xffff0000, v201
	v_cndmask_b32_e32 v234, v234, v216, vcc
	v_cndmask_b32_e32 v235, v235, v217, vcc
	v_pk_add_f32 v[230:231], v[230:231], v[236:237] op_sel_hi:[1,0] neg_lo:[0,1] neg_hi:[0,1]
	v_pk_add_f32 v[234:235], v[234:235], v[232:233] neg_lo:[0,1] neg_hi:[0,1]
	v_pk_mul_f32 v[230:231], v[230:231], v[238:239] op_sel_hi:[1,0]
	v_pk_fma_f32 v[232:233], v[176:177], v[234:235], v[232:233]
	v_pk_fma_f32 v[230:231], v[144:145], v[230:231], v[160:161]
	v_pk_fma_f32 v[230:231], v[240:241], v[232:233], v[230:231] op_sel_hi:[0,1,1]
	v_pk_mul_f32 v[78:79], v[78:79], v[230:231]
	v_cvt_pk_bf16_f32 v72, v72, v73
	v_cvt_pk_bf16_f32 v73, v74, v75
	v_cvt_pk_bf16_f32 v74, v76, v77
	v_cvt_pk_bf16_f32 v75, v78, v79
	v_add_u32_e32 v246, 0x10000, v237
	s_nop 0
	global_store_dwordx4 v246, v[72:75], s[22:23] offset:64
	v_add_u32_e32 v246, 0x18000, v237
	v_add_u32_e32 v247, 0x42000, v239
	v_subrev_u32_e32 v230, 0x1600, v247
	global_load_dwordx4 v[178:181], v246, s[22:23] offset:0
	global_load_dwordx4 v[182:185], v246, s[22:23] offset:64
	global_load_dwordx4 v[186:189], v247, s[96:97] offset:0
	global_load_dwordx4 v[190:193], v247, s[96:97] offset:64
	global_load_dwordx4 v[194:197], v230, s[96:97] offset:0
	global_load_dwordx4 v[198:201], v230, s[96:97] offset:64
	v_add_u32_e32 v246, 0x2400, v241
	s_nop 0
	global_load_dword v240, v246, s[96:97] offset:0
	v_add_u32_e32 v247, 0x1e000, v243
	global_load_dwordx4 v[202:205], v247, s[20:21] offset:0
	global_load_dwordx4 v[206:209], v247, s[20:21] offset:16
	global_load_dwordx4 v[210:213], v247, s[20:21] offset:128
	global_load_dwordx4 v[214:217], v247, s[20:21] offset:144
	s_waitcnt vmcnt(0)
; __device__ __forceinline__ float bf2f(u16 h) { return __uint_as_float(((unsigned)h) << 16); }
; template <int EPI> ...
;     ...
; #pragma unroll 16
;       for (int i = 0; i < 16; i++) {
;         const int rl = rbase + (i & 3) + 8 * (i >> 2);
;         const int row = m0 + rl;
;         float o0 = bf2f(Y[(size_t)row * 1024 + 256 + ch0]);
;         float o1 = bf2f(Y[(size_t)row * 1024 + 256 + ch1]);
;         float mean = hsum32(o0 + o1) * (1.0f / 64.0f);
;         float d0 = o0 - mean, d1 = o1 - mean;
;         float var = hsum32(d0 * d0 + d1 * d1) * (1.0f / 64.0f);
;         float rstd = rsqrtf(var + 64e-5f);
;         float pv0 = bf2f(P[(size_t)row * 2816 + 256 + 1536 + ch0]);
;         float pv1 = bf2f(P[(size_t)row * 2816 + 256 + 1536 + ch1]);
;         float pp0 = prevP(p, P, row, 1536 + ch0), pp1 = prevP(p, P, row, 1536 + ch1);
;         float vv0 = pv0 + (pp0 - pv0) * mu0, vv1 = pv1 + (pp1 - pv1) * mu1;
;         float b = bs[((size_t)row * 12 + hh) * 4 + 2];
;         float y0 = (d0 * rstd * gg0 + gb0 + b * vv0) * acc0[i];
;         float y1 = (d1 * rstd * gg1 + gb1 + b * vv1) * acc1[i];
;         Y[(size_t)row * 1024 + 256 + ch0] = f2bf(y0);
;         Y[(size_t)row * 1024 + 256 + ch1] = f2bf(y1);
;       }
	v_lshlrev_b32_e32 v232, 16, v178
	v_and_b32_e32 v233, 0xffff0000, v178
	v_lshlrev_b32_e32 v230, 16, v179
	v_and_b32_e32 v231, 0xffff0000, v179
	v_pk_add_f32 v[232:233], v[232:233], v[230:231]
	v_lshlrev_b32_e32 v230, 16, v180
	v_and_b32_e32 v231, 0xffff0000, v180
	v_pk_add_f32 v[232:233], v[232:233], v[230:231]
	v_lshlrev_b32_e32 v230, 16, v181
	v_and_b32_e32 v231, 0xffff0000, v181
	v_pk_add_f32 v[232:233], v[232:233], v[230:231]
	v_lshlrev_b32_e32 v230, 16, v182
	v_and_b32_e32 v231, 0xffff0000, v182
	v_pk_add_f32 v[232:233], v[232:233], v[230:231]
	v_lshlrev_b32_e32 v230, 16, v183
	v_and_b32_e32 v231, 0xffff0000, v183
	v_pk_add_f32 v[232:233], v[232:233], v[230:231]
	v_lshlrev_b32_e32 v230, 16, v184
	v_and_b32_e32 v231, 0xffff0000, v184
	v_pk_add_f32 v[232:233], v[232:233], v[230:231]
	v_lshlrev_b32_e32 v230, 16, v185
	v_and_b32_e32 v231, 0xffff0000, v185
	v_pk_add_f32 v[232:233], v[232:233], v[230:231]
	v_add_f32_e32 v232, v232, v233
	v_mov_b32_e32 v230, v232
	s_nop 1
	v_permlane16_swap_b32_e32 v230, v232
	v_add_f32_e32 v232, v232, v230
	v_mov_b32_e32 v230, v232
	s_nop 1
	v_permlane32_swap_b32_e32 v230, v232
	v_add_f32_e32 v232, v232, v230
	v_mul_f32_e32 v236, 0x3c800000, v232
	v_lshlrev_b32_e32 v230, 16, v178
	v_and_b32_e32 v231, 0xffff0000, v178
	v_pk_add_f32 v[230:231], v[230:231], v[236:237] op_sel_hi:[1,0] neg_lo:[0,1] neg_hi:[0,1]
	v_pk_mul_f32 v[232:233], v[230:231], v[230:231]
	v_lshlrev_b32_e32 v230, 16, v179
	v_and_b32_e32 v231, 0xffff0000, v179
	v_pk_add_f32 v[230:231], v[230:231], v[236:237] op_sel_hi:[1,0] neg_lo:[0,1] neg_hi:[0,1]
	v_pk_fma_f32 v[232:233], v[230:231], v[230:231], v[232:233]
	v_lshlrev_b32_e32 v230, 16, v180
	v_and_b32_e32 v231, 0xffff0000, v180
	v_pk_add_f32 v[230:231], v[230:231], v[236:237] op_sel_hi:[1,0] neg_lo:[0,1] neg_hi:[0,1]
	v_pk_fma_f32 v[232:233], v[230:231], v[230:231], v[232:233]
	v_lshlrev_b32_e32 v230, 16, v181
	v_and_b32_e32 v231, 0xffff0000, v181
	v_pk_add_f32 v[230:231], v[230:231], v[236:237] op_sel_hi:[1,0] neg_lo:[0,1] neg_hi:[0,1]
	v_pk_fma_f32 v[232:233], v[230:231], v[230:231], v[232:233]
	v_lshlrev_b32_e32 v230, 16, v182
	v_and_b32_e32 v231, 0xffff0000, v182
	v_pk_add_f32 v[230:231], v[230:231], v[236:237] op_sel_hi:[1,0] neg_lo:[0,1] neg_hi:[0,1]
	v_pk_fma_f32 v[232:233], v[230:231], v[230:231], v[232:233]
	v_lshlrev_b32_e32 v230, 16, v183
	v_and_b32_e32 v231, 0xffff0000, v183
	v_pk_add_f32 v[230:231], v[230:231], v[236:237] op_sel_hi:[1,0] neg_lo:[0,1] neg_hi:[0,1]
	v_pk_fma_f32 v[232:233], v[230:231], v[230:231], v[232:233]
	v_lshlrev_b32_e32 v230, 16, v184
	v_and_b32_e32 v231, 0xffff0000, v184
	v_pk_add_f32 v[230:231], v[230:231], v[236:237] op_sel_hi:[1,0] neg_lo:[0,1] neg_hi:[0,1]
	v_pk_fma_f32 v[232:233], v[230:231], v[230:231], v[232:233]
	v_lshlrev_b32_e32 v230, 16, v185
	v_and_b32_e32 v231, 0xffff0000, v185
	v_pk_add_f32 v[230:231], v[230:231], v[236:237] op_sel_hi:[1,0] neg_lo:[0,1] neg_hi:[0,1]
	v_pk_fma_f32 v[232:233], v[230:231], v[230:231], v[232:233]
	v_add_f32_e32 v232, v232, v233
	v_mov_b32_e32 v230, v232
	s_nop 1
	v_permlane16_swap_b32_e32 v230, v232
	v_add_f32_e32 v232, v232, v230
	v_mov_b32_e32 v230, v232
	s_nop 1
	v_permlane32_swap_b32_e32 v230, v232
	v_add_f32_e32 v232, v232, v230
	v_mov_b32_e32 v230, 0x3a27c5ac
	v_fmamk_f32 v232, v232, 0x3c800000, v230
	v_rsq_f32_e32 v238, v232
	v_and_b32_e32 v230, 3, v248
	v_cmp_eq_u32_e32 vcc, 0, v230
	s_nop 1
	v_lshlrev_b32_e32 v230, 16, v178
	v_and_b32_e32 v231, 0xffff0000, v178
	v_lshlrev_b32_e32 v232, 16, v186
	v_and_b32_e32 v233, 0xffff0000, v186
	v_lshlrev_b32_e32 v234, 16, v194
	v_and_b32_e32 v235, 0xffff0000, v194
	v_cndmask_b32_e32 v234, v234, v202, vcc
	v_cndmask_b32_e32 v235, v235, v203, vcc
	v_pk_add_f32 v[230:231], v[230:231], v[236:237] op_sel_hi:[1,0] neg_lo:[0,1] neg_hi:[0,1]
	v_pk_add_f32 v[234:235], v[234:235], v[232:233] neg_lo:[0,1] neg_hi:[0,1]
	v_pk_mul_f32 v[230:231], v[230:231], v[238:239] op_sel_hi:[1,0]
	v_pk_fma_f32 v[232:233], v[162:163], v[234:235], v[232:233]
	v_pk_fma_f32 v[230:231], v[130:131], v[230:231], v[146:147]
	v_pk_fma_f32 v[230:231], v[240:241], v[232:233], v[230:231] op_sel_hi:[0,1,1]
	v_pk_mul_f32 v[96:97], v[96:97], v[230:231]
	v_lshlrev_b32_e32 v230, 16, v179
	v_and_b32_e32 v231, 0xffff0000, v179
	v_lshlrev_b32_e32 v232, 16, v187
	v_and_b32_e32 v233, 0xffff0000, v187
	v_lshlrev_b32_e32 v234, 16, v195
	v_and_b32_e32 v235, 0xffff0000, v195
	v_cndmask_b32_e32 v234, v234, v204, vcc
	v_cndmask_b32_e32 v235, v235, v205, vcc
	v_pk_add_f32 v[230:231], v[230:231], v[236:237] op_sel_hi:[1,0] neg_lo:[0,1] neg_hi:[0,1]
	v_pk_add_f32 v[234:235], v[234:235], v[232:233] neg_lo:[0,1] neg_hi:[0,1]
	v_pk_mul_f32 v[230:231], v[230:231], v[238:239] op_sel_hi:[1,0]
	v_pk_fma_f32 v[232:233], v[164:165], v[234:235], v[232:233]
	v_pk_fma_f32 v[230:231], v[132:133], v[230:231], v[148:149]
	v_pk_fma_f32 v[230:231], v[240:241], v[232:233], v[230:231] op_sel_hi:[0,1,1]
	v_pk_mul_f32 v[98:99], v[98:99], v[230:231]
	v_lshlrev_b32_e32 v230, 16, v180
	v_and_b32_e32 v231, 0xffff0000, v180
	v_lshlrev_b32_e32 v232, 16, v188
	v_and_b32_e32 v233, 0xffff0000, v188
	v_lshlrev_b32_e32 v234, 16, v196
	v_and_b32_e32 v235, 0xffff0000, v196
	v_cndmask_b32_e32 v234, v234, v206, vcc
	v_cndmask_b32_e32 v235, v235, v207, vcc
	v_pk_add_f32 v[230:231], v[230:231], v[236:237] op_sel_hi:[1,0] neg_lo:[0,1] neg_hi:[0,1]
	v_pk_add_f32 v[234:235], v[234:235], v[232:233] neg_lo:[0,1] neg_hi:[0,1]
	v_pk_mul_f32 v[230:231], v[230:231], v[238:239] op_sel_hi:[1,0]
	v_pk_fma_f32 v[232:233], v[166:167], v[234:235], v[232:233]
	v_pk_fma_f32 v[230:231], v[134:135], v[230:231], v[150:151]
	v_pk_fma_f32 v[230:231], v[240:241], v[232:233], v[230:231] op_sel_hi:[0,1,1]
; __device__ __forceinline__ float bf2f(u16 h) { return __uint_as_float(((unsigned)h) << 16); }
; template <int EPI> ...
;     ...
;       const float gg0 = p.in[20][ch0], gg1 = p.in[20][ch1];
;       const float gb0 = p.in[21][ch0], gb1 = p.in[21][ch1];
;       const float mu0 = p.in[11][1536 + ch0], mu1 = p.in[11][1536 + ch1];
; #pragma unroll 16
;       for (int i = 0; i < 16; i++) {
;         const int rl = rbase + (i & 3) + 8 * (i >> 2);
;         const int row = m0 + rl;
;         float o0 = bf2f(Y[(size_t)row * 1024 + 256 + ch0]);
;         float o1 = bf2f(Y[(size_t)row * 1024 + 256 + ch1]);
;         float mean = hsum32(o0 + o1) * (1.0f / 64.0f);
;         float d0 = o0 - mean, d1 = o1 - mean;
;         float var = hsum32(d0 * d0 + d1 * d1) * (1.0f / 64.0f);
;         float rstd = rsqrtf(var + 64e-5f);
;         float pv0 = bf2f(P[(size_t)row * 2816 + 256 + 1536 + ch0]);
;         float pv1 = bf2f(P[(size_t)row * 2816 + 256 + 1536 + ch1]);
;         float pp0 = prevP(p, P, row, 1536 + ch0), pp1 = prevP(p, P, row, 1536 + ch1);
;         float vv0 = pv0 + (pp0 - pv0) * mu0, vv1 = pv1 + (pp1 - pv1) * mu1;
;         float b = bs[((size_t)row * 12 + hh) * 4 + 2];
;         float y0 = (d0 * rstd * gg0 + gb0 + b * vv0) * acc0[i];
;         float y1 = (d1 * rstd * gg1 + gb1 + b * vv1) * acc1[i];
;         Y[(size_t)row * 1024 + 256 + ch0] = f2bf(y0);
;         Y[(size_t)row * 1024 + 256 + ch1] = f2bf(y1);
;       }
	v_pk_mul_f32 v[100:101], v[100:101], v[230:231]
	v_lshlrev_b32_e32 v230, 16, v181
	v_and_b32_e32 v231, 0xffff0000, v181
	v_lshlrev_b32_e32 v232, 16, v189
	v_and_b32_e32 v233, 0xffff0000, v189
	v_lshlrev_b32_e32 v234, 16, v197
	v_and_b32_e32 v235, 0xffff0000, v197
	v_cndmask_b32_e32 v234, v234, v208, vcc
	v_cndmask_b32_e32 v235, v235, v209, vcc
	v_pk_add_f32 v[230:231], v[230:231], v[236:237] op_sel_hi:[1,0] neg_lo:[0,1] neg_hi:[0,1]
	v_pk_add_f32 v[234:235], v[234:235], v[232:233] neg_lo:[0,1] neg_hi:[0,1]
	v_pk_mul_f32 v[230:231], v[230:231], v[238:239] op_sel_hi:[1,0]
	v_pk_fma_f32 v[232:233], v[168:169], v[234:235], v[232:233]
	v_pk_fma_f32 v[230:231], v[136:137], v[230:231], v[152:153]
	v_pk_fma_f32 v[230:231], v[240:241], v[232:233], v[230:231] op_sel_hi:[0,1,1]
	v_pk_mul_f32 v[102:103], v[102:103], v[230:231]
	v_cvt_pk_bf16_f32 v96, v96, v97
	v_cvt_pk_bf16_f32 v97, v98, v99
	v_cvt_pk_bf16_f32 v98, v100, v101
	v_cvt_pk_bf16_f32 v99, v102, v103
	v_add_u32_e32 v246, 0x18000, v237
	s_nop 0
	global_store_dwordx4 v246, v[96:99], s[22:23] offset:0
	v_lshlrev_b32_e32 v230, 16, v182
	v_and_b32_e32 v231, 0xffff0000, v182
	v_lshlrev_b32_e32 v232, 16, v190
	v_and_b32_e32 v233, 0xffff0000, v190
	v_lshlrev_b32_e32 v234, 16, v198
	v_and_b32_e32 v235, 0xffff0000, v198
	v_cndmask_b32_e32 v234, v234, v210, vcc
	v_cndmask_b32_e32 v235, v235, v211, vcc
	v_pk_add_f32 v[230:231], v[230:231], v[236:237] op_sel_hi:[1,0] neg_lo:[0,1] neg_hi:[0,1]
	v_pk_add_f32 v[234:235], v[234:235], v[232:233] neg_lo:[0,1] neg_hi:[0,1]
	v_pk_mul_f32 v[230:231], v[230:231], v[238:239] op_sel_hi:[1,0]
	v_pk_fma_f32 v[232:233], v[170:171], v[234:235], v[232:233]
	v_pk_fma_f32 v[230:231], v[138:139], v[230:231], v[154:155]
	v_pk_fma_f32 v[230:231], v[240:241], v[232:233], v[230:231] op_sel_hi:[0,1,1]
	v_pk_mul_f32 v[104:105], v[104:105], v[230:231]
	v_lshlrev_b32_e32 v230, 16, v183
	v_and_b32_e32 v231, 0xffff0000, v183
	v_lshlrev_b32_e32 v232, 16, v191
	v_and_b32_e32 v233, 0xffff0000, v191
	v_lshlrev_b32_e32 v234, 16, v199
	v_and_b32_e32 v235, 0xffff0000, v199
	v_cndmask_b32_e32 v234, v234, v212, vcc
	v_cndmask_b32_e32 v235, v235, v213, vcc
	v_pk_add_f32 v[230:231], v[230:231], v[236:237] op_sel_hi:[1,0] neg_lo:[0,1] neg_hi:[0,1]
	v_pk_add_f32 v[234:235], v[234:235], v[232:233] neg_lo:[0,1] neg_hi:[0,1]
	v_pk_mul_f32 v[230:231], v[230:231], v[238:239] op_sel_hi:[1,0]
	v_pk_fma_f32 v[232:233], v[172:173], v[234:235], v[232:233]
	v_pk_fma_f32 v[230:231], v[140:141], v[230:231], v[156:157]
	v_pk_fma_f32 v[230:231], v[240:241], v[232:233], v[230:231] op_sel_hi:[0,1,1]
	v_pk_mul_f32 v[106:107], v[106:107], v[230:231]
	v_lshlrev_b32_e32 v230, 16, v184
	v_and_b32_e32 v231, 0xffff0000, v184
	v_lshlrev_b32_e32 v232, 16, v192
	v_and_b32_e32 v233, 0xffff0000, v192
	v_lshlrev_b32_e32 v234, 16, v200
	v_and_b32_e32 v235, 0xffff0000, v200
	v_cndmask_b32_e32 v234, v234, v214, vcc
	v_cndmask_b32_e32 v235, v235, v215, vcc
	v_pk_add_f32 v[230:231], v[230:231], v[236:237] op_sel_hi:[1,0] neg_lo:[0,1] neg_hi:[0,1]
	v_pk_add_f32 v[234:235], v[234:235], v[232:233] neg_lo:[0,1] neg_hi:[0,1]
	v_pk_mul_f32 v[230:231], v[230:231], v[238:239] op_sel_hi:[1,0]
	v_pk_fma_f32 v[232:233], v[174:175], v[234:235], v[232:233]
	v_pk_fma_f32 v[230:231], v[142:143], v[230:231], v[158:159]
	v_pk_fma_f32 v[230:231], v[240:241], v[232:233], v[230:231] op_sel_hi:[0,1,1]
	v_pk_mul_f32 v[108:109], v[108:109], v[230:231]
	v_lshlrev_b32_e32 v230, 16, v185
	v_and_b32_e32 v231, 0xffff0000, v185
	v_lshlrev_b32_e32 v232, 16, v193
	v_and_b32_e32 v233, 0xffff0000, v193
	v_lshlrev_b32_e32 v234, 16, v201
	v_and_b32_e32 v235, 0xffff0000, v201
	v_cndmask_b32_e32 v234, v234, v216, vcc
	v_cndmask_b32_e32 v235, v235, v217, vcc
	v_pk_add_f32 v[230:231], v[230:231], v[236:237] op_sel_hi:[1,0] neg_lo:[0,1] neg_hi:[0,1]
	v_pk_add_f32 v[234:235], v[234:235], v[232:233] neg_lo:[0,1] neg_hi:[0,1]
	v_pk_mul_f32 v[230:231], v[230:231], v[238:239] op_sel_hi:[1,0]
	v_pk_fma_f32 v[232:233], v[176:177], v[234:235], v[232:233]
	v_pk_fma_f32 v[230:231], v[144:145], v[230:231], v[160:161]
	v_pk_fma_f32 v[230:231], v[240:241], v[232:233], v[230:231] op_sel_hi:[0,1,1]
	v_pk_mul_f32 v[110:111], v[110:111], v[230:231]
	v_cvt_pk_bf16_f32 v104, v104, v105
	v_cvt_pk_bf16_f32 v105, v106, v107
	v_cvt_pk_bf16_f32 v106, v108, v109
	v_cvt_pk_bf16_f32 v107, v110, v111
	v_add_u32_e32 v246, 0x18000, v237
	s_nop 0
	global_store_dwordx4 v246, v[104:107], s[22:23] offset:64
	global_load_dwordx4 v[130:133], v245, s[2:3] offset:256
	global_load_dwordx4 v[134:137], v245, s[2:3] offset:272
	global_load_dwordx4 v[138:141], v245, s[2:3] offset:384
	global_load_dwordx4 v[142:145], v245, s[2:3] offset:400
	global_load_dwordx4 v[146:149], v245, s[16:17] offset:256
	global_load_dwordx4 v[150:153], v245, s[16:17] offset:272
	global_load_dwordx4 v[154:157], v245, s[16:17] offset:384
	global_load_dwordx4 v[158:161], v245, s[16:17] offset:400
	global_load_dwordx4 v[162:165], v245, s[0:1] offset:256
	global_load_dwordx4 v[166:169], v245, s[0:1] offset:272
	global_load_dwordx4 v[170:173], v245, s[0:1] offset:384
	global_load_dwordx4 v[174:177], v245, s[0:1] offset:400
	v_add_u32_e32 v246, 0x0, v237
	v_add_u32_e32 v247, 0x0, v239
	v_subrev_u32_e32 v230, 0x1600, v247
	global_load_dwordx4 v[178:181], v246, s[22:23] offset:128
	global_load_dwordx4 v[182:185], v246, s[22:23] offset:192
	global_load_dwordx4 v[186:189], v247, s[96:97] offset:128
	global_load_dwordx4 v[190:193], v247, s[96:97] offset:192
	global_load_dwordx4 v[194:197], v230, s[96:97] offset:128
	global_load_dwordx4 v[198:201], v230, s[96:97] offset:192
	v_add_u32_e32 v246, 0x0, v241
	s_nop 0
	global_load_dword v240, v246, s[96:97] offset:16
	v_add_u32_e32 v247, 0x0, v243
	global_load_dwordx4 v[202:205], v247, s[20:21] offset:256
	global_load_dwordx4 v[206:209], v247, s[20:21] offset:272
	global_load_dwordx4 v[210:213], v247, s[20:21] offset:384
	global_load_dwordx4 v[214:217], v247, s[20:21] offset:400
	s_waitcnt vmcnt(0)
; __device__ __forceinline__ float bf2f(u16 h) { return __uint_as_float(((unsigned)h) << 16); }
; template <int EPI> ...
;     ...
; #pragma unroll 16
;       for (int i = 0; i < 16; i++) {
;         const int rl = rbase + (i & 3) + 8 * (i >> 2);
;         const int row = m0 + rl;
;         float o0 = bf2f(Y[(size_t)row * 1024 + 256 + ch0]);
;         float o1 = bf2f(Y[(size_t)row * 1024 + 256 + ch1]);
;         float mean = hsum32(o0 + o1) * (1.0f / 64.0f);
;         float d0 = o0 - mean, d1 = o1 - mean;
;         float var = hsum32(d0 * d0 + d1 * d1) * (1.0f / 64.0f);
;         float rstd = rsqrtf(var + 64e-5f);
;         float pv0 = bf2f(P[(size_t)row * 2816 + 256 + 1536 + ch0]);
;         float pv1 = bf2f(P[(size_t)row * 2816 + 256 + 1536 + ch1]);
;         float pp0 = prevP(p, P, row, 1536 + ch0), pp1 = prevP(p, P, row, 1536 + ch1);
;         float vv0 = pv0 + (pp0 - pv0) * mu0, vv1 = pv1 + (pp1 - pv1) * mu1;
;         float b = bs[((size_t)row * 12 + hh) * 4 + 2];
;         float y0 = (d0 * rstd * gg0 + gb0 + b * vv0) * acc0[i];
;         float y1 = (d1 * rstd * gg1 + gb1 + b * vv1) * acc1[i];
;         Y[(size_t)row * 1024 + 256 + ch0] = f2bf(y0);
;         Y[(size_t)row * 1024 + 256 + ch1] = f2bf(y1);
;       }
	v_lshlrev_b32_e32 v232, 16, v178
	v_and_b32_e32 v233, 0xffff0000, v178
	v_lshlrev_b32_e32 v230, 16, v179
	v_and_b32_e32 v231, 0xffff0000, v179
	v_pk_add_f32 v[232:233], v[232:233], v[230:231]
	v_lshlrev_b32_e32 v230, 16, v180
	v_and_b32_e32 v231, 0xffff0000, v180
	v_pk_add_f32 v[232:233], v[232:233], v[230:231]
	v_lshlrev_b32_e32 v230, 16, v181
	v_and_b32_e32 v231, 0xffff0000, v181
	v_pk_add_f32 v[232:233], v[232:233], v[230:231]
	v_lshlrev_b32_e32 v230, 16, v182
	v_and_b32_e32 v231, 0xffff0000, v182
	v_pk_add_f32 v[232:233], v[232:233], v[230:231]
	v_lshlrev_b32_e32 v230, 16, v183
	v_and_b32_e32 v231, 0xffff0000, v183
	v_pk_add_f32 v[232:233], v[232:233], v[230:231]
	v_lshlrev_b32_e32 v230, 16, v184
	v_and_b32_e32 v231, 0xffff0000, v184
	v_pk_add_f32 v[232:233], v[232:233], v[230:231]
	v_lshlrev_b32_e32 v230, 16, v185
	v_and_b32_e32 v231, 0xffff0000, v185
	v_pk_add_f32 v[232:233], v[232:233], v[230:231]
	v_add_f32_e32 v232, v232, v233
	v_mov_b32_e32 v230, v232
	s_nop 1
	v_permlane16_swap_b32_e32 v230, v232
	v_add_f32_e32 v232, v232, v230
	v_mov_b32_e32 v230, v232
	s_nop 1
	v_permlane32_swap_b32_e32 v230, v232
	v_add_f32_e32 v232, v232, v230
	v_mul_f32_e32 v236, 0x3c800000, v232
	v_lshlrev_b32_e32 v230, 16, v178
	v_and_b32_e32 v231, 0xffff0000, v178
	v_pk_add_f32 v[230:231], v[230:231], v[236:237] op_sel_hi:[1,0] neg_lo:[0,1] neg_hi:[0,1]
	v_pk_mul_f32 v[232:233], v[230:231], v[230:231]
	v_lshlrev_b32_e32 v230, 16, v179
	v_and_b32_e32 v231, 0xffff0000, v179
	v_pk_add_f32 v[230:231], v[230:231], v[236:237] op_sel_hi:[1,0] neg_lo:[0,1] neg_hi:[0,1]
	v_pk_fma_f32 v[232:233], v[230:231], v[230:231], v[232:233]
	v_lshlrev_b32_e32 v230, 16, v180
	v_and_b32_e32 v231, 0xffff0000, v180
	v_pk_add_f32 v[230:231], v[230:231], v[236:237] op_sel_hi:[1,0] neg_lo:[0,1] neg_hi:[0,1]
	v_pk_fma_f32 v[232:233], v[230:231], v[230:231], v[232:233]
	v_lshlrev_b32_e32 v230, 16, v181
	v_and_b32_e32 v231, 0xffff0000, v181
	v_pk_add_f32 v[230:231], v[230:231], v[236:237] op_sel_hi:[1,0] neg_lo:[0,1] neg_hi:[0,1]
	v_pk_fma_f32 v[232:233], v[230:231], v[230:231], v[232:233]
	v_lshlrev_b32_e32 v230, 16, v182
	v_and_b32_e32 v231, 0xffff0000, v182
	v_pk_add_f32 v[230:231], v[230:231], v[236:237] op_sel_hi:[1,0] neg_lo:[0,1] neg_hi:[0,1]
	v_pk_fma_f32 v[232:233], v[230:231], v[230:231], v[232:233]
	v_lshlrev_b32_e32 v230, 16, v183
	v_and_b32_e32 v231, 0xffff0000, v183
	v_pk_add_f32 v[230:231], v[230:231], v[236:237] op_sel_hi:[1,0] neg_lo:[0,1] neg_hi:[0,1]
	v_pk_fma_f32 v[232:233], v[230:231], v[230:231], v[232:233]
	v_lshlrev_b32_e32 v230, 16, v184
	v_and_b32_e32 v231, 0xffff0000, v184
	v_pk_add_f32 v[230:231], v[230:231], v[236:237] op_sel_hi:[1,0] neg_lo:[0,1] neg_hi:[0,1]
	v_pk_fma_f32 v[232:233], v[230:231], v[230:231], v[232:233]
	v_lshlrev_b32_e32 v230, 16, v185
	v_and_b32_e32 v231, 0xffff0000, v185
	v_pk_add_f32 v[230:231], v[230:231], v[236:237] op_sel_hi:[1,0] neg_lo:[0,1] neg_hi:[0,1]
	v_pk_fma_f32 v[232:233], v[230:231], v[230:231], v[232:233]
	v_add_f32_e32 v232, v232, v233
	v_mov_b32_e32 v230, v232
	s_nop 1
	v_permlane16_swap_b32_e32 v230, v232
	v_add_f32_e32 v232, v232, v230
	v_mov_b32_e32 v230, v232
	s_nop 1
	v_permlane32_swap_b32_e32 v230, v232
	v_add_f32_e32 v232, v232, v230
	v_mov_b32_e32 v230, 0x3a27c5ac
	v_fmamk_f32 v232, v232, 0x3c800000, v230
	v_rsq_f32_e32 v238, v232
	v_and_b32_e32 v230, 3, v248
	v_cmp_eq_u32_e32 vcc, 0, v230
	s_nop 1
	v_lshlrev_b32_e32 v230, 16, v178
	v_and_b32_e32 v231, 0xffff0000, v178
	v_lshlrev_b32_e32 v232, 16, v186
	v_and_b32_e32 v233, 0xffff0000, v186
	v_lshlrev_b32_e32 v234, 16, v194
	v_and_b32_e32 v235, 0xffff0000, v194
	v_cndmask_b32_e32 v234, v234, v202, vcc
	v_cndmask_b32_e32 v235, v235, v203, vcc
	v_pk_add_f32 v[230:231], v[230:231], v[236:237] op_sel_hi:[1,0] neg_lo:[0,1] neg_hi:[0,1]
	v_pk_add_f32 v[234:235], v[234:235], v[232:233] neg_lo:[0,1] neg_hi:[0,1]
	v_pk_mul_f32 v[230:231], v[230:231], v[238:239] op_sel_hi:[1,0]
	v_pk_fma_f32 v[232:233], v[162:163], v[234:235], v[232:233]
	v_pk_fma_f32 v[230:231], v[130:131], v[230:231], v[146:147]
	v_pk_fma_f32 v[230:231], v[240:241], v[232:233], v[230:231] op_sel_hi:[0,1,1]
	v_pk_mul_f32 v[16:17], v[16:17], v[230:231]
	v_lshlrev_b32_e32 v230, 16, v179
	v_and_b32_e32 v231, 0xffff0000, v179
	v_lshlrev_b32_e32 v232, 16, v187
	v_and_b32_e32 v233, 0xffff0000, v187
	v_lshlrev_b32_e32 v234, 16, v195
	v_and_b32_e32 v235, 0xffff0000, v195
	v_cndmask_b32_e32 v234, v234, v204, vcc
	v_cndmask_b32_e32 v235, v235, v205, vcc
	v_pk_add_f32 v[230:231], v[230:231], v[236:237] op_sel_hi:[1,0] neg_lo:[0,1] neg_hi:[0,1]
	v_pk_add_f32 v[234:235], v[234:235], v[232:233] neg_lo:[0,1] neg_hi:[0,1]
	v_pk_mul_f32 v[230:231], v[230:231], v[238:239] op_sel_hi:[1,0]
	v_pk_fma_f32 v[232:233], v[164:165], v[234:235], v[232:233]
	v_pk_fma_f32 v[230:231], v[132:133], v[230:231], v[148:149]
	v_pk_fma_f32 v[230:231], v[240:241], v[232:233], v[230:231] op_sel_hi:[0,1,1]
	v_pk_mul_f32 v[18:19], v[18:19], v[230:231]
	v_lshlrev_b32_e32 v230, 16, v180
	v_and_b32_e32 v231, 0xffff0000, v180
	v_lshlrev_b32_e32 v232, 16, v188
	v_and_b32_e32 v233, 0xffff0000, v188
	v_lshlrev_b32_e32 v234, 16, v196
	v_and_b32_e32 v235, 0xffff0000, v196
	v_cndmask_b32_e32 v234, v234, v206, vcc
	v_cndmask_b32_e32 v235, v235, v207, vcc
	v_pk_add_f32 v[230:231], v[230:231], v[236:237] op_sel_hi:[1,0] neg_lo:[0,1] neg_hi:[0,1]
	v_pk_add_f32 v[234:235], v[234:235], v[232:233] neg_lo:[0,1] neg_hi:[0,1]
	v_pk_mul_f32 v[230:231], v[230:231], v[238:239] op_sel_hi:[1,0]
	v_pk_fma_f32 v[232:233], v[166:167], v[234:235], v[232:233]
	v_pk_fma_f32 v[230:231], v[134:135], v[230:231], v[150:151]
	v_pk_fma_f32 v[230:231], v[240:241], v[232:233], v[230:231] op_sel_hi:[0,1,1]
; __device__ __forceinline__ float bf2f(u16 h) { return __uint_as_float(((unsigned)h) << 16); }
; template <int EPI> ...
;     ...
; #pragma unroll 16
;       for (int i = 0; i < 16; i++) {
;         const int rl = rbase + (i & 3) + 8 * (i >> 2);
;         const int row = m0 + rl;
;         float o0 = bf2f(Y[(size_t)row * 1024 + 256 + ch0]);
;         float o1 = bf2f(Y[(size_t)row * 1024 + 256 + ch1]);
;         float mean = hsum32(o0 + o1) * (1.0f / 64.0f);
;         float d0 = o0 - mean, d1 = o1 - mean;
;         float var = hsum32(d0 * d0 + d1 * d1) * (1.0f / 64.0f);
;         float rstd = rsqrtf(var + 64e-5f);
;         float pv0 = bf2f(P[(size_t)row * 2816 + 256 + 1536 + ch0]);
;         float pv1 = bf2f(P[(size_t)row * 2816 + 256 + 1536 + ch1]);
;         float pp0 = prevP(p, P, row, 1536 + ch0), pp1 = prevP(p, P, row, 1536 + ch1);
;         float vv0 = pv0 + (pp0 - pv0) * mu0, vv1 = pv1 + (pp1 - pv1) * mu1;
;         float b = bs[((size_t)row * 12 + hh) * 4 + 2];
;         float y0 = (d0 * rstd * gg0 + gb0 + b * vv0) * acc0[i];
;         float y1 = (d1 * rstd * gg1 + gb1 + b * vv1) * acc1[i];
;         Y[(size_t)row * 1024 + 256 + ch0] = f2bf(y0);
;         Y[(size_t)row * 1024 + 256 + ch1] = f2bf(y1);
;       }
	v_pk_mul_f32 v[20:21], v[20:21], v[230:231]
	v_lshlrev_b32_e32 v230, 16, v181
	v_and_b32_e32 v231, 0xffff0000, v181
	v_lshlrev_b32_e32 v232, 16, v189
	v_and_b32_e32 v233, 0xffff0000, v189
	v_lshlrev_b32_e32 v234, 16, v197
	v_and_b32_e32 v235, 0xffff0000, v197
	v_cndmask_b32_e32 v234, v234, v208, vcc
	v_cndmask_b32_e32 v235, v235, v209, vcc
	v_pk_add_f32 v[230:231], v[230:231], v[236:237] op_sel_hi:[1,0] neg_lo:[0,1] neg_hi:[0,1]
	v_pk_add_f32 v[234:235], v[234:235], v[232:233] neg_lo:[0,1] neg_hi:[0,1]
	v_pk_mul_f32 v[230:231], v[230:231], v[238:239] op_sel_hi:[1,0]
	v_pk_fma_f32 v[232:233], v[168:169], v[234:235], v[232:233]
	v_pk_fma_f32 v[230:231], v[136:137], v[230:231], v[152:153]
	v_pk_fma_f32 v[230:231], v[240:241], v[232:233], v[230:231] op_sel_hi:[0,1,1]
	v_pk_mul_f32 v[22:23], v[22:23], v[230:231]
	v_cvt_pk_bf16_f32 v16, v16, v17
	v_cvt_pk_bf16_f32 v17, v18, v19
	v_cvt_pk_bf16_f32 v18, v20, v21
	v_cvt_pk_bf16_f32 v19, v22, v23
	v_add_u32_e32 v246, 0x0, v237
	s_nop 0
	global_store_dwordx4 v246, v[16:19], s[22:23] offset:128
	v_lshlrev_b32_e32 v230, 16, v182
	v_and_b32_e32 v231, 0xffff0000, v182
	v_lshlrev_b32_e32 v232, 16, v190
	v_and_b32_e32 v233, 0xffff0000, v190
	v_lshlrev_b32_e32 v234, 16, v198
	v_and_b32_e32 v235, 0xffff0000, v198
	v_cndmask_b32_e32 v234, v234, v210, vcc
	v_cndmask_b32_e32 v235, v235, v211, vcc
	v_pk_add_f32 v[230:231], v[230:231], v[236:237] op_sel_hi:[1,0] neg_lo:[0,1] neg_hi:[0,1]
	v_pk_add_f32 v[234:235], v[234:235], v[232:233] neg_lo:[0,1] neg_hi:[0,1]
	v_pk_mul_f32 v[230:231], v[230:231], v[238:239] op_sel_hi:[1,0]
	v_pk_fma_f32 v[232:233], v[170:171], v[234:235], v[232:233]
	v_pk_fma_f32 v[230:231], v[138:139], v[230:231], v[154:155]
	v_pk_fma_f32 v[230:231], v[240:241], v[232:233], v[230:231] op_sel_hi:[0,1,1]
	v_pk_mul_f32 v[24:25], v[24:25], v[230:231]
	v_lshlrev_b32_e32 v230, 16, v183
	v_and_b32_e32 v231, 0xffff0000, v183
	v_lshlrev_b32_e32 v232, 16, v191
	v_and_b32_e32 v233, 0xffff0000, v191
	v_lshlrev_b32_e32 v234, 16, v199
	v_and_b32_e32 v235, 0xffff0000, v199
	v_cndmask_b32_e32 v234, v234, v212, vcc
	v_cndmask_b32_e32 v235, v235, v213, vcc
	v_pk_add_f32 v[230:231], v[230:231], v[236:237] op_sel_hi:[1,0] neg_lo:[0,1] neg_hi:[0,1]
	v_pk_add_f32 v[234:235], v[234:235], v[232:233] neg_lo:[0,1] neg_hi:[0,1]
	v_pk_mul_f32 v[230:231], v[230:231], v[238:239] op_sel_hi:[1,0]
	v_pk_fma_f32 v[232:233], v[172:173], v[234:235], v[232:233]
	v_pk_fma_f32 v[230:231], v[140:141], v[230:231], v[156:157]
	v_pk_fma_f32 v[230:231], v[240:241], v[232:233], v[230:231] op_sel_hi:[0,1,1]
	v_pk_mul_f32 v[26:27], v[26:27], v[230:231]
	v_lshlrev_b32_e32 v230, 16, v184
	v_and_b32_e32 v231, 0xffff0000, v184
	v_lshlrev_b32_e32 v232, 16, v192
	v_and_b32_e32 v233, 0xffff0000, v192
	v_lshlrev_b32_e32 v234, 16, v200
	v_and_b32_e32 v235, 0xffff0000, v200
	v_cndmask_b32_e32 v234, v234, v214, vcc
	v_cndmask_b32_e32 v235, v235, v215, vcc
	v_pk_add_f32 v[230:231], v[230:231], v[236:237] op_sel_hi:[1,0] neg_lo:[0,1] neg_hi:[0,1]
	v_pk_add_f32 v[234:235], v[234:235], v[232:233] neg_lo:[0,1] neg_hi:[0,1]
	v_pk_mul_f32 v[230:231], v[230:231], v[238:239] op_sel_hi:[1,0]
	v_pk_fma_f32 v[232:233], v[174:175], v[234:235], v[232:233]
	v_pk_fma_f32 v[230:231], v[142:143], v[230:231], v[158:159]
	v_pk_fma_f32 v[230:231], v[240:241], v[232:233], v[230:231] op_sel_hi:[0,1,1]
	v_pk_mul_f32 v[28:29], v[28:29], v[230:231]
	v_lshlrev_b32_e32 v230, 16, v185
	v_and_b32_e32 v231, 0xffff0000, v185
	v_lshlrev_b32_e32 v232, 16, v193
	v_and_b32_e32 v233, 0xffff0000, v193
	v_lshlrev_b32_e32 v234, 16, v201
	v_and_b32_e32 v235, 0xffff0000, v201
	v_cndmask_b32_e32 v234, v234, v216, vcc
	v_cndmask_b32_e32 v235, v235, v217, vcc
	v_pk_add_f32 v[230:231], v[230:231], v[236:237] op_sel_hi:[1,0] neg_lo:[0,1] neg_hi:[0,1]
	v_pk_add_f32 v[234:235], v[234:235], v[232:233] neg_lo:[0,1] neg_hi:[0,1]
	v_pk_mul_f32 v[230:231], v[230:231], v[238:239] op_sel_hi:[1,0]
	v_pk_fma_f32 v[232:233], v[176:177], v[234:235], v[232:233]
	v_pk_fma_f32 v[230:231], v[144:145], v[230:231], v[160:161]
	v_pk_fma_f32 v[230:231], v[240:241], v[232:233], v[230:231] op_sel_hi:[0,1,1]
	v_pk_mul_f32 v[30:31], v[30:31], v[230:231]
	v_cvt_pk_bf16_f32 v24, v24, v25
	v_cvt_pk_bf16_f32 v25, v26, v27
	v_cvt_pk_bf16_f32 v26, v28, v29
	v_cvt_pk_bf16_f32 v27, v30, v31
	v_add_u32_e32 v246, 0x0, v237
	s_nop 0
	global_store_dwordx4 v246, v[24:27], s[22:23] offset:192
	v_add_u32_e32 v246, 0x8000, v237
	v_add_u32_e32 v247, 0x16000, v239
	v_subrev_u32_e32 v230, 0x1600, v247
	global_load_dwordx4 v[178:181], v246, s[22:23] offset:128
	global_load_dwordx4 v[182:185], v246, s[22:23] offset:192
	global_load_dwordx4 v[186:189], v247, s[96:97] offset:128
	global_load_dwordx4 v[190:193], v247, s[96:97] offset:192
	global_load_dwordx4 v[194:197], v230, s[96:97] offset:128
	global_load_dwordx4 v[198:201], v230, s[96:97] offset:192
	v_add_u32_e32 v246, 0xc00, v241
	s_nop 0
	global_load_dword v240, v246, s[96:97] offset:16
	v_add_u32_e32 v247, 0xa000, v243
	global_load_dwordx4 v[202:205], v247, s[20:21] offset:256
	global_load_dwordx4 v[206:209], v247, s[20:21] offset:272
	global_load_dwordx4 v[210:213], v247, s[20:21] offset:384
	global_load_dwordx4 v[214:217], v247, s[20:21] offset:400
	s_waitcnt vmcnt(0)
; __device__ __forceinline__ float bf2f(u16 h) { return __uint_as_float(((unsigned)h) << 16); }
; template <int EPI> ...
;     ...
; #pragma unroll 16
;       for (int i = 0; i < 16; i++) {
;         const int rl = rbase + (i & 3) + 8 * (i >> 2);
;         const int row = m0 + rl;
;         float o0 = bf2f(Y[(size_t)row * 1024 + 256 + ch0]);
;         float o1 = bf2f(Y[(size_t)row * 1024 + 256 + ch1]);
;         float mean = hsum32(o0 + o1) * (1.0f / 64.0f);
;         float d0 = o0 - mean, d1 = o1 - mean;
;         float var = hsum32(d0 * d0 + d1 * d1) * (1.0f / 64.0f);
;         float rstd = rsqrtf(var + 64e-5f);
;         float pv0 = bf2f(P[(size_t)row * 2816 + 256 + 1536 + ch0]);
;         float pv1 = bf2f(P[(size_t)row * 2816 + 256 + 1536 + ch1]);
;         float pp0 = prevP(p, P, row, 1536 + ch0), pp1 = prevP(p, P, row, 1536 + ch1);
;         float vv0 = pv0 + (pp0 - pv0) * mu0, vv1 = pv1 + (pp1 - pv1) * mu1;
;         float b = bs[((size_t)row * 12 + hh) * 4 + 2];
;         float y0 = (d0 * rstd * gg0 + gb0 + b * vv0) * acc0[i];
;         float y1 = (d1 * rstd * gg1 + gb1 + b * vv1) * acc1[i];
;         Y[(size_t)row * 1024 + 256 + ch0] = f2bf(y0);
;         Y[(size_t)row * 1024 + 256 + ch1] = f2bf(y1);
;       }
	v_lshlrev_b32_e32 v232, 16, v178
	v_and_b32_e32 v233, 0xffff0000, v178
	v_lshlrev_b32_e32 v230, 16, v179
	v_and_b32_e32 v231, 0xffff0000, v179
	v_pk_add_f32 v[232:233], v[232:233], v[230:231]
	v_lshlrev_b32_e32 v230, 16, v180
	v_and_b32_e32 v231, 0xffff0000, v180
	v_pk_add_f32 v[232:233], v[232:233], v[230:231]
	v_lshlrev_b32_e32 v230, 16, v181
	v_and_b32_e32 v231, 0xffff0000, v181
	v_pk_add_f32 v[232:233], v[232:233], v[230:231]
	v_lshlrev_b32_e32 v230, 16, v182
	v_and_b32_e32 v231, 0xffff0000, v182
	v_pk_add_f32 v[232:233], v[232:233], v[230:231]
	v_lshlrev_b32_e32 v230, 16, v183
	v_and_b32_e32 v231, 0xffff0000, v183
	v_pk_add_f32 v[232:233], v[232:233], v[230:231]
	v_lshlrev_b32_e32 v230, 16, v184
	v_and_b32_e32 v231, 0xffff0000, v184
	v_pk_add_f32 v[232:233], v[232:233], v[230:231]
	v_lshlrev_b32_e32 v230, 16, v185
	v_and_b32_e32 v231, 0xffff0000, v185
	v_pk_add_f32 v[232:233], v[232:233], v[230:231]
	v_add_f32_e32 v232, v232, v233
	v_mov_b32_e32 v230, v232
	s_nop 1
	v_permlane16_swap_b32_e32 v230, v232
	v_add_f32_e32 v232, v232, v230
	v_mov_b32_e32 v230, v232
	s_nop 1
	v_permlane32_swap_b32_e32 v230, v232
	v_add_f32_e32 v232, v232, v230
	v_mul_f32_e32 v236, 0x3c800000, v232
	v_lshlrev_b32_e32 v230, 16, v178
	v_and_b32_e32 v231, 0xffff0000, v178
	v_pk_add_f32 v[230:231], v[230:231], v[236:237] op_sel_hi:[1,0] neg_lo:[0,1] neg_hi:[0,1]
	v_pk_mul_f32 v[232:233], v[230:231], v[230:231]
	v_lshlrev_b32_e32 v230, 16, v179
	v_and_b32_e32 v231, 0xffff0000, v179
	v_pk_add_f32 v[230:231], v[230:231], v[236:237] op_sel_hi:[1,0] neg_lo:[0,1] neg_hi:[0,1]
	v_pk_fma_f32 v[232:233], v[230:231], v[230:231], v[232:233]
	v_lshlrev_b32_e32 v230, 16, v180
	v_and_b32_e32 v231, 0xffff0000, v180
	v_pk_add_f32 v[230:231], v[230:231], v[236:237] op_sel_hi:[1,0] neg_lo:[0,1] neg_hi:[0,1]
	v_pk_fma_f32 v[232:233], v[230:231], v[230:231], v[232:233]
	v_lshlrev_b32_e32 v230, 16, v181
	v_and_b32_e32 v231, 0xffff0000, v181
	v_pk_add_f32 v[230:231], v[230:231], v[236:237] op_sel_hi:[1,0] neg_lo:[0,1] neg_hi:[0,1]
	v_pk_fma_f32 v[232:233], v[230:231], v[230:231], v[232:233]
	v_lshlrev_b32_e32 v230, 16, v182
	v_and_b32_e32 v231, 0xffff0000, v182
	v_pk_add_f32 v[230:231], v[230:231], v[236:237] op_sel_hi:[1,0] neg_lo:[0,1] neg_hi:[0,1]
	v_pk_fma_f32 v[232:233], v[230:231], v[230:231], v[232:233]
	v_lshlrev_b32_e32 v230, 16, v183
	v_and_b32_e32 v231, 0xffff0000, v183
	v_pk_add_f32 v[230:231], v[230:231], v[236:237] op_sel_hi:[1,0] neg_lo:[0,1] neg_hi:[0,1]
	v_pk_fma_f32 v[232:233], v[230:231], v[230:231], v[232:233]
	v_lshlrev_b32_e32 v230, 16, v184
	v_and_b32_e32 v231, 0xffff0000, v184
	v_pk_add_f32 v[230:231], v[230:231], v[236:237] op_sel_hi:[1,0] neg_lo:[0,1] neg_hi:[0,1]
	v_pk_fma_f32 v[232:233], v[230:231], v[230:231], v[232:233]
	v_lshlrev_b32_e32 v230, 16, v185
	v_and_b32_e32 v231, 0xffff0000, v185
	v_pk_add_f32 v[230:231], v[230:231], v[236:237] op_sel_hi:[1,0] neg_lo:[0,1] neg_hi:[0,1]
	v_pk_fma_f32 v[232:233], v[230:231], v[230:231], v[232:233]
	v_add_f32_e32 v232, v232, v233
	v_mov_b32_e32 v230, v232
	s_nop 1
	v_permlane16_swap_b32_e32 v230, v232
	v_add_f32_e32 v232, v232, v230
	v_mov_b32_e32 v230, v232
	s_nop 1
	v_permlane32_swap_b32_e32 v230, v232
	v_add_f32_e32 v232, v232, v230
	v_mov_b32_e32 v230, 0x3a27c5ac
	v_fmamk_f32 v232, v232, 0x3c800000, v230
	v_rsq_f32_e32 v238, v232
	v_and_b32_e32 v230, 3, v248
	v_cmp_eq_u32_e32 vcc, 0, v230
	s_nop 1
	v_lshlrev_b32_e32 v230, 16, v178
	v_and_b32_e32 v231, 0xffff0000, v178
	v_lshlrev_b32_e32 v232, 16, v186
	v_and_b32_e32 v233, 0xffff0000, v186
	v_lshlrev_b32_e32 v234, 16, v194
	v_and_b32_e32 v235, 0xffff0000, v194
	v_cndmask_b32_e32 v234, v234, v202, vcc
	v_cndmask_b32_e32 v235, v235, v203, vcc
	v_pk_add_f32 v[230:231], v[230:231], v[236:237] op_sel_hi:[1,0] neg_lo:[0,1] neg_hi:[0,1]
	v_pk_add_f32 v[234:235], v[234:235], v[232:233] neg_lo:[0,1] neg_hi:[0,1]
	v_pk_mul_f32 v[230:231], v[230:231], v[238:239] op_sel_hi:[1,0]
	v_pk_fma_f32 v[232:233], v[162:163], v[234:235], v[232:233]
	v_pk_fma_f32 v[230:231], v[130:131], v[230:231], v[146:147]
	v_pk_fma_f32 v[230:231], v[240:241], v[232:233], v[230:231] op_sel_hi:[0,1,1]
	v_pk_mul_f32 v[48:49], v[48:49], v[230:231]
	v_lshlrev_b32_e32 v230, 16, v179
	v_and_b32_e32 v231, 0xffff0000, v179
	v_lshlrev_b32_e32 v232, 16, v187
	v_and_b32_e32 v233, 0xffff0000, v187
	v_lshlrev_b32_e32 v234, 16, v195
	v_and_b32_e32 v235, 0xffff0000, v195
	v_cndmask_b32_e32 v234, v234, v204, vcc
	v_cndmask_b32_e32 v235, v235, v205, vcc
	v_pk_add_f32 v[230:231], v[230:231], v[236:237] op_sel_hi:[1,0] neg_lo:[0,1] neg_hi:[0,1]
	v_pk_add_f32 v[234:235], v[234:235], v[232:233] neg_lo:[0,1] neg_hi:[0,1]
	v_pk_mul_f32 v[230:231], v[230:231], v[238:239] op_sel_hi:[1,0]
	v_pk_fma_f32 v[232:233], v[164:165], v[234:235], v[232:233]
	v_pk_fma_f32 v[230:231], v[132:133], v[230:231], v[148:149]
	v_pk_fma_f32 v[230:231], v[240:241], v[232:233], v[230:231] op_sel_hi:[0,1,1]
	v_pk_mul_f32 v[50:51], v[50:51], v[230:231]
	v_lshlrev_b32_e32 v230, 16, v180
	v_and_b32_e32 v231, 0xffff0000, v180
	v_lshlrev_b32_e32 v232, 16, v188
	v_and_b32_e32 v233, 0xffff0000, v188
	v_lshlrev_b32_e32 v234, 16, v196
	v_and_b32_e32 v235, 0xffff0000, v196
	v_cndmask_b32_e32 v234, v234, v206, vcc
	v_cndmask_b32_e32 v235, v235, v207, vcc
	v_pk_add_f32 v[230:231], v[230:231], v[236:237] op_sel_hi:[1,0] neg_lo:[0,1] neg_hi:[0,1]
	v_pk_add_f32 v[234:235], v[234:235], v[232:233] neg_lo:[0,1] neg_hi:[0,1]
	v_pk_mul_f32 v[230:231], v[230:231], v[238:239] op_sel_hi:[1,0]
	v_pk_fma_f32 v[232:233], v[166:167], v[234:235], v[232:233]
	v_pk_fma_f32 v[230:231], v[134:135], v[230:231], v[150:151]
	v_pk_fma_f32 v[230:231], v[240:241], v[232:233], v[230:231] op_sel_hi:[0,1,1]
; __device__ __forceinline__ float bf2f(u16 h) { return __uint_as_float(((unsigned)h) << 16); }
; template <int EPI> ...
;     ...
; #pragma unroll 16
;       for (int i = 0; i < 16; i++) {
;         const int rl = rbase + (i & 3) + 8 * (i >> 2);
;         const int row = m0 + rl;
;         float o0 = bf2f(Y[(size_t)row * 1024 + 256 + ch0]);
;         float o1 = bf2f(Y[(size_t)row * 1024 + 256 + ch1]);
;         float mean = hsum32(o0 + o1) * (1.0f / 64.0f);
;         float d0 = o0 - mean, d1 = o1 - mean;
;         float var = hsum32(d0 * d0 + d1 * d1) * (1.0f / 64.0f);
;         float rstd = rsqrtf(var + 64e-5f);
;         float pv0 = bf2f(P[(size_t)row * 2816 + 256 + 1536 + ch0]);
;         float pv1 = bf2f(P[(size_t)row * 2816 + 256 + 1536 + ch1]);
;         float pp0 = prevP(p, P, row, 1536 + ch0), pp1 = prevP(p, P, row, 1536 + ch1);
;         float vv0 = pv0 + (pp0 - pv0) * mu0, vv1 = pv1 + (pp1 - pv1) * mu1;
;         float b = bs[((size_t)row * 12 + hh) * 4 + 2];
;         float y0 = (d0 * rstd * gg0 + gb0 + b * vv0) * acc0[i];
;         float y1 = (d1 * rstd * gg1 + gb1 + b * vv1) * acc1[i];
;         Y[(size_t)row * 1024 + 256 + ch0] = f2bf(y0);
;         Y[(size_t)row * 1024 + 256 + ch1] = f2bf(y1);
;       }
	v_pk_mul_f32 v[52:53], v[52:53], v[230:231]
	v_lshlrev_b32_e32 v230, 16, v181
	v_and_b32_e32 v231, 0xffff0000, v181
	v_lshlrev_b32_e32 v232, 16, v189
	v_and_b32_e32 v233, 0xffff0000, v189
	v_lshlrev_b32_e32 v234, 16, v197
	v_and_b32_e32 v235, 0xffff0000, v197
	v_cndmask_b32_e32 v234, v234, v208, vcc
	v_cndmask_b32_e32 v235, v235, v209, vcc
	v_pk_add_f32 v[230:231], v[230:231], v[236:237] op_sel_hi:[1,0] neg_lo:[0,1] neg_hi:[0,1]
	v_pk_add_f32 v[234:235], v[234:235], v[232:233] neg_lo:[0,1] neg_hi:[0,1]
	v_pk_mul_f32 v[230:231], v[230:231], v[238:239] op_sel_hi:[1,0]
	v_pk_fma_f32 v[232:233], v[168:169], v[234:235], v[232:233]
	v_pk_fma_f32 v[230:231], v[136:137], v[230:231], v[152:153]
	v_pk_fma_f32 v[230:231], v[240:241], v[232:233], v[230:231] op_sel_hi:[0,1,1]
	v_pk_mul_f32 v[54:55], v[54:55], v[230:231]
	v_cvt_pk_bf16_f32 v48, v48, v49
	v_cvt_pk_bf16_f32 v49, v50, v51
	v_cvt_pk_bf16_f32 v50, v52, v53
	v_cvt_pk_bf16_f32 v51, v54, v55
	v_add_u32_e32 v246, 0x8000, v237
	s_nop 0
	global_store_dwordx4 v246, v[48:51], s[22:23] offset:128
	v_lshlrev_b32_e32 v230, 16, v182
	v_and_b32_e32 v231, 0xffff0000, v182
	v_lshlrev_b32_e32 v232, 16, v190
	v_and_b32_e32 v233, 0xffff0000, v190
	v_lshlrev_b32_e32 v234, 16, v198
	v_and_b32_e32 v235, 0xffff0000, v198
	v_cndmask_b32_e32 v234, v234, v210, vcc
	v_cndmask_b32_e32 v235, v235, v211, vcc
	v_pk_add_f32 v[230:231], v[230:231], v[236:237] op_sel_hi:[1,0] neg_lo:[0,1] neg_hi:[0,1]
	v_pk_add_f32 v[234:235], v[234:235], v[232:233] neg_lo:[0,1] neg_hi:[0,1]
	v_pk_mul_f32 v[230:231], v[230:231], v[238:239] op_sel_hi:[1,0]
	v_pk_fma_f32 v[232:233], v[170:171], v[234:235], v[232:233]
	v_pk_fma_f32 v[230:231], v[138:139], v[230:231], v[154:155]
	v_pk_fma_f32 v[230:231], v[240:241], v[232:233], v[230:231] op_sel_hi:[0,1,1]
	v_pk_mul_f32 v[56:57], v[56:57], v[230:231]
	v_lshlrev_b32_e32 v230, 16, v183
	v_and_b32_e32 v231, 0xffff0000, v183
	v_lshlrev_b32_e32 v232, 16, v191
	v_and_b32_e32 v233, 0xffff0000, v191
	v_lshlrev_b32_e32 v234, 16, v199
	v_and_b32_e32 v235, 0xffff0000, v199
	v_cndmask_b32_e32 v234, v234, v212, vcc
	v_cndmask_b32_e32 v235, v235, v213, vcc
	v_pk_add_f32 v[230:231], v[230:231], v[236:237] op_sel_hi:[1,0] neg_lo:[0,1] neg_hi:[0,1]
	v_pk_add_f32 v[234:235], v[234:235], v[232:233] neg_lo:[0,1] neg_hi:[0,1]
	v_pk_mul_f32 v[230:231], v[230:231], v[238:239] op_sel_hi:[1,0]
	v_pk_fma_f32 v[232:233], v[172:173], v[234:235], v[232:233]
	v_pk_fma_f32 v[230:231], v[140:141], v[230:231], v[156:157]
	v_pk_fma_f32 v[230:231], v[240:241], v[232:233], v[230:231] op_sel_hi:[0,1,1]
	v_pk_mul_f32 v[58:59], v[58:59], v[230:231]
	v_lshlrev_b32_e32 v230, 16, v184
	v_and_b32_e32 v231, 0xffff0000, v184
	v_lshlrev_b32_e32 v232, 16, v192
	v_and_b32_e32 v233, 0xffff0000, v192
	v_lshlrev_b32_e32 v234, 16, v200
	v_and_b32_e32 v235, 0xffff0000, v200
	v_cndmask_b32_e32 v234, v234, v214, vcc
	v_cndmask_b32_e32 v235, v235, v215, vcc
	v_pk_add_f32 v[230:231], v[230:231], v[236:237] op_sel_hi:[1,0] neg_lo:[0,1] neg_hi:[0,1]
	v_pk_add_f32 v[234:235], v[234:235], v[232:233] neg_lo:[0,1] neg_hi:[0,1]
	v_pk_mul_f32 v[230:231], v[230:231], v[238:239] op_sel_hi:[1,0]
	v_pk_fma_f32 v[232:233], v[174:175], v[234:235], v[232:233]
	v_pk_fma_f32 v[230:231], v[142:143], v[230:231], v[158:159]
	v_pk_fma_f32 v[230:231], v[240:241], v[232:233], v[230:231] op_sel_hi:[0,1,1]
	v_pk_mul_f32 v[60:61], v[60:61], v[230:231]
	v_lshlrev_b32_e32 v230, 16, v185
	v_and_b32_e32 v231, 0xffff0000, v185
	v_lshlrev_b32_e32 v232, 16, v193
	v_and_b32_e32 v233, 0xffff0000, v193
	v_lshlrev_b32_e32 v234, 16, v201
	v_and_b32_e32 v235, 0xffff0000, v201
	v_cndmask_b32_e32 v234, v234, v216, vcc
	v_cndmask_b32_e32 v235, v235, v217, vcc
	v_pk_add_f32 v[230:231], v[230:231], v[236:237] op_sel_hi:[1,0] neg_lo:[0,1] neg_hi:[0,1]
	v_pk_add_f32 v[234:235], v[234:235], v[232:233] neg_lo:[0,1] neg_hi:[0,1]
	v_pk_mul_f32 v[230:231], v[230:231], v[238:239] op_sel_hi:[1,0]
	v_pk_fma_f32 v[232:233], v[176:177], v[234:235], v[232:233]
	v_pk_fma_f32 v[230:231], v[144:145], v[230:231], v[160:161]
	v_pk_fma_f32 v[230:231], v[240:241], v[232:233], v[230:231] op_sel_hi:[0,1,1]
	v_pk_mul_f32 v[62:63], v[62:63], v[230:231]
	v_cvt_pk_bf16_f32 v56, v56, v57
	v_cvt_pk_bf16_f32 v57, v58, v59
	v_cvt_pk_bf16_f32 v58, v60, v61
	v_cvt_pk_bf16_f32 v59, v62, v63
	v_add_u32_e32 v246, 0x8000, v237
	s_nop 0
	global_store_dwordx4 v246, v[56:59], s[22:23] offset:192
	v_add_u32_e32 v246, 0x10000, v237
	v_add_u32_e32 v247, 0x2c000, v239
	v_subrev_u32_e32 v230, 0x1600, v247
	global_load_dwordx4 v[178:181], v246, s[22:23] offset:128
	global_load_dwordx4 v[182:185], v246, s[22:23] offset:192
	global_load_dwordx4 v[186:189], v247, s[96:97] offset:128
	global_load_dwordx4 v[190:193], v247, s[96:97] offset:192
	global_load_dwordx4 v[194:197], v230, s[96:97] offset:128
	global_load_dwordx4 v[198:201], v230, s[96:97] offset:192
	v_add_u32_e32 v246, 0x1800, v241
	s_nop 0
	global_load_dword v240, v246, s[96:97] offset:16
	v_add_u32_e32 v247, 0x14000, v243
	global_load_dwordx4 v[202:205], v247, s[20:21] offset:256
	global_load_dwordx4 v[206:209], v247, s[20:21] offset:272
	global_load_dwordx4 v[210:213], v247, s[20:21] offset:384
	global_load_dwordx4 v[214:217], v247, s[20:21] offset:400
	s_waitcnt vmcnt(0)
; __device__ __forceinline__ float bf2f(u16 h) { return __uint_as_float(((unsigned)h) << 16); }
; template <int EPI> ...
;     ...
; #pragma unroll 16
;       for (int i = 0; i < 16; i++) {
;         const int rl = rbase + (i & 3) + 8 * (i >> 2);
;         const int row = m0 + rl;
;         float o0 = bf2f(Y[(size_t)row * 1024 + 256 + ch0]);
;         float o1 = bf2f(Y[(size_t)row * 1024 + 256 + ch1]);
;         float mean = hsum32(o0 + o1) * (1.0f / 64.0f);
;         float d0 = o0 - mean, d1 = o1 - mean;
;         float var = hsum32(d0 * d0 + d1 * d1) * (1.0f / 64.0f);
;         float rstd = rsqrtf(var + 64e-5f);
;         float pv0 = bf2f(P[(size_t)row * 2816 + 256 + 1536 + ch0]);
;         float pv1 = bf2f(P[(size_t)row * 2816 + 256 + 1536 + ch1]);
;         float pp0 = prevP(p, P, row, 1536 + ch0), pp1 = prevP(p, P, row, 1536 + ch1);
;         float vv0 = pv0 + (pp0 - pv0) * mu0, vv1 = pv1 + (pp1 - pv1) * mu1;
;         float b = bs[((size_t)row * 12 + hh) * 4 + 2];
;         float y0 = (d0 * rstd * gg0 + gb0 + b * vv0) * acc0[i];
;         float y1 = (d1 * rstd * gg1 + gb1 + b * vv1) * acc1[i];
;         Y[(size_t)row * 1024 + 256 + ch0] = f2bf(y0);
;         Y[(size_t)row * 1024 + 256 + ch1] = f2bf(y1);
;       }
	v_lshlrev_b32_e32 v232, 16, v178
	v_and_b32_e32 v233, 0xffff0000, v178
	v_lshlrev_b32_e32 v230, 16, v179
	v_and_b32_e32 v231, 0xffff0000, v179
	v_pk_add_f32 v[232:233], v[232:233], v[230:231]
	v_lshlrev_b32_e32 v230, 16, v180
	v_and_b32_e32 v231, 0xffff0000, v180
	v_pk_add_f32 v[232:233], v[232:233], v[230:231]
	v_lshlrev_b32_e32 v230, 16, v181
	v_and_b32_e32 v231, 0xffff0000, v181
	v_pk_add_f32 v[232:233], v[232:233], v[230:231]
	v_lshlrev_b32_e32 v230, 16, v182
	v_and_b32_e32 v231, 0xffff0000, v182
	v_pk_add_f32 v[232:233], v[232:233], v[230:231]
	v_lshlrev_b32_e32 v230, 16, v183
	v_and_b32_e32 v231, 0xffff0000, v183
	v_pk_add_f32 v[232:233], v[232:233], v[230:231]
	v_lshlrev_b32_e32 v230, 16, v184
	v_and_b32_e32 v231, 0xffff0000, v184
	v_pk_add_f32 v[232:233], v[232:233], v[230:231]
	v_lshlrev_b32_e32 v230, 16, v185
	v_and_b32_e32 v231, 0xffff0000, v185
	v_pk_add_f32 v[232:233], v[232:233], v[230:231]
	v_add_f32_e32 v232, v232, v233
	v_mov_b32_e32 v230, v232
	s_nop 1
	v_permlane16_swap_b32_e32 v230, v232
	v_add_f32_e32 v232, v232, v230
	v_mov_b32_e32 v230, v232
	s_nop 1
	v_permlane32_swap_b32_e32 v230, v232
	v_add_f32_e32 v232, v232, v230
	v_mul_f32_e32 v236, 0x3c800000, v232
	v_lshlrev_b32_e32 v230, 16, v178
	v_and_b32_e32 v231, 0xffff0000, v178
	v_pk_add_f32 v[230:231], v[230:231], v[236:237] op_sel_hi:[1,0] neg_lo:[0,1] neg_hi:[0,1]
	v_pk_mul_f32 v[232:233], v[230:231], v[230:231]
	v_lshlrev_b32_e32 v230, 16, v179
	v_and_b32_e32 v231, 0xffff0000, v179
	v_pk_add_f32 v[230:231], v[230:231], v[236:237] op_sel_hi:[1,0] neg_lo:[0,1] neg_hi:[0,1]
	v_pk_fma_f32 v[232:233], v[230:231], v[230:231], v[232:233]
	v_lshlrev_b32_e32 v230, 16, v180
	v_and_b32_e32 v231, 0xffff0000, v180
	v_pk_add_f32 v[230:231], v[230:231], v[236:237] op_sel_hi:[1,0] neg_lo:[0,1] neg_hi:[0,1]
	v_pk_fma_f32 v[232:233], v[230:231], v[230:231], v[232:233]
	v_lshlrev_b32_e32 v230, 16, v181
	v_and_b32_e32 v231, 0xffff0000, v181
	v_pk_add_f32 v[230:231], v[230:231], v[236:237] op_sel_hi:[1,0] neg_lo:[0,1] neg_hi:[0,1]
	v_pk_fma_f32 v[232:233], v[230:231], v[230:231], v[232:233]
	v_lshlrev_b32_e32 v230, 16, v182
	v_and_b32_e32 v231, 0xffff0000, v182
	v_pk_add_f32 v[230:231], v[230:231], v[236:237] op_sel_hi:[1,0] neg_lo:[0,1] neg_hi:[0,1]
	v_pk_fma_f32 v[232:233], v[230:231], v[230:231], v[232:233]
	v_lshlrev_b32_e32 v230, 16, v183
	v_and_b32_e32 v231, 0xffff0000, v183
	v_pk_add_f32 v[230:231], v[230:231], v[236:237] op_sel_hi:[1,0] neg_lo:[0,1] neg_hi:[0,1]
	v_pk_fma_f32 v[232:233], v[230:231], v[230:231], v[232:233]
	v_lshlrev_b32_e32 v230, 16, v184
	v_and_b32_e32 v231, 0xffff0000, v184
	v_pk_add_f32 v[230:231], v[230:231], v[236:237] op_sel_hi:[1,0] neg_lo:[0,1] neg_hi:[0,1]
	v_pk_fma_f32 v[232:233], v[230:231], v[230:231], v[232:233]
	v_lshlrev_b32_e32 v230, 16, v185
	v_and_b32_e32 v231, 0xffff0000, v185
	v_pk_add_f32 v[230:231], v[230:231], v[236:237] op_sel_hi:[1,0] neg_lo:[0,1] neg_hi:[0,1]
	v_pk_fma_f32 v[232:233], v[230:231], v[230:231], v[232:233]
	v_add_f32_e32 v232, v232, v233
	v_mov_b32_e32 v230, v232
	s_nop 1
	v_permlane16_swap_b32_e32 v230, v232
	v_add_f32_e32 v232, v232, v230
	v_mov_b32_e32 v230, v232
	s_nop 1
	v_permlane32_swap_b32_e32 v230, v232
	v_add_f32_e32 v232, v232, v230
	v_mov_b32_e32 v230, 0x3a27c5ac
	v_fmamk_f32 v232, v232, 0x3c800000, v230
	v_rsq_f32_e32 v238, v232
	v_and_b32_e32 v230, 3, v248
	v_cmp_eq_u32_e32 vcc, 0, v230
	s_nop 1
	v_lshlrev_b32_e32 v230, 16, v178
	v_and_b32_e32 v231, 0xffff0000, v178
	v_lshlrev_b32_e32 v232, 16, v186
	v_and_b32_e32 v233, 0xffff0000, v186
	v_lshlrev_b32_e32 v234, 16, v194
	v_and_b32_e32 v235, 0xffff0000, v194
	v_cndmask_b32_e32 v234, v234, v202, vcc
	v_cndmask_b32_e32 v235, v235, v203, vcc
	v_pk_add_f32 v[230:231], v[230:231], v[236:237] op_sel_hi:[1,0] neg_lo:[0,1] neg_hi:[0,1]
	v_pk_add_f32 v[234:235], v[234:235], v[232:233] neg_lo:[0,1] neg_hi:[0,1]
	v_pk_mul_f32 v[230:231], v[230:231], v[238:239] op_sel_hi:[1,0]
	v_pk_fma_f32 v[232:233], v[162:163], v[234:235], v[232:233]
	v_pk_fma_f32 v[230:231], v[130:131], v[230:231], v[146:147]
	v_pk_fma_f32 v[230:231], v[240:241], v[232:233], v[230:231] op_sel_hi:[0,1,1]
	v_pk_mul_f32 v[80:81], v[80:81], v[230:231]
	v_lshlrev_b32_e32 v230, 16, v179
	v_and_b32_e32 v231, 0xffff0000, v179
	v_lshlrev_b32_e32 v232, 16, v187
	v_and_b32_e32 v233, 0xffff0000, v187
	v_lshlrev_b32_e32 v234, 16, v195
	v_and_b32_e32 v235, 0xffff0000, v195
	v_cndmask_b32_e32 v234, v234, v204, vcc
	v_cndmask_b32_e32 v235, v235, v205, vcc
	v_pk_add_f32 v[230:231], v[230:231], v[236:237] op_sel_hi:[1,0] neg_lo:[0,1] neg_hi:[0,1]
	v_pk_add_f32 v[234:235], v[234:235], v[232:233] neg_lo:[0,1] neg_hi:[0,1]
	v_pk_mul_f32 v[230:231], v[230:231], v[238:239] op_sel_hi:[1,0]
	v_pk_fma_f32 v[232:233], v[164:165], v[234:235], v[232:233]
	v_pk_fma_f32 v[230:231], v[132:133], v[230:231], v[148:149]
	v_pk_fma_f32 v[230:231], v[240:241], v[232:233], v[230:231] op_sel_hi:[0,1,1]
	v_pk_mul_f32 v[82:83], v[82:83], v[230:231]
	v_lshlrev_b32_e32 v230, 16, v180
	v_and_b32_e32 v231, 0xffff0000, v180
	v_lshlrev_b32_e32 v232, 16, v188
	v_and_b32_e32 v233, 0xffff0000, v188
	v_lshlrev_b32_e32 v234, 16, v196
	v_and_b32_e32 v235, 0xffff0000, v196
	v_cndmask_b32_e32 v234, v234, v206, vcc
	v_cndmask_b32_e32 v235, v235, v207, vcc
	v_pk_add_f32 v[230:231], v[230:231], v[236:237] op_sel_hi:[1,0] neg_lo:[0,1] neg_hi:[0,1]
	v_pk_add_f32 v[234:235], v[234:235], v[232:233] neg_lo:[0,1] neg_hi:[0,1]
	v_pk_mul_f32 v[230:231], v[230:231], v[238:239] op_sel_hi:[1,0]
	v_pk_fma_f32 v[232:233], v[166:167], v[234:235], v[232:233]
	v_pk_fma_f32 v[230:231], v[134:135], v[230:231], v[150:151]
	v_pk_fma_f32 v[230:231], v[240:241], v[232:233], v[230:231] op_sel_hi:[0,1,1]
; __device__ __forceinline__ float bf2f(u16 h) { return __uint_as_float(((unsigned)h) << 16); }
; template <int EPI> ...
;     ...
; #pragma unroll 16
;       for (int i = 0; i < 16; i++) {
;         const int rl = rbase + (i & 3) + 8 * (i >> 2);
;         const int row = m0 + rl;
;         float o0 = bf2f(Y[(size_t)row * 1024 + 256 + ch0]);
;         float o1 = bf2f(Y[(size_t)row * 1024 + 256 + ch1]);
;         float mean = hsum32(o0 + o1) * (1.0f / 64.0f);
;         float d0 = o0 - mean, d1 = o1 - mean;
;         float var = hsum32(d0 * d0 + d1 * d1) * (1.0f / 64.0f);
;         float rstd = rsqrtf(var + 64e-5f);
;         float pv0 = bf2f(P[(size_t)row * 2816 + 256 + 1536 + ch0]);
;         float pv1 = bf2f(P[(size_t)row * 2816 + 256 + 1536 + ch1]);
;         float pp0 = prevP(p, P, row, 1536 + ch0), pp1 = prevP(p, P, row, 1536 + ch1);
;         float vv0 = pv0 + (pp0 - pv0) * mu0, vv1 = pv1 + (pp1 - pv1) * mu1;
;         float b = bs[((size_t)row * 12 + hh) * 4 + 2];
;         float y0 = (d0 * rstd * gg0 + gb0 + b * vv0) * acc0[i];
;         float y1 = (d1 * rstd * gg1 + gb1 + b * vv1) * acc1[i];
;         Y[(size_t)row * 1024 + 256 + ch0] = f2bf(y0);
;         Y[(size_t)row * 1024 + 256 + ch1] = f2bf(y1);
;       }
	v_pk_mul_f32 v[84:85], v[84:85], v[230:231]
	v_lshlrev_b32_e32 v230, 16, v181
	v_and_b32_e32 v231, 0xffff0000, v181
	v_lshlrev_b32_e32 v232, 16, v189
	v_and_b32_e32 v233, 0xffff0000, v189
	v_lshlrev_b32_e32 v234, 16, v197
	v_and_b32_e32 v235, 0xffff0000, v197
	v_cndmask_b32_e32 v234, v234, v208, vcc
	v_cndmask_b32_e32 v235, v235, v209, vcc
	v_pk_add_f32 v[230:231], v[230:231], v[236:237] op_sel_hi:[1,0] neg_lo:[0,1] neg_hi:[0,1]
	v_pk_add_f32 v[234:235], v[234:235], v[232:233] neg_lo:[0,1] neg_hi:[0,1]
	v_pk_mul_f32 v[230:231], v[230:231], v[238:239] op_sel_hi:[1,0]
	v_pk_fma_f32 v[232:233], v[168:169], v[234:235], v[232:233]
	v_pk_fma_f32 v[230:231], v[136:137], v[230:231], v[152:153]
	v_pk_fma_f32 v[230:231], v[240:241], v[232:233], v[230:231] op_sel_hi:[0,1,1]
	v_pk_mul_f32 v[86:87], v[86:87], v[230:231]
	v_cvt_pk_bf16_f32 v80, v80, v81
	v_cvt_pk_bf16_f32 v81, v82, v83
	v_cvt_pk_bf16_f32 v82, v84, v85
	v_cvt_pk_bf16_f32 v83, v86, v87
	v_add_u32_e32 v246, 0x10000, v237
	s_nop 0
	global_store_dwordx4 v246, v[80:83], s[22:23] offset:128
	v_lshlrev_b32_e32 v230, 16, v182
	v_and_b32_e32 v231, 0xffff0000, v182
	v_lshlrev_b32_e32 v232, 16, v190
	v_and_b32_e32 v233, 0xffff0000, v190
	v_lshlrev_b32_e32 v234, 16, v198
	v_and_b32_e32 v235, 0xffff0000, v198
	v_cndmask_b32_e32 v234, v234, v210, vcc
	v_cndmask_b32_e32 v235, v235, v211, vcc
	v_pk_add_f32 v[230:231], v[230:231], v[236:237] op_sel_hi:[1,0] neg_lo:[0,1] neg_hi:[0,1]
	v_pk_add_f32 v[234:235], v[234:235], v[232:233] neg_lo:[0,1] neg_hi:[0,1]
	v_pk_mul_f32 v[230:231], v[230:231], v[238:239] op_sel_hi:[1,0]
	v_pk_fma_f32 v[232:233], v[170:171], v[234:235], v[232:233]
	v_pk_fma_f32 v[230:231], v[138:139], v[230:231], v[154:155]
	v_pk_fma_f32 v[230:231], v[240:241], v[232:233], v[230:231] op_sel_hi:[0,1,1]
	v_pk_mul_f32 v[88:89], v[88:89], v[230:231]
	v_lshlrev_b32_e32 v230, 16, v183
	v_and_b32_e32 v231, 0xffff0000, v183
	v_lshlrev_b32_e32 v232, 16, v191
	v_and_b32_e32 v233, 0xffff0000, v191
	v_lshlrev_b32_e32 v234, 16, v199
	v_and_b32_e32 v235, 0xffff0000, v199
	v_cndmask_b32_e32 v234, v234, v212, vcc
	v_cndmask_b32_e32 v235, v235, v213, vcc
	v_pk_add_f32 v[230:231], v[230:231], v[236:237] op_sel_hi:[1,0] neg_lo:[0,1] neg_hi:[0,1]
	v_pk_add_f32 v[234:235], v[234:235], v[232:233] neg_lo:[0,1] neg_hi:[0,1]
	v_pk_mul_f32 v[230:231], v[230:231], v[238:239] op_sel_hi:[1,0]
	v_pk_fma_f32 v[232:233], v[172:173], v[234:235], v[232:233]
	v_pk_fma_f32 v[230:231], v[140:141], v[230:231], v[156:157]
	v_pk_fma_f32 v[230:231], v[240:241], v[232:233], v[230:231] op_sel_hi:[0,1,1]
	v_pk_mul_f32 v[90:91], v[90:91], v[230:231]
	v_lshlrev_b32_e32 v230, 16, v184
	v_and_b32_e32 v231, 0xffff0000, v184
	v_lshlrev_b32_e32 v232, 16, v192
	v_and_b32_e32 v233, 0xffff0000, v192
	v_lshlrev_b32_e32 v234, 16, v200
	v_and_b32_e32 v235, 0xffff0000, v200
	v_cndmask_b32_e32 v234, v234, v214, vcc
	v_cndmask_b32_e32 v235, v235, v215, vcc
	v_pk_add_f32 v[230:231], v[230:231], v[236:237] op_sel_hi:[1,0] neg_lo:[0,1] neg_hi:[0,1]
	v_pk_add_f32 v[234:235], v[234:235], v[232:233] neg_lo:[0,1] neg_hi:[0,1]
	v_pk_mul_f32 v[230:231], v[230:231], v[238:239] op_sel_hi:[1,0]
	v_pk_fma_f32 v[232:233], v[174:175], v[234:235], v[232:233]
	v_pk_fma_f32 v[230:231], v[142:143], v[230:231], v[158:159]
	v_pk_fma_f32 v[230:231], v[240:241], v[232:233], v[230:231] op_sel_hi:[0,1,1]
	v_pk_mul_f32 v[92:93], v[92:93], v[230:231]
	v_lshlrev_b32_e32 v230, 16, v185
	v_and_b32_e32 v231, 0xffff0000, v185
	v_lshlrev_b32_e32 v232, 16, v193
	v_and_b32_e32 v233, 0xffff0000, v193
	v_lshlrev_b32_e32 v234, 16, v201
	v_and_b32_e32 v235, 0xffff0000, v201
	v_cndmask_b32_e32 v234, v234, v216, vcc
	v_cndmask_b32_e32 v235, v235, v217, vcc
	v_pk_add_f32 v[230:231], v[230:231], v[236:237] op_sel_hi:[1,0] neg_lo:[0,1] neg_hi:[0,1]
	v_pk_add_f32 v[234:235], v[234:235], v[232:233] neg_lo:[0,1] neg_hi:[0,1]
	v_pk_mul_f32 v[230:231], v[230:231], v[238:239] op_sel_hi:[1,0]
	v_pk_fma_f32 v[232:233], v[176:177], v[234:235], v[232:233]
	v_pk_fma_f32 v[230:231], v[144:145], v[230:231], v[160:161]
	v_pk_fma_f32 v[230:231], v[240:241], v[232:233], v[230:231] op_sel_hi:[0,1,1]
	v_pk_mul_f32 v[94:95], v[94:95], v[230:231]
	v_cvt_pk_bf16_f32 v88, v88, v89
	v_cvt_pk_bf16_f32 v89, v90, v91
	v_cvt_pk_bf16_f32 v90, v92, v93
	v_cvt_pk_bf16_f32 v91, v94, v95
	v_add_u32_e32 v246, 0x10000, v237
	s_nop 0
	global_store_dwordx4 v246, v[88:91], s[22:23] offset:192
	v_add_u32_e32 v246, 0x18000, v237
	v_add_u32_e32 v247, 0x42000, v239
	v_subrev_u32_e32 v230, 0x1600, v247
	global_load_dwordx4 v[178:181], v246, s[22:23] offset:128
	global_load_dwordx4 v[182:185], v246, s[22:23] offset:192
	global_load_dwordx4 v[186:189], v247, s[96:97] offset:128
	global_load_dwordx4 v[190:193], v247, s[96:97] offset:192
	global_load_dwordx4 v[194:197], v230, s[96:97] offset:128
	global_load_dwordx4 v[198:201], v230, s[96:97] offset:192
	v_add_u32_e32 v246, 0x2400, v241
	s_nop 0
	global_load_dword v240, v246, s[96:97] offset:16
	v_add_u32_e32 v247, 0x1e000, v243
	global_load_dwordx4 v[202:205], v247, s[20:21] offset:256
	global_load_dwordx4 v[206:209], v247, s[20:21] offset:272
	global_load_dwordx4 v[210:213], v247, s[20:21] offset:384
	global_load_dwordx4 v[214:217], v247, s[20:21] offset:400
	s_waitcnt vmcnt(0)
; __device__ __forceinline__ float bf2f(u16 h) { return __uint_as_float(((unsigned)h) << 16); }
; template <int EPI> ...
;     ...
; #pragma unroll 16
;       for (int i = 0; i < 16; i++) {
;         const int rl = rbase + (i & 3) + 8 * (i >> 2);
;         const int row = m0 + rl;
;         float o0 = bf2f(Y[(size_t)row * 1024 + 256 + ch0]);
;         float o1 = bf2f(Y[(size_t)row * 1024 + 256 + ch1]);
;         float mean = hsum32(o0 + o1) * (1.0f / 64.0f);
;         float d0 = o0 - mean, d1 = o1 - mean;
;         float var = hsum32(d0 * d0 + d1 * d1) * (1.0f / 64.0f);
;         float rstd = rsqrtf(var + 64e-5f);
;         float pv0 = bf2f(P[(size_t)row * 2816 + 256 + 1536 + ch0]);
;         float pv1 = bf2f(P[(size_t)row * 2816 + 256 + 1536 + ch1]);
;         float pp0 = prevP(p, P, row, 1536 + ch0), pp1 = prevP(p, P, row, 1536 + ch1);
;         float vv0 = pv0 + (pp0 - pv0) * mu0, vv1 = pv1 + (pp1 - pv1) * mu1;
;         float b = bs[((size_t)row * 12 + hh) * 4 + 2];
;         float y0 = (d0 * rstd * gg0 + gb0 + b * vv0) * acc0[i];
;         float y1 = (d1 * rstd * gg1 + gb1 + b * vv1) * acc1[i];
;         Y[(size_t)row * 1024 + 256 + ch0] = f2bf(y0);
;         Y[(size_t)row * 1024 + 256 + ch1] = f2bf(y1);
;       }
	v_lshlrev_b32_e32 v232, 16, v178
	v_and_b32_e32 v233, 0xffff0000, v178
	v_lshlrev_b32_e32 v230, 16, v179
	v_and_b32_e32 v231, 0xffff0000, v179
	v_pk_add_f32 v[232:233], v[232:233], v[230:231]
	v_lshlrev_b32_e32 v230, 16, v180
	v_and_b32_e32 v231, 0xffff0000, v180
	v_pk_add_f32 v[232:233], v[232:233], v[230:231]
	v_lshlrev_b32_e32 v230, 16, v181
	v_and_b32_e32 v231, 0xffff0000, v181
	v_pk_add_f32 v[232:233], v[232:233], v[230:231]
	v_lshlrev_b32_e32 v230, 16, v182
	v_and_b32_e32 v231, 0xffff0000, v182
	v_pk_add_f32 v[232:233], v[232:233], v[230:231]
	v_lshlrev_b32_e32 v230, 16, v183
	v_and_b32_e32 v231, 0xffff0000, v183
	v_pk_add_f32 v[232:233], v[232:233], v[230:231]
	v_lshlrev_b32_e32 v230, 16, v184
	v_and_b32_e32 v231, 0xffff0000, v184
	v_pk_add_f32 v[232:233], v[232:233], v[230:231]
	v_lshlrev_b32_e32 v230, 16, v185
	v_and_b32_e32 v231, 0xffff0000, v185
	v_pk_add_f32 v[232:233], v[232:233], v[230:231]
	v_add_f32_e32 v232, v232, v233
	v_mov_b32_e32 v230, v232
	s_nop 1
	v_permlane16_swap_b32_e32 v230, v232
	v_add_f32_e32 v232, v232, v230
	v_mov_b32_e32 v230, v232
	s_nop 1
	v_permlane32_swap_b32_e32 v230, v232
	v_add_f32_e32 v232, v232, v230
	v_mul_f32_e32 v236, 0x3c800000, v232
	v_lshlrev_b32_e32 v230, 16, v178
	v_and_b32_e32 v231, 0xffff0000, v178
	v_pk_add_f32 v[230:231], v[230:231], v[236:237] op_sel_hi:[1,0] neg_lo:[0,1] neg_hi:[0,1]
	v_pk_mul_f32 v[232:233], v[230:231], v[230:231]
	v_lshlrev_b32_e32 v230, 16, v179
	v_and_b32_e32 v231, 0xffff0000, v179
	v_pk_add_f32 v[230:231], v[230:231], v[236:237] op_sel_hi:[1,0] neg_lo:[0,1] neg_hi:[0,1]
	v_pk_fma_f32 v[232:233], v[230:231], v[230:231], v[232:233]
	v_lshlrev_b32_e32 v230, 16, v180
	v_and_b32_e32 v231, 0xffff0000, v180
	v_pk_add_f32 v[230:231], v[230:231], v[236:237] op_sel_hi:[1,0] neg_lo:[0,1] neg_hi:[0,1]
	v_pk_fma_f32 v[232:233], v[230:231], v[230:231], v[232:233]
	v_lshlrev_b32_e32 v230, 16, v181
	v_and_b32_e32 v231, 0xffff0000, v181
	v_pk_add_f32 v[230:231], v[230:231], v[236:237] op_sel_hi:[1,0] neg_lo:[0,1] neg_hi:[0,1]
	v_pk_fma_f32 v[232:233], v[230:231], v[230:231], v[232:233]
	v_lshlrev_b32_e32 v230, 16, v182
	v_and_b32_e32 v231, 0xffff0000, v182
	v_pk_add_f32 v[230:231], v[230:231], v[236:237] op_sel_hi:[1,0] neg_lo:[0,1] neg_hi:[0,1]
	v_pk_fma_f32 v[232:233], v[230:231], v[230:231], v[232:233]
	v_lshlrev_b32_e32 v230, 16, v183
	v_and_b32_e32 v231, 0xffff0000, v183
	v_pk_add_f32 v[230:231], v[230:231], v[236:237] op_sel_hi:[1,0] neg_lo:[0,1] neg_hi:[0,1]
	v_pk_fma_f32 v[232:233], v[230:231], v[230:231], v[232:233]
	v_lshlrev_b32_e32 v230, 16, v184
	v_and_b32_e32 v231, 0xffff0000, v184
	v_pk_add_f32 v[230:231], v[230:231], v[236:237] op_sel_hi:[1,0] neg_lo:[0,1] neg_hi:[0,1]
	v_pk_fma_f32 v[232:233], v[230:231], v[230:231], v[232:233]
	v_lshlrev_b32_e32 v230, 16, v185
	v_and_b32_e32 v231, 0xffff0000, v185
	v_pk_add_f32 v[230:231], v[230:231], v[236:237] op_sel_hi:[1,0] neg_lo:[0,1] neg_hi:[0,1]
	v_pk_fma_f32 v[232:233], v[230:231], v[230:231], v[232:233]
	v_add_f32_e32 v232, v232, v233
	v_mov_b32_e32 v230, v232
	s_nop 1
	v_permlane16_swap_b32_e32 v230, v232
	v_add_f32_e32 v232, v232, v230
	v_mov_b32_e32 v230, v232
	s_nop 1
	v_permlane32_swap_b32_e32 v230, v232
	v_add_f32_e32 v232, v232, v230
	v_mov_b32_e32 v230, 0x3a27c5ac
	v_fmamk_f32 v232, v232, 0x3c800000, v230
	v_rsq_f32_e32 v238, v232
	v_and_b32_e32 v230, 3, v248
	v_cmp_eq_u32_e32 vcc, 0, v230
	s_nop 1
	v_lshlrev_b32_e32 v230, 16, v178
	v_and_b32_e32 v231, 0xffff0000, v178
	v_lshlrev_b32_e32 v232, 16, v186
	v_and_b32_e32 v233, 0xffff0000, v186
	v_lshlrev_b32_e32 v234, 16, v194
	v_and_b32_e32 v235, 0xffff0000, v194
	v_cndmask_b32_e32 v234, v234, v202, vcc
	v_cndmask_b32_e32 v235, v235, v203, vcc
	v_pk_add_f32 v[230:231], v[230:231], v[236:237] op_sel_hi:[1,0] neg_lo:[0,1] neg_hi:[0,1]
	v_pk_add_f32 v[234:235], v[234:235], v[232:233] neg_lo:[0,1] neg_hi:[0,1]
	v_pk_mul_f32 v[230:231], v[230:231], v[238:239] op_sel_hi:[1,0]
	v_pk_fma_f32 v[232:233], v[162:163], v[234:235], v[232:233]
	v_pk_fma_f32 v[230:231], v[130:131], v[230:231], v[146:147]
	v_pk_fma_f32 v[230:231], v[240:241], v[232:233], v[230:231] op_sel_hi:[0,1,1]
	v_pk_mul_f32 v[112:113], v[112:113], v[230:231]
	v_lshlrev_b32_e32 v230, 16, v179
	v_and_b32_e32 v231, 0xffff0000, v179
	v_lshlrev_b32_e32 v232, 16, v187
	v_and_b32_e32 v233, 0xffff0000, v187
	v_lshlrev_b32_e32 v234, 16, v195
	v_and_b32_e32 v235, 0xffff0000, v195
	v_cndmask_b32_e32 v234, v234, v204, vcc
	v_cndmask_b32_e32 v235, v235, v205, vcc
	v_pk_add_f32 v[230:231], v[230:231], v[236:237] op_sel_hi:[1,0] neg_lo:[0,1] neg_hi:[0,1]
	v_pk_add_f32 v[234:235], v[234:235], v[232:233] neg_lo:[0,1] neg_hi:[0,1]
	v_pk_mul_f32 v[230:231], v[230:231], v[238:239] op_sel_hi:[1,0]
	v_pk_fma_f32 v[232:233], v[164:165], v[234:235], v[232:233]
	v_pk_fma_f32 v[230:231], v[132:133], v[230:231], v[148:149]
	v_pk_fma_f32 v[230:231], v[240:241], v[232:233], v[230:231] op_sel_hi:[0,1,1]
	v_pk_mul_f32 v[114:115], v[114:115], v[230:231]
	v_lshlrev_b32_e32 v230, 16, v180
	v_and_b32_e32 v231, 0xffff0000, v180
	v_lshlrev_b32_e32 v232, 16, v188
; __device__ __forceinline__ float bf2f(u16 h) { return __uint_as_float(((unsigned)h) << 16); }
; template <int EPI> ...
;     ...
; #pragma unroll 16
;       for (int i = 0; i < 16; i++) {
;         const int rl = rbase + (i & 3) + 8 * (i >> 2);
;         const int row = m0 + rl;
;         float o0 = bf2f(Y[(size_t)row * 1024 + 256 + ch0]);
;         float o1 = bf2f(Y[(size_t)row * 1024 + 256 + ch1]);
;         float mean = hsum32(o0 + o1) * (1.0f / 64.0f);
;         float d0 = o0 - mean, d1 = o1 - mean;
;         float var = hsum32(d0 * d0 + d1 * d1) * (1.0f / 64.0f);
;         float rstd = rsqrtf(var + 64e-5f);
;         float pv0 = bf2f(P[(size_t)row * 2816 + 256 + 1536 + ch0]);
;         float pv1 = bf2f(P[(size_t)row * 2816 + 256 + 1536 + ch1]);
;         float pp0 = prevP(p, P, row, 1536 + ch0), pp1 = prevP(p, P, row, 1536 + ch1);
;         float vv0 = pv0 + (pp0 - pv0) * mu0, vv1 = pv1 + (pp1 - pv1) * mu1;
;         float b = bs[((size_t)row * 12 + hh) * 4 + 2];
;         float y0 = (d0 * rstd * gg0 + gb0 + b * vv0) * acc0[i];
;         float y1 = (d1 * rstd * gg1 + gb1 + b * vv1) * acc1[i];
;         Y[(size_t)row * 1024 + 256 + ch0] = f2bf(y0);
;         Y[(size_t)row * 1024 + 256 + ch1] = f2bf(y1);
;       }
	v_and_b32_e32 v233, 0xffff0000, v188
	v_lshlrev_b32_e32 v234, 16, v196
	v_and_b32_e32 v235, 0xffff0000, v196
	v_cndmask_b32_e32 v234, v234, v206, vcc
	v_cndmask_b32_e32 v235, v235, v207, vcc
	v_pk_add_f32 v[230:231], v[230:231], v[236:237] op_sel_hi:[1,0] neg_lo:[0,1] neg_hi:[0,1]
	v_pk_add_f32 v[234:235], v[234:235], v[232:233] neg_lo:[0,1] neg_hi:[0,1]
	v_pk_mul_f32 v[230:231], v[230:231], v[238:239] op_sel_hi:[1,0]
	v_pk_fma_f32 v[232:233], v[166:167], v[234:235], v[232:233]
	v_pk_fma_f32 v[230:231], v[134:135], v[230:231], v[150:151]
	v_pk_fma_f32 v[230:231], v[240:241], v[232:233], v[230:231] op_sel_hi:[0,1,1]
	v_pk_mul_f32 v[116:117], v[116:117], v[230:231]
	v_lshlrev_b32_e32 v230, 16, v181
	v_and_b32_e32 v231, 0xffff0000, v181
	v_lshlrev_b32_e32 v232, 16, v189
	v_and_b32_e32 v233, 0xffff0000, v189
	v_lshlrev_b32_e32 v234, 16, v197
	v_and_b32_e32 v235, 0xffff0000, v197
	v_cndmask_b32_e32 v234, v234, v208, vcc
	v_cndmask_b32_e32 v235, v235, v209, vcc
	v_pk_add_f32 v[230:231], v[230:231], v[236:237] op_sel_hi:[1,0] neg_lo:[0,1] neg_hi:[0,1]
	v_pk_add_f32 v[234:235], v[234:235], v[232:233] neg_lo:[0,1] neg_hi:[0,1]
	v_pk_mul_f32 v[230:231], v[230:231], v[238:239] op_sel_hi:[1,0]
	v_pk_fma_f32 v[232:233], v[168:169], v[234:235], v[232:233]
	v_pk_fma_f32 v[230:231], v[136:137], v[230:231], v[152:153]
	v_pk_fma_f32 v[230:231], v[240:241], v[232:233], v[230:231] op_sel_hi:[0,1,1]
	v_pk_mul_f32 v[118:119], v[118:119], v[230:231]
	v_cvt_pk_bf16_f32 v112, v112, v113
	v_cvt_pk_bf16_f32 v113, v114, v115
	v_cvt_pk_bf16_f32 v114, v116, v117
	v_cvt_pk_bf16_f32 v115, v118, v119
	v_add_u32_e32 v246, 0x18000, v237
	s_nop 0
	global_store_dwordx4 v246, v[112:115], s[22:23] offset:128
	v_lshlrev_b32_e32 v230, 16, v182
	v_and_b32_e32 v231, 0xffff0000, v182
	v_lshlrev_b32_e32 v232, 16, v190
	v_and_b32_e32 v233, 0xffff0000, v190
	v_lshlrev_b32_e32 v234, 16, v198
	v_and_b32_e32 v235, 0xffff0000, v198
	v_cndmask_b32_e32 v234, v234, v210, vcc
	v_cndmask_b32_e32 v235, v235, v211, vcc
	v_pk_add_f32 v[230:231], v[230:231], v[236:237] op_sel_hi:[1,0] neg_lo:[0,1] neg_hi:[0,1]
	v_pk_add_f32 v[234:235], v[234:235], v[232:233] neg_lo:[0,1] neg_hi:[0,1]
	v_pk_mul_f32 v[230:231], v[230:231], v[238:239] op_sel_hi:[1,0]
	v_pk_fma_f32 v[232:233], v[170:171], v[234:235], v[232:233]
	v_pk_fma_f32 v[230:231], v[138:139], v[230:231], v[154:155]
	v_pk_fma_f32 v[230:231], v[240:241], v[232:233], v[230:231] op_sel_hi:[0,1,1]
	v_pk_mul_f32 v[120:121], v[120:121], v[230:231]
	v_lshlrev_b32_e32 v230, 16, v183
	v_and_b32_e32 v231, 0xffff0000, v183
	v_lshlrev_b32_e32 v232, 16, v191
	v_and_b32_e32 v233, 0xffff0000, v191
	v_lshlrev_b32_e32 v234, 16, v199
	v_and_b32_e32 v235, 0xffff0000, v199
	v_cndmask_b32_e32 v234, v234, v212, vcc
	v_cndmask_b32_e32 v235, v235, v213, vcc
	v_pk_add_f32 v[230:231], v[230:231], v[236:237] op_sel_hi:[1,0] neg_lo:[0,1] neg_hi:[0,1]
	v_pk_add_f32 v[234:235], v[234:235], v[232:233] neg_lo:[0,1] neg_hi:[0,1]
	v_pk_mul_f32 v[230:231], v[230:231], v[238:239] op_sel_hi:[1,0]
	v_pk_fma_f32 v[232:233], v[172:173], v[234:235], v[232:233]
	v_pk_fma_f32 v[230:231], v[140:141], v[230:231], v[156:157]
	v_pk_fma_f32 v[230:231], v[240:241], v[232:233], v[230:231] op_sel_hi:[0,1,1]
	v_pk_mul_f32 v[122:123], v[122:123], v[230:231]
	v_lshlrev_b32_e32 v230, 16, v184
	v_and_b32_e32 v231, 0xffff0000, v184
	v_lshlrev_b32_e32 v232, 16, v192
	v_and_b32_e32 v233, 0xffff0000, v192
	v_lshlrev_b32_e32 v234, 16, v200
	v_and_b32_e32 v235, 0xffff0000, v200
	v_cndmask_b32_e32 v234, v234, v214, vcc
	v_cndmask_b32_e32 v235, v235, v215, vcc
	v_pk_add_f32 v[230:231], v[230:231], v[236:237] op_sel_hi:[1,0] neg_lo:[0,1] neg_hi:[0,1]
	v_pk_add_f32 v[234:235], v[234:235], v[232:233] neg_lo:[0,1] neg_hi:[0,1]
	v_pk_mul_f32 v[230:231], v[230:231], v[238:239] op_sel_hi:[1,0]
	v_pk_fma_f32 v[232:233], v[174:175], v[234:235], v[232:233]
	v_pk_fma_f32 v[230:231], v[142:143], v[230:231], v[158:159]
	v_pk_fma_f32 v[230:231], v[240:241], v[232:233], v[230:231] op_sel_hi:[0,1,1]
	v_pk_mul_f32 v[124:125], v[124:125], v[230:231]
	v_lshlrev_b32_e32 v230, 16, v185
	v_and_b32_e32 v231, 0xffff0000, v185
	v_lshlrev_b32_e32 v232, 16, v193
	v_and_b32_e32 v233, 0xffff0000, v193
	v_lshlrev_b32_e32 v234, 16, v201
	v_and_b32_e32 v235, 0xffff0000, v201
	v_cndmask_b32_e32 v234, v234, v216, vcc
	v_cndmask_b32_e32 v235, v235, v217, vcc
	v_pk_add_f32 v[230:231], v[230:231], v[236:237] op_sel_hi:[1,0] neg_lo:[0,1] neg_hi:[0,1]
	v_pk_add_f32 v[234:235], v[234:235], v[232:233] neg_lo:[0,1] neg_hi:[0,1]
	v_pk_mul_f32 v[230:231], v[230:231], v[238:239] op_sel_hi:[1,0]
	v_pk_fma_f32 v[232:233], v[176:177], v[234:235], v[232:233]
	v_pk_fma_f32 v[230:231], v[144:145], v[230:231], v[160:161]
	v_pk_fma_f32 v[230:231], v[240:241], v[232:233], v[230:231] op_sel_hi:[0,1,1]
	v_pk_mul_f32 v[126:127], v[126:127], v[230:231]
	v_cvt_pk_bf16_f32 v120, v120, v121
	v_cvt_pk_bf16_f32 v121, v122, v123
	v_cvt_pk_bf16_f32 v122, v124, v125
	v_cvt_pk_bf16_f32 v123, v126, v127
	v_add_u32_e32 v246, 0x18000, v237
	s_nop 0
	global_store_dwordx4 v246, v[120:123], s[22:23] offset:192
